# all dwordx2/x4 stores in the layer loop made write-through (sc1) so the end-of-phase L2 writeback has nothing to flush
# baseline (speedup 1.0000x reference)
; __device__ __forceinline__ unsigned cvt_pk_bf16(float lo, float hi) { unsigned r; asm("v_cvt_pk_bf16_f32 %0, %1, %2" : "=v"(r) : "v"(lo), "v"(hi)); return r; }
;     __device__ __forceinline__ void operator()(const f32x4 (&acc)[2][2][4][2], const GU& u, int wr, int wc, int fr, int fq) const {
;     ...
; #pragma unroll
;         for (int ai = 0; ai < 2; ++ai)
; #pragma unroll
;             for (int m = 0; m < 4; ++m) {
;                 const int row = r0 + ai * 128 + m * 16;
;                 const float rs = rsv[ai][m];
;                 bf16_t* rowp = u.out + (size_t)row * u.ldc + c0;
; #pragma unroll
;                 for (int bj = 0; bj < 2; ++bj) {
;                     if (bj == 1 && (u.mode & 8)) continue;
;                     f32x4 v0 = acc[ai][bj][m][0] * cs[bj][0] * rs, v1 = acc[ai][bj][m][1] * cs[bj][1] * rs;
;                     u32x4 w; w.x = cvt_pk_bf16(v0[0], v0[1]); w.y = cvt_pk_bf16(v0[2], v0[3]); w.z = cvt_pk_bf16(v1[0], v1[1]); w.w = cvt_pk_bf16(v1[2], v1[3]);
;                     *(u32x4*)(rowp + bj * 128) = w;
;                     if (bj == 0 && u.gates != nullptr && wc == 0) { float* gp = u.gates + (size_t)row * 32 + 8 * fq; *(f32x4*)gp = v0; *(f32x4*)(gp + 4) = v1; }
;                 }
.LBB0_370:
	v_mul_lo_u32 v194, s19, v136
	v_mul_lo_u32 v195, s18, v137
	v_mad_u64_u32 v[192:193], s[0:1], s18, v136, 0
	s_cmp_lg_u64 s[20:21], 0
	v_add3_u32 v193, v193, v195, v194
	s_cselect_b64 s[0:1], -1, 0
	v_lshl_add_u64 v[192:193], v[192:193], 1, s[16:17]
	s_and_b64 s[4:5], s[8:9], s[0:1]
	v_lshl_add_u64 v[194:195], v[192:193], 0, v[200:201]
	v_pk_mul_f32 v[126:127], v[126:127], v[172:173]
	v_pk_mul_f32 v[124:125], v[124:125], v[170:171]
	v_pk_mul_f32 v[122:123], v[122:123], v[176:177]
	v_pk_mul_f32 v[120:121], v[120:121], v[168:169]
	v_cndmask_b32_e64 v192, 0, 1, s[4:5]
	v_pk_mul_f32 v[126:127], v[126:127], v[188:189] op_sel_hi:[1,0]
	v_pk_mul_f32 v[124:125], v[124:125], v[188:189] op_sel_hi:[1,0]
	v_pk_mul_f32 v[122:123], v[122:123], v[188:189] op_sel_hi:[1,0]
	v_pk_mul_f32 v[120:121], v[120:121], v[188:189] op_sel_hi:[1,0]
	v_cmp_ne_u32_e64 s[0:1], 1, v192
	s_andn2_b64 vcc, exec, s[4:5]
	v_lshlrev_b32_e32 v192, 2, v138
	v_cvt_pk_bf16_f32 v196, v124, v125
	v_cvt_pk_bf16_f32 v197, v126, v127
	v_cvt_pk_bf16_f32 v198, v120, v121
	v_cvt_pk_bf16_f32 v199, v122, v123
	flat_store_dwordx4 v[194:195], v[196:199] sc1
	s_cbranch_vccnz .LBB0_372
	s_nop 0
	v_lshlrev_b64 v[196:197], 7, v[136:137]
	v_lshl_add_u64 v[196:197], s[20:21], 0, v[196:197]
	v_mov_b32_e32 v193, v201
	v_lshl_add_u64 v[196:197], v[196:197], 0, v[192:193]
	flat_store_dwordx4 v[196:197], v[124:127] sc1
	flat_store_dwordx4 v[196:197], v[120:123] offset:16 sc1
.LBB0_372:
	s_nop 1
	v_mov_b32_e32 v120, v188
	v_mov_b32_e32 v121, v188
	v_pk_mul_f32 v[118:119], v[118:119], v[180:181]
	v_mov_b32_e32 v122, v188
	v_mov_b32_e32 v123, v188
	v_pk_mul_f32 v[114:115], v[114:115], v[182:183]
	v_pk_mul_f32 v[112:113], v[112:113], v[174:175]
	v_pk_mul_f32 v[116:117], v[116:117], v[178:179]
	v_pk_mul_f32 v[118:119], v[118:119], v[122:123]
	v_pk_mul_f32 v[122:123], v[114:115], v[122:123]
	v_pk_mul_f32 v[114:115], v[112:113], v[120:121]
	v_pk_mul_f32 v[116:117], v[116:117], v[120:121]
	v_cvt_pk_bf16_f32 v113, v118, v119
	v_cvt_pk_bf16_f32 v114, v114, v115
	v_cvt_pk_bf16_f32 v115, v122, v123
	v_pk_mul_f32 v[110:111], v[110:111], v[172:173]
	v_cvt_pk_bf16_f32 v112, v116, v117
	flat_store_dwordx4 v[194:195], v[112:115] offset:256 sc1
	v_pk_mul_f32 v[108:109], v[108:109], v[170:171]
	v_pk_mul_f32 v[106:107], v[106:107], v[176:177]
	v_mul_lo_u32 v114, s19, v142
	v_mul_lo_u32 v115, s18, v143
	v_mad_u64_u32 v[112:113], s[4:5], s18, v142, 0
	v_add3_u32 v113, v113, v115, v114
	v_lshl_add_u64 v[112:113], v[112:113], 1, s[16:17]
	v_pk_mul_f32 v[104:105], v[104:105], v[168:169]
	v_lshl_add_u64 v[112:113], v[112:113], 0, v[200:201]
	v_pk_mul_f32 v[110:111], v[110:111], v[188:189] op_sel:[0,1]
	v_pk_mul_f32 v[108:109], v[108:109], v[188:189] op_sel:[0,1]
	v_pk_mul_f32 v[106:107], v[106:107], v[188:189] op_sel:[0,1]
	v_pk_mul_f32 v[104:105], v[104:105], v[188:189] op_sel:[0,1]
	s_and_b64 vcc, exec, s[0:1]
	v_cvt_pk_bf16_f32 v114, v108, v109
	v_cvt_pk_bf16_f32 v115, v110, v111
	v_cvt_pk_bf16_f32 v116, v104, v105
	v_cvt_pk_bf16_f32 v117, v106, v107
	flat_store_dwordx4 v[112:113], v[114:117] sc1
	s_cbranch_vccnz .LBB0_374
	s_nop 0
	v_lshlrev_b64 v[114:115], 7, v[142:143]
	v_lshl_add_u64 v[114:115], s[20:21], 0, v[114:115]
	v_mov_b32_e32 v193, v201
	v_lshl_add_u64 v[114:115], v[114:115], 0, v[192:193]
	flat_store_dwordx4 v[114:115], v[108:111] sc1
	flat_store_dwordx4 v[114:115], v[104:107] offset:16 sc1
.LBB0_374:
	v_mov_b32_e32 v188, v189
	v_pk_mul_f32 v[102:103], v[102:103], v[180:181]
	v_mov_b32_e32 v104, v189
	v_mov_b32_e32 v105, v189
	v_pk_mul_f32 v[98:99], v[98:99], v[182:183]
	v_pk_mul_f32 v[96:97], v[96:97], v[174:175]
	v_pk_mul_f32 v[100:101], v[100:101], v[178:179]
	v_pk_mul_f32 v[102:103], v[102:103], v[104:105]
	v_pk_mul_f32 v[104:105], v[98:99], v[104:105]
	v_pk_mul_f32 v[98:99], v[96:97], v[188:189]
	v_pk_mul_f32 v[100:101], v[100:101], v[188:189]
	v_cvt_pk_bf16_f32 v97, v102, v103
	v_cvt_pk_bf16_f32 v98, v98, v99
	v_cvt_pk_bf16_f32 v99, v104, v105
	v_pk_mul_f32 v[94:95], v[94:95], v[172:173]
	v_cvt_pk_bf16_f32 v96, v100, v101
	flat_store_dwordx4 v[112:113], v[96:99] offset:256 sc1
	v_pk_mul_f32 v[92:93], v[92:93], v[170:171]
	v_pk_mul_f32 v[90:91], v[90:91], v[176:177]
	v_mul_lo_u32 v98, s19, v144
	v_mul_lo_u32 v99, s18, v145
	v_mad_u64_u32 v[96:97], s[4:5], s18, v144, 0
	v_add3_u32 v97, v97, v99, v98
	v_lshl_add_u64 v[96:97], v[96:97], 1, s[16:17]
	v_pk_mul_f32 v[88:89], v[88:89], v[168:169]
	v_lshl_add_u64 v[96:97], v[96:97], 0, v[200:201]
	v_pk_mul_f32 v[94:95], v[94:95], v[186:187] op_sel_hi:[1,0]
	v_pk_mul_f32 v[92:93], v[92:93], v[186:187] op_sel_hi:[1,0]
	v_pk_mul_f32 v[90:91], v[90:91], v[186:187] op_sel_hi:[1,0]
	v_pk_mul_f32 v[88:89], v[88:89], v[186:187] op_sel_hi:[1,0]
	s_and_b64 vcc, exec, s[0:1]
	v_cvt_pk_bf16_f32 v98, v92, v93
	v_cvt_pk_bf16_f32 v99, v94, v95
	v_cvt_pk_bf16_f32 v100, v88, v89
	v_cvt_pk_bf16_f32 v101, v90, v91
	flat_store_dwordx4 v[96:97], v[98:101] sc1
	s_cbranch_vccnz .LBB0_376
	s_nop 0
	v_lshlrev_b64 v[98:99], 7, v[144:145]
	v_lshl_add_u64 v[98:99], s[20:21], 0, v[98:99]
	v_mov_b32_e32 v193, v201
	v_lshl_add_u64 v[98:99], v[98:99], 0, v[192:193]
	flat_store_dwordx4 v[98:99], v[92:95] sc1
	flat_store_dwordx4 v[98:99], v[88:91] offset:16 sc1
; __device__ __forceinline__ unsigned cvt_pk_bf16(float lo, float hi) { unsigned r; asm("v_cvt_pk_bf16_f32 %0, %1, %2" : "=v"(r) : "v"(lo), "v"(hi)); return r; }
;     __device__ __forceinline__ void operator()(const f32x4 (&acc)[2][2][4][2], const GU& u, int wr, int wc, int fr, int fq) const {
;     ...
; #pragma unroll
;         for (int ai = 0; ai < 2; ++ai)
; #pragma unroll
;             for (int m = 0; m < 4; ++m) {
;                 const int row = r0 + ai * 128 + m * 16;
;                 const float rs = rsv[ai][m];
;                 bf16_t* rowp = u.out + (size_t)row * u.ldc + c0;
; #pragma unroll
;                 for (int bj = 0; bj < 2; ++bj) {
;                     if (bj == 1 && (u.mode & 8)) continue;
;                     f32x4 v0 = acc[ai][bj][m][0] * cs[bj][0] * rs, v1 = acc[ai][bj][m][1] * cs[bj][1] * rs;
;                     u32x4 w; w.x = cvt_pk_bf16(v0[0], v0[1]); w.y = cvt_pk_bf16(v0[2], v0[3]); w.z = cvt_pk_bf16(v1[0], v1[1]); w.w = cvt_pk_bf16(v1[2], v1[3]);
;                     *(u32x4*)(rowp + bj * 128) = w;
;                     if (bj == 0 && u.gates != nullptr && wc == 0) { float* gp = u.gates + (size_t)row * 32 + 8 * fq; *(f32x4*)gp = v0; *(f32x4*)(gp + 4) = v1; }
;                 }
.LBB0_376:
	s_nop 1
	v_mov_b32_e32 v88, v186
	v_mov_b32_e32 v89, v186
	v_pk_mul_f32 v[86:87], v[86:87], v[180:181]
	v_mov_b32_e32 v90, v186
	v_mov_b32_e32 v91, v186
	v_pk_mul_f32 v[82:83], v[82:83], v[182:183]
	v_pk_mul_f32 v[80:81], v[80:81], v[174:175]
	v_pk_mul_f32 v[84:85], v[84:85], v[178:179]
	v_pk_mul_f32 v[86:87], v[86:87], v[90:91]
	v_pk_mul_f32 v[90:91], v[82:83], v[90:91]
	v_pk_mul_f32 v[82:83], v[80:81], v[88:89]
	v_pk_mul_f32 v[84:85], v[84:85], v[88:89]
	v_cvt_pk_bf16_f32 v81, v86, v87
	v_cvt_pk_bf16_f32 v82, v82, v83
	v_cvt_pk_bf16_f32 v83, v90, v91
	v_pk_mul_f32 v[78:79], v[78:79], v[172:173]
	v_cvt_pk_bf16_f32 v80, v84, v85
	flat_store_dwordx4 v[96:97], v[80:83] offset:256 sc1
	v_pk_mul_f32 v[76:77], v[76:77], v[170:171]
	v_pk_mul_f32 v[74:75], v[74:75], v[176:177]
	v_mul_lo_u32 v82, s19, v146
	v_mul_lo_u32 v83, s18, v147
	v_mad_u64_u32 v[80:81], s[4:5], s18, v146, 0
	v_add3_u32 v81, v81, v83, v82
	v_lshl_add_u64 v[80:81], v[80:81], 1, s[16:17]
	v_pk_mul_f32 v[72:73], v[72:73], v[168:169]
	v_lshl_add_u64 v[80:81], v[80:81], 0, v[200:201]
	v_pk_mul_f32 v[78:79], v[78:79], v[186:187] op_sel:[0,1]
	v_pk_mul_f32 v[76:77], v[76:77], v[186:187] op_sel:[0,1]
	v_pk_mul_f32 v[74:75], v[74:75], v[186:187] op_sel:[0,1]
	v_pk_mul_f32 v[72:73], v[72:73], v[186:187] op_sel:[0,1]
	s_and_b64 vcc, exec, s[0:1]
	v_cvt_pk_bf16_f32 v82, v76, v77
	v_cvt_pk_bf16_f32 v83, v78, v79
	v_cvt_pk_bf16_f32 v84, v72, v73
	v_cvt_pk_bf16_f32 v85, v74, v75
	flat_store_dwordx4 v[80:81], v[82:85] sc1
	s_cbranch_vccnz .LBB0_378
	s_nop 0
	v_lshlrev_b64 v[82:83], 7, v[146:147]
	v_lshl_add_u64 v[82:83], s[20:21], 0, v[82:83]
	v_mov_b32_e32 v193, v201
	v_lshl_add_u64 v[82:83], v[82:83], 0, v[192:193]
	flat_store_dwordx4 v[82:83], v[76:79] sc1
	flat_store_dwordx4 v[82:83], v[72:75] offset:16 sc1
.LBB0_378:
	v_mov_b32_e32 v186, v187
	v_pk_mul_f32 v[70:71], v[70:71], v[180:181]
	v_mov_b32_e32 v72, v187
	v_mov_b32_e32 v73, v187
	v_pk_mul_f32 v[66:67], v[66:67], v[182:183]
	v_pk_mul_f32 v[64:65], v[64:65], v[174:175]
	v_pk_mul_f32 v[68:69], v[68:69], v[178:179]
	v_pk_mul_f32 v[70:71], v[70:71], v[72:73]
	v_pk_mul_f32 v[72:73], v[66:67], v[72:73]
	v_pk_mul_f32 v[66:67], v[64:65], v[186:187]
	v_pk_mul_f32 v[68:69], v[68:69], v[186:187]
	v_cvt_pk_bf16_f32 v65, v70, v71
	v_cvt_pk_bf16_f32 v66, v66, v67
	v_cvt_pk_bf16_f32 v67, v72, v73
	v_pk_mul_f32 v[62:63], v[62:63], v[172:173]
	v_cvt_pk_bf16_f32 v64, v68, v69
	flat_store_dwordx4 v[80:81], v[64:67] offset:256 sc1
	v_pk_mul_f32 v[60:61], v[60:61], v[170:171]
	v_pk_mul_f32 v[58:59], v[58:59], v[176:177]
	v_mul_lo_u32 v66, s19, v148
	v_mul_lo_u32 v67, s18, v149
	v_mad_u64_u32 v[64:65], s[4:5], s18, v148, 0
	v_add3_u32 v65, v65, v67, v66
	v_lshl_add_u64 v[64:65], v[64:65], 1, s[16:17]
	v_pk_mul_f32 v[56:57], v[56:57], v[168:169]
	v_lshl_add_u64 v[64:65], v[64:65], 0, v[200:201]
	v_pk_mul_f32 v[62:63], v[62:63], v[184:185] op_sel_hi:[1,0]
	v_pk_mul_f32 v[60:61], v[60:61], v[184:185] op_sel_hi:[1,0]
	v_pk_mul_f32 v[58:59], v[58:59], v[184:185] op_sel_hi:[1,0]
	v_pk_mul_f32 v[56:57], v[56:57], v[184:185] op_sel_hi:[1,0]
	s_and_b64 vcc, exec, s[0:1]
	v_cvt_pk_bf16_f32 v66, v60, v61
	v_cvt_pk_bf16_f32 v67, v62, v63
	v_cvt_pk_bf16_f32 v68, v56, v57
	v_cvt_pk_bf16_f32 v69, v58, v59
	flat_store_dwordx4 v[64:65], v[66:69] sc1
	s_cbranch_vccnz .LBB0_380
	s_nop 0
	v_lshl_add_u64 v[66:67], s[20:21], 0, v[150:151]
	v_mov_b32_e32 v193, v201
	v_lshl_add_u64 v[66:67], v[66:67], 0, v[192:193]
	flat_store_dwordx4 v[66:67], v[60:63] sc1
	flat_store_dwordx4 v[66:67], v[56:59] offset:16 sc1
.LBB0_380:
	s_nop 1
	v_mov_b32_e32 v56, v184
	v_mov_b32_e32 v57, v184
	v_pk_mul_f32 v[54:55], v[54:55], v[180:181]
	v_mov_b32_e32 v58, v184
	v_mov_b32_e32 v59, v184
	v_pk_mul_f32 v[50:51], v[50:51], v[182:183]
	v_pk_mul_f32 v[48:49], v[48:49], v[174:175]
	v_pk_mul_f32 v[52:53], v[52:53], v[178:179]
	v_pk_mul_f32 v[54:55], v[54:55], v[58:59]
	v_pk_mul_f32 v[58:59], v[50:51], v[58:59]
	v_pk_mul_f32 v[50:51], v[48:49], v[56:57]
	v_pk_mul_f32 v[52:53], v[52:53], v[56:57]
	v_cvt_pk_bf16_f32 v49, v54, v55
	v_cvt_pk_bf16_f32 v50, v50, v51
	v_cvt_pk_bf16_f32 v51, v58, v59
	v_pk_mul_f32 v[46:47], v[46:47], v[172:173]
	v_cvt_pk_bf16_f32 v48, v52, v53
	flat_store_dwordx4 v[64:65], v[48:51] offset:256 sc1
	v_pk_mul_f32 v[44:45], v[44:45], v[170:171]
	v_pk_mul_f32 v[42:43], v[42:43], v[176:177]
	v_mul_lo_u32 v50, s19, v152
	v_mul_lo_u32 v51, s18, v153
	v_mad_u64_u32 v[48:49], s[4:5], s18, v152, 0
	v_add3_u32 v49, v49, v51, v50
	v_lshl_add_u64 v[48:49], v[48:49], 1, s[16:17]
	v_pk_mul_f32 v[40:41], v[40:41], v[168:169]
	v_lshl_add_u64 v[48:49], v[48:49], 0, v[200:201]
	v_pk_mul_f32 v[46:47], v[46:47], v[184:185] op_sel:[0,1]
	v_pk_mul_f32 v[44:45], v[44:45], v[184:185] op_sel:[0,1]
	v_pk_mul_f32 v[42:43], v[42:43], v[184:185] op_sel:[0,1]
	v_pk_mul_f32 v[40:41], v[40:41], v[184:185] op_sel:[0,1]
	s_and_b64 vcc, exec, s[0:1]
	v_cvt_pk_bf16_f32 v50, v44, v45
	v_cvt_pk_bf16_f32 v51, v46, v47
	v_cvt_pk_bf16_f32 v52, v40, v41
	v_cvt_pk_bf16_f32 v53, v42, v43
	flat_store_dwordx4 v[48:49], v[50:53] sc1
	s_cbranch_vccnz .LBB0_382
	s_nop 0
	v_lshl_add_u64 v[50:51], s[20:21], 0, v[154:155]
	v_mov_b32_e32 v193, v201
	v_lshl_add_u64 v[50:51], v[50:51], 0, v[192:193]
	flat_store_dwordx4 v[50:51], v[44:47] sc1
	flat_store_dwordx4 v[50:51], v[40:43] offset:16 sc1
; __device__ __forceinline__ unsigned cvt_pk_bf16(float lo, float hi) { unsigned r; asm("v_cvt_pk_bf16_f32 %0, %1, %2" : "=v"(r) : "v"(lo), "v"(hi)); return r; }
; #define PG8_BAR __builtin_amdgcn_s_barrier()
; template <class Epi, class Sched, bool APERM = false, bool HALFN = false>
; __device__ __forceinline__ void gemm_phase(LAS unsigned char* lds, const int tid_in, const int K, const Sched& S, const Epi& E) {
;     ...
;         if (wr == 1) PG8_BAR;
;     __device__ __forceinline__ void operator()(const f32x4 (&acc)[2][2][4][2], const GU& u, int wr, int wc, int fr, int fq) const {
;     ...
; #pragma unroll
;         for (int ai = 0; ai < 2; ++ai)
; #pragma unroll
;             for (int m = 0; m < 4; ++m) {
;                 const int row = r0 + ai * 128 + m * 16;
;                 const float rs = rsv[ai][m];
;                 bf16_t* rowp = u.out + (size_t)row * u.ldc + c0;
; #pragma unroll
;                 for (int bj = 0; bj < 2; ++bj) {
;                     if (bj == 1 && (u.mode & 8)) continue;
;                     f32x4 v0 = acc[ai][bj][m][0] * cs[bj][0] * rs, v1 = acc[ai][bj][m][1] * cs[bj][1] * rs;
;                     u32x4 w; w.x = cvt_pk_bf16(v0[0], v0[1]); w.y = cvt_pk_bf16(v0[2], v0[3]); w.z = cvt_pk_bf16(v1[0], v1[1]); w.w = cvt_pk_bf16(v1[2], v1[3]);
;                     *(u32x4*)(rowp + bj * 128) = w;
;                     if (bj == 0 && u.gates != nullptr && wc == 0) { float* gp = u.gates + (size_t)row * 32 + 8 * fq; *(f32x4*)gp = v0; *(f32x4*)(gp + 4) = v1; }
;                 }
.LBB0_382:
	v_mov_b32_e32 v184, v185
	v_pk_mul_f32 v[38:39], v[38:39], v[180:181]
	v_mov_b32_e32 v40, v185
	v_mov_b32_e32 v41, v185
	v_pk_mul_f32 v[34:35], v[34:35], v[182:183]
	v_pk_mul_f32 v[32:33], v[32:33], v[174:175]
	v_pk_mul_f32 v[36:37], v[36:37], v[178:179]
	v_pk_mul_f32 v[38:39], v[38:39], v[40:41]
	v_pk_mul_f32 v[40:41], v[34:35], v[40:41]
	v_pk_mul_f32 v[34:35], v[32:33], v[184:185]
	v_pk_mul_f32 v[36:37], v[36:37], v[184:185]
	v_cvt_pk_bf16_f32 v33, v38, v39
	v_cvt_pk_bf16_f32 v34, v34, v35
	v_cvt_pk_bf16_f32 v35, v40, v41
	v_pk_mul_f32 v[30:31], v[30:31], v[172:173]
	v_cvt_pk_bf16_f32 v32, v36, v37
	flat_store_dwordx4 v[48:49], v[32:35] offset:256 sc1
	v_pk_mul_f32 v[28:29], v[28:29], v[170:171]
	v_pk_mul_f32 v[26:27], v[26:27], v[176:177]
	v_mul_lo_u32 v34, s19, v156
	v_mul_lo_u32 v35, s18, v157
	v_mad_u64_u32 v[32:33], s[4:5], s18, v156, 0
	v_add3_u32 v33, v33, v35, v34
	v_lshl_add_u64 v[32:33], v[32:33], 1, s[16:17]
	v_pk_mul_f32 v[24:25], v[24:25], v[168:169]
	v_lshl_add_u64 v[32:33], v[32:33], 0, v[200:201]
	v_pk_mul_f32 v[30:31], v[30:31], v[190:191] op_sel_hi:[1,0]
	v_pk_mul_f32 v[28:29], v[28:29], v[190:191] op_sel_hi:[1,0]
	v_pk_mul_f32 v[26:27], v[26:27], v[190:191] op_sel_hi:[1,0]
	v_pk_mul_f32 v[24:25], v[24:25], v[190:191] op_sel_hi:[1,0]
	s_and_b64 vcc, exec, s[0:1]
	v_cvt_pk_bf16_f32 v34, v28, v29
	v_cvt_pk_bf16_f32 v35, v30, v31
	v_cvt_pk_bf16_f32 v36, v24, v25
	v_cvt_pk_bf16_f32 v37, v26, v27
	flat_store_dwordx4 v[32:33], v[34:37] sc1
	s_cbranch_vccnz .LBB0_384
	s_nop 0
	v_lshl_add_u64 v[34:35], s[20:21], 0, v[158:159]
	v_mov_b32_e32 v193, v201
	v_lshl_add_u64 v[34:35], v[34:35], 0, v[192:193]
	flat_store_dwordx4 v[34:35], v[28:31] sc1
	flat_store_dwordx4 v[34:35], v[24:27] offset:16 sc1
.LBB0_384:
	s_nop 1
	v_mov_b32_e32 v24, v190
	v_mov_b32_e32 v25, v190
	v_pk_mul_f32 v[22:23], v[22:23], v[180:181]
	v_mov_b32_e32 v26, v190
	v_mov_b32_e32 v27, v190
	v_pk_mul_f32 v[18:19], v[18:19], v[182:183]
	v_pk_mul_f32 v[16:17], v[16:17], v[174:175]
	v_pk_mul_f32 v[20:21], v[20:21], v[178:179]
	v_pk_mul_f32 v[22:23], v[22:23], v[26:27]
	v_pk_mul_f32 v[26:27], v[18:19], v[26:27]
	v_pk_mul_f32 v[18:19], v[16:17], v[24:25]
	v_pk_mul_f32 v[20:21], v[20:21], v[24:25]
	v_cvt_pk_bf16_f32 v17, v22, v23
	v_cvt_pk_bf16_f32 v18, v18, v19
	v_cvt_pk_bf16_f32 v19, v26, v27
	v_pk_mul_f32 v[14:15], v[14:15], v[172:173]
	v_cvt_pk_bf16_f32 v16, v20, v21
	flat_store_dwordx4 v[32:33], v[16:19] offset:256 sc1
	v_pk_mul_f32 v[12:13], v[12:13], v[170:171]
	v_pk_mul_f32 v[10:11], v[10:11], v[176:177]
	v_mul_lo_u32 v18, s19, v160
	v_mul_lo_u32 v19, s18, v161
	v_mad_u64_u32 v[16:17], s[4:5], s18, v160, 0
	v_add3_u32 v17, v17, v19, v18
	v_lshl_add_u64 v[16:17], v[16:17], 1, s[16:17]
	v_pk_mul_f32 v[8:9], v[8:9], v[168:169]
	v_lshl_add_u64 v[16:17], v[16:17], 0, v[200:201]
	v_pk_mul_f32 v[14:15], v[14:15], v[190:191] op_sel:[0,1]
	v_pk_mul_f32 v[12:13], v[12:13], v[190:191] op_sel:[0,1]
	v_pk_mul_f32 v[10:11], v[10:11], v[190:191] op_sel:[0,1]
	v_pk_mul_f32 v[8:9], v[8:9], v[190:191] op_sel:[0,1]
	s_and_b64 vcc, exec, s[0:1]
	v_cvt_pk_bf16_f32 v18, v12, v13
	v_cvt_pk_bf16_f32 v19, v14, v15
	v_cvt_pk_bf16_f32 v20, v8, v9
	v_cvt_pk_bf16_f32 v21, v10, v11
	flat_store_dwordx4 v[16:17], v[18:21] sc1
	s_cbranch_vccnz .LBB0_386
	s_nop 0
	v_lshl_add_u64 v[18:19], s[20:21], 0, v[162:163]
	v_mov_b32_e32 v193, v201
	v_lshl_add_u64 v[18:19], v[18:19], 0, v[192:193]
	flat_store_dwordx4 v[18:19], v[12:15] sc1
	flat_store_dwordx4 v[18:19], v[8:11] offset:16 sc1
.LBB0_386:
	v_mov_b32_e32 v190, v191
	v_pk_mul_f32 v[6:7], v[6:7], v[180:181]
	v_mov_b32_e32 v8, v191
	v_mov_b32_e32 v9, v191
	v_pk_mul_f32 v[2:3], v[2:3], v[182:183]
	v_pk_mul_f32 v[0:1], v[0:1], v[174:175]
	v_pk_mul_f32 v[4:5], v[4:5], v[178:179]
	v_pk_mul_f32 v[6:7], v[6:7], v[8:9]
	v_pk_mul_f32 v[8:9], v[2:3], v[8:9]
	v_pk_mul_f32 v[2:3], v[0:1], v[190:191]
	s_andn2_b64 vcc, exec, s[14:15]
	s_mov_b64 s[0:1], -1
	v_readlane_b32 s19, v255, 1
	v_pk_mul_f32 v[4:5], v[4:5], v[190:191]
	v_cvt_pk_bf16_f32 v1, v6, v7
	v_cvt_pk_bf16_f32 v2, v2, v3
	v_cvt_pk_bf16_f32 v3, v8, v9
	s_nop 0
	v_cvt_pk_bf16_f32 v0, v4, v5
	flat_store_dwordx4 v[16:17], v[0:3] offset:256 sc1
	s_cbranch_vccnz .LBB0_335
	s_andn2_b64 vcc, exec, s[2:3]
	s_cbranch_vccnz .LBB0_334
	s_barrier
	s_branch .LBB0_334

; __global__ void __launch_bounds__(512, 2) hybrid_fwd(Params p) {
;     ...
;                     float base = 0.f;
; #pragma unroll
;                     for (int g = 0; g < 8; ++g) if (g < wave) base += wt[g];
;                     const float excl = base + xs - run;
; #pragma unroll
;                     for (int j = 0; j < 16; ++j) CC[(size_t)hd * T_ + tid * 16 + j] = excl + pre[j];
;                     __syncthreads();
.LBB0_444:
	v_cndmask_b32_e64 v69, v70, v69, s[14:15]
	v_add_f32_e32 v69, v69, v71
	v_sub_f32_e32 v70, v69, v15
	s_lshl_b64 s[18:19], s[2:3], 15
	v_lshl_add_u64 v[72:73], v[16:17], 0, s[18:19]
	v_pk_add_f32 v[0:1], v[70:71], v[0:1] op_sel_hi:[0,1]
	v_pk_add_f32 v[2:3], v[70:71], v[2:3] op_sel_hi:[0,1]
	flat_store_dwordx4 v[72:73], v[0:3] sc1
	s_nop 1
	v_pk_add_f32 v[0:1], v[70:71], v[4:5] op_sel_hi:[0,1]
	v_pk_add_f32 v[2:3], v[70:71], v[6:7] op_sel_hi:[0,1]
	flat_store_dwordx4 v[72:73], v[0:3] offset:16 sc1
	s_nop 1
	v_pk_add_f32 v[0:1], v[70:71], v[8:9] op_sel_hi:[0,1]
	v_pk_add_f32 v[2:3], v[70:71], v[10:11] op_sel_hi:[0,1]
	flat_store_dwordx4 v[72:73], v[0:3] offset:32 sc1
	s_nop 1
	v_pk_add_f32 v[0:1], v[70:71], v[12:13] op_sel_hi:[0,1]
	v_pk_add_f32 v[2:3], v[70:71], v[14:15] op_sel_hi:[0,1]
	flat_store_dwordx4 v[72:73], v[0:3] offset:48 sc1
	s_waitcnt lgkmcnt(0)
	s_barrier

; __device__ __forceinline__ unsigned cvt_pk_bf16(float lo, float hi) { unsigned r; asm("v_cvt_pk_bf16_f32 %0, %1, %2" : "=v"(r) : "v"(lo), "v"(hi)); return r; }
; __device__ __forceinline__ float xsum(float v) { const auto r = __builtin_amdgcn_permlane32_swap(__float_as_uint(v), __float_as_uint(v), false, false); return __uint_as_float(r[0]) + __uint_as_float(r[1]); }
; __device__ __forceinline__ void st16_wt(void* p, u32x4 v) { asm volatile("global_store_dwordx4 %0, %1, off sc1\n\ts_nop 1" :: "v"(p), "v"(v) : "memory"); }
;     ...
;     l = xsum(l);
;     const float inv = 1.f / l;
; #pragma unroll
;     for (int db = 0; db < 4; ++db)
; #pragma unroll
;         for (int g = 0; g < 4; g += 2) {
;             unsigned ax = cvt_pk_bf16(o[db][4 * g] * inv, o[db][4 * g + 1] * inv), ay = cvt_pk_bf16(o[db][4 * g + 2] * inv, o[db][4 * g + 3] * inv);
;             unsigned bx = cvt_pk_bf16(o[db][4 * g + 4] * inv, o[db][4 * g + 5] * inv), by = cvt_pk_bf16(o[db][4 * g + 6] * inv, o[db][4 * g + 7] * inv);
;             const auto rx = __builtin_amdgcn_permlane32_swap(ax, bx, false, false), ry = __builtin_amdgcn_permlane32_swap(ay, by, false, false);
;             u32x4 w; w.x = rx[0]; w.y = ry[0]; w.z = rx[1]; w.w = ry[1];
;             if (MODE == 2) st16_wt(Orow + 32 * db + 8 * g + 8 * hh, w); else *(u32x4*)(Orow + 32 * db + 8 * g + 8 * hh) = w;
;         }
; __global__ void __launch_bounds__(512, 2) hybrid_fwd(Params p) {
;     ...
;                 for (int si = 0; si < (cc < 64 ? 1 : 3); ++si) {
;                     const int su = cc < 64 ? cc : 64 + (cc - 64) * 3 + si;
;                     const int v = su, kvh = v >> 7, n = (v >> 1) & 63, pr = v & 1;
;                     const int hl = wave >> 2, qh = kvh * 4 + pr * 2 + hl, tq0 = 128 * n + 32 * (wave & 3), t_row = tq0 + (lane & 31);
;                     attn_unit<1>(lds, tid, PROJ + (size_t)t_row * NP + PJ_SQ + qh * 128, PROJ + PJ_SK + kvh * 128, NP, VT + (size_t)(VT_S + kvh * 128) * T_, T_,
;                                  (2 * n - 2) < 0 ? 0 : (2 * n - 2), 2 * n + 2, t_row, tq0, nullptr, p.swa_sinks[l * 8 + qh] * LOG2E, 1.f, t5 + qh * 128,
;                                  O + (size_t)t_row * D_ + 512 + qh * 128);
;                 }
.LBB0_557:
	v_mov_b32_e32 v67, v149
	v_mul_hi_i32_i24_e32 v65, 0xfffff400, v160
	v_mul_i32_i24_e32 v64, 0xfffff400, v160
	v_permlane32_swap_b32_e32 v149, v67
	v_lshl_add_u64 v[64:65], v[146:147], 0, v[64:65]
	v_add_f32_e32 v67, v149, v67
	v_lshl_add_u64 v[64:65], s[4:5], 1, v[64:65]
	v_div_scale_f32 v68, s[4:5], v67, v67, 1.0
	v_rcp_f32_e32 v69, v68
	v_lshlrev_b32_e32 v66, 3, v161
	v_lshlrev_b32_e32 v200, 1, v66
	v_lshl_add_u64 v[64:65], v[64:65], 0, v[200:201]
	v_fma_f32 v70, -v68, v69, 1.0
	v_fmac_f32_e32 v69, v70, v69
	v_div_scale_f32 v70, vcc, 1.0, v67, 1.0
	v_mul_f32_e32 v71, v70, v69
	v_fma_f32 v72, -v68, v71, v70
	v_fmac_f32_e32 v71, v72, v69
	v_fma_f32 v68, -v68, v71, v70
	v_div_fmas_f32 v68, v68, v69, v71
	v_div_fixup_f32 v68, v68, v67, 1.0
	v_mul_f32_e32 v48, v48, v68
	v_mul_f32_e32 v49, v49, v68
	v_mul_f32_e32 v32, v32, v68
	v_mul_f32_e32 v33, v33, v68
	v_mul_f32_e32 v16, v16, v68
	v_mul_f32_e32 v17, v17, v68
	v_mul_f32_e32 v0, v0, v68
	v_mul_f32_e32 v1, v1, v68
	v_cvt_pk_bf16_f32 v48, v48, v49
	v_mul_f32_e32 v49, v50, v68
	v_mul_f32_e32 v50, v51, v68
	v_cvt_pk_bf16_f32 v32, v32, v33
	v_mul_f32_e32 v33, v34, v68
	v_mul_f32_e32 v34, v35, v68
	v_cvt_pk_bf16_f32 v16, v16, v17
	v_mul_f32_e32 v17, v18, v68
	v_mul_f32_e32 v18, v19, v68
	v_cvt_pk_bf16_f32 v0, v0, v1
	v_mul_f32_e32 v1, v2, v68
	v_mul_f32_e32 v2, v3, v68
	s_mov_b64 s[4:5], 0x24300400
	v_cvt_pk_bf16_f32 v49, v49, v50
	v_mul_f32_e32 v50, v52, v68
	v_mul_f32_e32 v51, v53, v68
	v_cvt_pk_bf16_f32 v33, v33, v34
	v_mul_f32_e32 v34, v36, v68
	v_mul_f32_e32 v35, v37, v68
	v_cvt_pk_bf16_f32 v17, v17, v18
	v_mul_f32_e32 v18, v20, v68
	v_mul_f32_e32 v19, v21, v68
	v_cvt_pk_bf16_f32 v1, v1, v2
	v_mul_f32_e32 v2, v4, v68
	v_mul_f32_e32 v3, v5, v68
	v_lshl_add_u64 v[66:67], v[64:65], 0, s[4:5]
	v_cvt_pk_bf16_f32 v50, v50, v51
	v_mul_f32_e32 v51, v54, v68
	v_mul_f32_e32 v52, v55, v68
	s_mov_b32 s4, 0x24300000
	v_cvt_pk_bf16_f32 v34, v34, v35
	v_mul_f32_e32 v35, v38, v68
	v_cvt_pk_bf16_f32 v18, v18, v19
	v_mul_f32_e32 v19, v22, v68
	v_cvt_pk_bf16_f32 v2, v2, v3
	v_mul_f32_e32 v3, v6, v68
	v_cvt_pk_bf16_f32 v51, v51, v52
	v_add_co_u32_e32 v52, vcc, s4, v64
	v_mul_f32_e32 v36, v39, v68
	v_cvt_pk_bf16_f32 v35, v35, v36
	v_mul_f32_e32 v20, v23, v68
	v_cvt_pk_bf16_f32 v19, v19, v20
	v_mul_f32_e32 v4, v7, v68
	v_cvt_pk_bf16_f32 v3, v3, v4
	v_permlane32_swap_b32_e32 v48, v50
	v_permlane32_swap_b32_e32 v49, v51
	v_addc_co_u32_e32 v53, vcc, 0, v65, vcc
	v_permlane32_swap_b32_e32 v32, v34
	v_permlane32_swap_b32_e32 v33, v35
	v_permlane32_swap_b32_e32 v16, v18
	v_permlane32_swap_b32_e32 v17, v19
	v_permlane32_swap_b32_e32 v0, v2
	v_permlane32_swap_b32_e32 v1, v3
	flat_store_dwordx4 v[52:53], v[48:51] offset:1024 sc1
	flat_store_dwordx4 v[66:67], v[32:35] offset:64 sc1
	flat_store_dwordx4 v[66:67], v[16:19] offset:128 sc1
	v_mul_f32_e32 v48, v56, v68
	v_mul_f32_e32 v49, v57, v68
	v_mul_f32_e32 v32, v40, v68
	v_mul_f32_e32 v33, v41, v68
	v_mul_f32_e32 v16, v24, v68
	v_mul_f32_e32 v17, v25, v68
	flat_store_dwordx4 v[66:67], v[0:3] offset:192 sc1
	v_cvt_pk_bf16_f32 v48, v48, v49
	v_mul_f32_e32 v49, v58, v68
	v_mul_f32_e32 v50, v59, v68
	v_mul_f32_e32 v0, v8, v68
	v_mul_f32_e32 v1, v9, v68
	v_cvt_pk_bf16_f32 v32, v32, v33
	v_mul_f32_e32 v33, v42, v68
	v_mul_f32_e32 v34, v43, v68
	v_cvt_pk_bf16_f32 v16, v16, v17
	v_mul_f32_e32 v17, v26, v68
	v_mul_f32_e32 v18, v27, v68
	v_cvt_pk_bf16_f32 v0, v0, v1
	v_mul_f32_e32 v1, v10, v68
	v_mul_f32_e32 v2, v11, v68
	v_cvt_pk_bf16_f32 v49, v49, v50
	v_mul_f32_e32 v50, v60, v68
	v_mul_f32_e32 v51, v61, v68
	v_cvt_pk_bf16_f32 v33, v33, v34
	v_mul_f32_e32 v34, v44, v68
	v_mul_f32_e32 v35, v45, v68
	v_cvt_pk_bf16_f32 v17, v17, v18
	v_mul_f32_e32 v18, v28, v68
	v_mul_f32_e32 v19, v29, v68
	v_cvt_pk_bf16_f32 v1, v1, v2
	v_mul_f32_e32 v2, v12, v68
	v_mul_f32_e32 v3, v13, v68
	v_cvt_pk_bf16_f32 v50, v50, v51
	v_mul_f32_e32 v51, v62, v68
	v_cvt_pk_bf16_f32 v34, v34, v35
	v_mul_f32_e32 v35, v46, v68
	v_cvt_pk_bf16_f32 v18, v18, v19
	v_mul_f32_e32 v19, v30, v68
	v_cvt_pk_bf16_f32 v2, v2, v3
	v_mul_f32_e32 v3, v14, v68
	v_mul_f32_e32 v52, v63, v68
	v_cvt_pk_bf16_f32 v51, v51, v52
	v_mul_f32_e32 v36, v47, v68
	v_cvt_pk_bf16_f32 v35, v35, v36
	v_mul_f32_e32 v20, v31, v68
	v_cvt_pk_bf16_f32 v19, v19, v20
	v_mul_f32_e32 v4, v15, v68
	v_cvt_pk_bf16_f32 v3, v3, v4
	s_add_i32 s23, s23, 1
	v_permlane32_swap_b32_e32 v48, v50
	v_permlane32_swap_b32_e32 v49, v51
	v_permlane32_swap_b32_e32 v32, v34
	v_permlane32_swap_b32_e32 v33, v35
	v_permlane32_swap_b32_e32 v16, v18
	v_permlane32_swap_b32_e32 v17, v19
	v_permlane32_swap_b32_e32 v0, v2
	v_permlane32_swap_b32_e32 v1, v3
	s_cmp_lg_u32 s23, s13
	flat_store_dwordx4 v[66:67], v[48:51] offset:32 sc1
	flat_store_dwordx4 v[66:67], v[32:35] offset:96 sc1
	flat_store_dwordx4 v[66:67], v[16:19] offset:160 sc1
	flat_store_dwordx4 v[66:67], v[0:3] offset:224 sc1
	s_cbranch_scc0 .LBB0_567

; __device__ __forceinline__ unsigned cvt_pk_bf16(float lo, float hi) { unsigned r; asm("v_cvt_pk_bf16_f32 %0, %1, %2" : "=v"(r) : "v"(lo), "v"(hi)); return r; }
; __device__ __forceinline__ float xsum(float v) { const auto r = __builtin_amdgcn_permlane32_swap(__float_as_uint(v), __float_as_uint(v), false, false); return __uint_as_float(r[0]) + __uint_as_float(r[1]); }
; __device__ __forceinline__ void st16_wt(void* p, u32x4 v) { asm volatile("global_store_dwordx4 %0, %1, off sc1\n\ts_nop 1" :: "v"(p), "v"(v) : "memory"); }
;     ...
;     if (MODE == 0) __syncthreads();
;     ...
;     l = xsum(l);
;     const float inv = 1.f / l;
; #pragma unroll
;     for (int db = 0; db < 4; ++db)
; #pragma unroll
;         for (int g = 0; g < 4; g += 2) {
;             unsigned ax = cvt_pk_bf16(o[db][4 * g] * inv, o[db][4 * g + 1] * inv), ay = cvt_pk_bf16(o[db][4 * g + 2] * inv, o[db][4 * g + 3] * inv);
;             unsigned bx = cvt_pk_bf16(o[db][4 * g + 4] * inv, o[db][4 * g + 5] * inv), by = cvt_pk_bf16(o[db][4 * g + 6] * inv, o[db][4 * g + 7] * inv);
;             const auto rx = __builtin_amdgcn_permlane32_swap(ax, bx, false, false), ry = __builtin_amdgcn_permlane32_swap(ay, by, false, false);
;             u32x4 w; w.x = rx[0]; w.y = ry[0]; w.z = rx[1]; w.w = ry[1];
;             if (MODE == 2) st16_wt(Orow + 32 * db + 8 * g + 8 * hh, w); else *(u32x4*)(Orow + 32 * db + 8 * g + 8 * hh) = w;
;         }
.LBB0_590:
	v_mov_b32_e32 v66, v177
	s_nop 1
	v_permlane32_swap_b32_e32 v177, v66
	v_add_f32_e32 v66, v177, v66
	v_div_scale_f32 v67, s[0:1], v66, v66, 1.0
	v_rcp_f32_e32 v68, v67
	v_lshlrev_b64 v[64:65], 12, v[146:147]
	v_lshl_add_u64 v[64:65], s[8:9], 0, v[64:65]
	s_lshl_b32 s72, s16, 1
	v_fma_f32 v69, -v67, v68, 1.0
	v_fmac_f32_e32 v68, v69, v68
	v_div_scale_f32 v69, vcc, 1.0, v66, 1.0
	v_mul_f32_e32 v70, v69, v68
	v_fma_f32 v71, -v67, v70, v69
	v_fmac_f32_e32 v70, v71, v68
	v_fma_f32 v67, -v67, v70, v69
	v_div_fmas_f32 v67, v67, v68, v70
	v_div_fixup_f32 v68, v67, v66, 1.0
	v_mul_f32_e32 v48, v48, v68
	v_mul_f32_e32 v49, v49, v68
	v_mul_f32_e32 v32, v32, v68
	v_mul_f32_e32 v33, v33, v68
	v_mul_f32_e32 v16, v16, v68
	v_mul_f32_e32 v17, v17, v68
	v_mul_f32_e32 v0, v0, v68
	v_mul_f32_e32 v1, v1, v68
	v_lshl_add_u64 v[64:65], v[64:65], 0, s[72:73]
	v_lshlrev_b32_e32 v200, 1, v151
	v_cvt_pk_bf16_f32 v48, v48, v49
	v_mul_f32_e32 v49, v50, v68
	v_mul_f32_e32 v50, v51, v68
	v_cvt_pk_bf16_f32 v32, v32, v33
	v_mul_f32_e32 v33, v34, v68
	v_mul_f32_e32 v34, v35, v68
	v_cvt_pk_bf16_f32 v16, v16, v17
	v_mul_f32_e32 v17, v18, v68
	v_mul_f32_e32 v18, v19, v68
	v_cvt_pk_bf16_f32 v0, v0, v1
	v_mul_f32_e32 v1, v2, v68
	v_mul_f32_e32 v2, v3, v68
	v_lshl_add_u64 v[64:65], v[64:65], 0, v[200:201]
	s_mov_b64 s[0:1], 0x24300000
	v_cvt_pk_bf16_f32 v49, v49, v50
	v_mul_f32_e32 v50, v52, v68
	v_mul_f32_e32 v51, v53, v68
	v_cvt_pk_bf16_f32 v33, v33, v34
	v_mul_f32_e32 v34, v36, v68
	v_mul_f32_e32 v35, v37, v68
	v_cvt_pk_bf16_f32 v17, v17, v18
	v_mul_f32_e32 v18, v20, v68
	v_mul_f32_e32 v19, v21, v68
	v_cvt_pk_bf16_f32 v1, v1, v2
	v_mul_f32_e32 v2, v4, v68
	v_mul_f32_e32 v3, v5, v68
	v_lshl_add_u64 v[66:67], v[64:65], 0, s[0:1]
	v_cvt_pk_bf16_f32 v50, v50, v51
	v_mul_f32_e32 v51, v54, v68
	v_mul_f32_e32 v52, v55, v68
	s_mov_b32 s0, 0x24300000
	v_cvt_pk_bf16_f32 v34, v34, v35
	v_mul_f32_e32 v35, v38, v68
	v_cvt_pk_bf16_f32 v18, v18, v19
	v_mul_f32_e32 v19, v22, v68
	v_cvt_pk_bf16_f32 v2, v2, v3
	v_mul_f32_e32 v3, v6, v68
	v_cvt_pk_bf16_f32 v51, v51, v52
	v_add_co_u32_e32 v52, vcc, s0, v64
	v_mul_f32_e32 v36, v39, v68
	v_cvt_pk_bf16_f32 v35, v35, v36
	v_mul_f32_e32 v20, v23, v68
	v_cvt_pk_bf16_f32 v19, v19, v20
	v_mul_f32_e32 v4, v7, v68
	v_cvt_pk_bf16_f32 v3, v3, v4
	v_permlane32_swap_b32_e32 v48, v50
	v_permlane32_swap_b32_e32 v49, v51
	v_addc_co_u32_e32 v53, vcc, 0, v65, vcc
	v_permlane32_swap_b32_e32 v32, v34
	v_permlane32_swap_b32_e32 v33, v35
	v_permlane32_swap_b32_e32 v16, v18
	v_permlane32_swap_b32_e32 v17, v19
	v_permlane32_swap_b32_e32 v0, v2
	v_permlane32_swap_b32_e32 v1, v3
	s_barrier
	flat_store_dwordx4 v[52:53], v[48:51] sc1
	flat_store_dwordx4 v[66:67], v[32:35] offset:64 sc1
	flat_store_dwordx4 v[66:67], v[16:19] offset:128 sc1
	v_mul_f32_e32 v48, v56, v68
	v_mul_f32_e32 v49, v57, v68
	v_mul_f32_e32 v32, v40, v68
	v_mul_f32_e32 v33, v41, v68
	v_mul_f32_e32 v16, v24, v68
	v_mul_f32_e32 v17, v25, v68
	flat_store_dwordx4 v[66:67], v[0:3] offset:192 sc1
	v_cvt_pk_bf16_f32 v48, v48, v49
	v_mul_f32_e32 v49, v58, v68
	v_mul_f32_e32 v50, v59, v68
	v_mul_f32_e32 v0, v8, v68
	v_mul_f32_e32 v1, v9, v68
	v_cvt_pk_bf16_f32 v32, v32, v33
	v_mul_f32_e32 v33, v42, v68
	v_mul_f32_e32 v34, v43, v68
	v_cvt_pk_bf16_f32 v16, v16, v17
	v_mul_f32_e32 v17, v26, v68
	v_mul_f32_e32 v18, v27, v68
	v_cvt_pk_bf16_f32 v0, v0, v1
	v_mul_f32_e32 v1, v10, v68
	v_mul_f32_e32 v2, v11, v68
	v_cvt_pk_bf16_f32 v49, v49, v50
	v_mul_f32_e32 v50, v60, v68
	v_mul_f32_e32 v51, v61, v68
	v_cvt_pk_bf16_f32 v33, v33, v34
	v_mul_f32_e32 v34, v44, v68
	v_mul_f32_e32 v35, v45, v68
	v_cvt_pk_bf16_f32 v17, v17, v18
	v_mul_f32_e32 v18, v28, v68
	v_mul_f32_e32 v19, v29, v68
	v_cvt_pk_bf16_f32 v1, v1, v2
	v_mul_f32_e32 v2, v12, v68
	v_mul_f32_e32 v3, v13, v68
	v_cvt_pk_bf16_f32 v50, v50, v51
	v_mul_f32_e32 v51, v62, v68
	v_cvt_pk_bf16_f32 v34, v34, v35
	v_mul_f32_e32 v35, v46, v68
	v_cvt_pk_bf16_f32 v18, v18, v19
	v_mul_f32_e32 v19, v30, v68
	v_cvt_pk_bf16_f32 v2, v2, v3
	v_mul_f32_e32 v3, v14, v68
	v_mul_f32_e32 v52, v63, v68
	v_cvt_pk_bf16_f32 v51, v51, v52
	v_mul_f32_e32 v36, v47, v68
	v_cvt_pk_bf16_f32 v35, v35, v36
	v_mul_f32_e32 v20, v31, v68
	v_cvt_pk_bf16_f32 v19, v19, v20
	v_mul_f32_e32 v4, v15, v68
	v_cvt_pk_bf16_f32 v3, v3, v4
	v_permlane32_swap_b32_e32 v48, v50
	v_permlane32_swap_b32_e32 v49, v51
	v_permlane32_swap_b32_e32 v32, v34
	v_permlane32_swap_b32_e32 v33, v35
	v_permlane32_swap_b32_e32 v16, v18
	v_permlane32_swap_b32_e32 v17, v19
	v_permlane32_swap_b32_e32 v0, v2
	v_permlane32_swap_b32_e32 v1, v3
	flat_store_dwordx4 v[66:67], v[48:51] offset:32 sc1
	flat_store_dwordx4 v[66:67], v[32:35] offset:96 sc1
	flat_store_dwordx4 v[66:67], v[16:19] offset:160 sc1
	flat_store_dwordx4 v[66:67], v[0:3] offset:224 sc1
	v_cmp_eq_u32_e32 vcc, 0, v144
	s_and_saveexec_b64 s[0:1], vcc
	s_cbranch_execz .LBB0_604

; __device__ __forceinline__ unsigned cvt_pk_bf16(float lo, float hi) { unsigned r; asm("v_cvt_pk_bf16_f32 %0, %1, %2" : "=v"(r) : "v"(lo), "v"(hi)); return r; }
; __device__ __forceinline__ float bflo(unsigned w) { return __uint_as_float(w << 16); }
; __device__ __forceinline__ float bfhi(unsigned w) { return __uint_as_float(w & 0xffff0000u); }
; template <int MODEC>
; __device__ __forceinline__ void gla_unit(LAS unsigned char* lds, const int tid_in, const Params& p, int l, int hh, int n) {
;     ...
;         __syncthreads();
;         const float tot = (ss[tt * 4] + ss[tt * 4 + 1]) + (ss[tt * 4 + 2] + ss[tt * 4 + 3]);
;         const float rstd = rsqrtf(tot * (1.f / 128.f) + EPS);
;         bf16_t* op = (bf16_t*)(ws + WS_O) + (size_t)(t0 + tt) * D_ + 1536 + hh * 128;
;         const bf16_t* grp = proj + (size_t)(t0 + tt) * NP + PJ_GR + hh * 128;
;         const float* gn = p.gla_norm + l * 128;
; #pragma unroll
;         for (int g = 0; g < 4; ++g) {
;             const int dv = 32 * dvb + 8 * g + 4 * h2;
;             const u32x2 gw = *(const u32x2*)(grp + dv); const f32x4 gnv = *(const f32x4*)(gn + dv);
;             const float g0 = bflo(gw.x), g1 = bfhi(gw.x), g2 = bflo(gw.y), g3 = bfhi(gw.y);
;             const float v0 = acc[4 * g] * rstd * gnv[0] * (g0 * __builtin_amdgcn_rcpf(1.f + __expf(-g0))), v1 = acc[4 * g + 1] * rstd * gnv[1] * (g1 * __builtin_amdgcn_rcpf(1.f + __expf(-g1)));
;             const float v2 = acc[4 * g + 2] * rstd * gnv[2] * (g2 * __builtin_amdgcn_rcpf(1.f + __expf(-g2))), v3 = acc[4 * g + 3] * rstd * gnv[3] * (g3 * __builtin_amdgcn_rcpf(1.f + __expf(-g3)));
;             u32x2 wv; wv.x = cvt_pk_bf16(v0, v1); wv.y = cvt_pk_bf16(v2, v3); *(u32x2*)(op + dv) = wv;
;         }
;         __syncthreads();
.LBB0_606:
	s_or_b64 exec, exec, s[0:1]
	v_add_u32_e32 v16, 0, v17
	s_waitcnt lgkmcnt(0)
	s_barrier
	ds_read_b128 v[16:19], v16 offset:37120
	s_ashr_i32 s77, s76, 31
	v_mov_b64_e32 v[22:23], s[34:35]
	s_lshl_b64 s[0:1], s[76:77], 1
	s_add_i32 s2, s2, s70
	s_waitcnt lgkmcnt(0)
	v_mov_b32_e32 v20, v17
	v_mov_b32_e32 v21, v18
	v_mov_b32_e32 v17, v19
	v_pk_add_f32 v[16:17], v[20:21], v[16:17]
	v_lshl_or_b32 v21, v89, 2, s45
	v_add_f32_e32 v16, v16, v17
	v_fmamk_f32 v16, v16, 0x3c000000, v240
	v_cmp_gt_f32_e32 vcc, s85, v16
	v_mul_f32_e32 v17, 0x4b800000, v16
	v_lshlrev_b32_e32 v200, 1, v21
	v_cndmask_b32_e32 v16, v16, v17, vcc
	v_rsq_f32_e32 v16, v16
	s_movk_i32 s45, 0x1000
	v_lshlrev_b32_e32 v21, 2, v21
	s_add_u32 s92, s92, s74
	v_mul_f32_e32 v17, 0x45800000, v16
	v_cndmask_b32_e32 v20, v16, v17, vcc
	v_add_u32_e32 v16, s44, v90
	v_ashrrev_i32_e32 v17, 31, v16
	v_lshlrev_b64 v[18:19], 12, v[16:17]
	v_mad_i64_i32 v[16:17], s[4:5], v16, s56, v[22:23]
	v_lshl_add_u64 v[18:19], s[86:87], 0, v[18:19]
	v_lshl_add_u64 v[16:17], v[16:17], 0, s[0:1]
	v_lshl_add_u64 v[18:19], v[18:19], 0, s[0:1]
	v_lshl_add_u64 v[22:23], v[16:17], 0, v[200:201]
	s_mov_b64 s[0:1], 0x1600
	v_lshl_add_u64 v[16:17], v[22:23], 0, s[0:1]
	v_add_co_u32_e32 v22, vcc, s45, v22
	v_mul_f32_e32 v29, v0, v20
	s_nop 0
	v_addc_co_u32_e32 v23, vcc, 0, v23, vcc
	flat_load_dwordx2 v[26:27], v[22:23] offset:1536
	v_mul_f32_e32 v31, v2, v20
	global_load_dwordx4 v[22:25], v21, s[80:81]
	v_mul_f32_e32 v33, v3, v20
	v_lshl_add_u64 v[18:19], v[18:19], 0, v[200:201]
	s_mov_b64 s[0:1], 0x24300c00
	s_addc_u32 s93, s93, s75
	s_add_i32 s3, s3, s39
	s_cmpk_gt_i32 s2, 0x1ff
	s_waitcnt vmcnt(0) lgkmcnt(0)
	v_lshlrev_b32_e32 v28, 16, v26
	v_mul_f32_e32 v0, 0xbfb8aa3b, v28
	v_exp_f32_e32 v0, v0
	v_and_b32_e32 v26, 0xffff0000, v26
	v_mov_b32_e32 v35, v22
	v_lshlrev_b32_e32 v30, 16, v27
	v_add_f32_e32 v0, 1.0, v0
	v_rcp_f32_e32 v34, v0
	v_mul_f32_e32 v0, 0xbfb8aa3b, v26
	v_exp_f32_e32 v0, v0
	v_and_b32_e32 v32, 0xffff0000, v27
	v_mul_f32_e32 v27, v1, v20
	v_pk_mul_f32 v[28:29], v[34:35], v[28:29]
	v_add_f32_e32 v0, 1.0, v0
	v_rcp_f32_e32 v22, v0
	v_mul_f32_e32 v28, v28, v29
	v_pk_mul_f32 v[0:1], v[22:23], v[26:27]
	s_nop 0
	v_mul_f32_e32 v22, v0, v1
	v_mul_f32_e32 v0, 0xbfb8aa3b, v30
	v_exp_f32_e32 v0, v0
	v_mov_b32_e32 v1, v24
	v_cvt_pk_bf16_f32 v2, v28, v22
	v_mul_f32_e32 v26, v5, v20
	v_add_f32_e32 v0, 1.0, v0
	v_rcp_f32_e32 v0, v0
	v_mul_f32_e32 v28, v6, v20
	v_pk_mul_f32 v[0:1], v[0:1], v[30:31]
	s_nop 0
	v_mul_f32_e32 v23, v0, v1
	v_mul_f32_e32 v0, 0xbfb8aa3b, v32
	v_exp_f32_e32 v0, v0
	s_nop 0
	v_add_f32_e32 v0, 1.0, v0
	v_rcp_f32_e32 v24, v0
	s_nop 0
	v_pk_mul_f32 v[0:1], v[24:25], v[32:33]
	s_nop 0
	v_mul_f32_e32 v0, v0, v1
	v_cvt_pk_bf16_f32 v3, v23, v0
	v_lshl_add_u64 v[0:1], v[18:19], 0, s[0:1]
	s_mov_b32 s0, 0x24300000
	v_add_co_u32_e32 v18, vcc, s0, v18
	s_nop 1
	v_addc_co_u32_e32 v19, vcc, 0, v19, vcc
	flat_store_dwordx2 v[18:19], v[2:3] offset:3072 sc1
	flat_load_dwordx2 v[2:3], v[16:17] offset:16
	s_nop 0
	global_load_dwordx4 v[22:25], v21, s[80:81] offset:32
	v_mul_f32_e32 v18, v4, v20
	s_waitcnt vmcnt(0) lgkmcnt(0)
	v_lshlrev_b32_e32 v19, 16, v2
	v_and_b32_e32 v27, 0xffff0000, v2
	v_mul_f32_e32 v2, 0xbfb8aa3b, v19
	v_exp_f32_e32 v2, v2
	v_lshlrev_b32_e32 v29, 16, v3
	v_mov_b32_e32 v30, v22
	v_mov_b32_e32 v4, v23
	v_add_f32_e32 v2, 1.0, v2
	v_rcp_f32_e32 v31, v2
	v_mul_f32_e32 v2, 0xbfb8aa3b, v27
	v_exp_f32_e32 v2, v2
	v_and_b32_e32 v3, 0xffff0000, v3
	v_pk_mul_f32 v[18:19], v[30:31], v[18:19]
	v_add_f32_e32 v2, 1.0, v2
	v_rcp_f32_e32 v5, v2
	v_mul_f32_e32 v2, 0xbfb8aa3b, v29
	v_exp_f32_e32 v2, v2
	v_mul_f32_e32 v18, v18, v19
	v_pk_mul_f32 v[4:5], v[4:5], v[26:27]
	v_mul_f32_e32 v26, v8, v20
	v_add_f32_e32 v2, 1.0, v2
	v_mul_f32_e32 v19, v4, v5
	v_rcp_f32_e32 v5, v2
	v_mov_b32_e32 v4, v24
	v_mul_f32_e32 v2, v7, v20
	v_mul_f32_e32 v8, v9, v20
	v_pk_mul_f32 v[4:5], v[4:5], v[28:29]
	s_nop 0
	v_mul_f32_e32 v6, v4, v5
	v_mul_f32_e32 v4, 0xbfb8aa3b, v3
	v_exp_f32_e32 v4, v4
	s_nop 0
	v_add_f32_e32 v4, 1.0, v4
	v_rcp_f32_e32 v5, v4
	v_mov_b32_e32 v4, v25
	v_pk_mul_f32 v[2:3], v[4:5], v[2:3]
	s_nop 0
	v_mul_f32_e32 v3, v2, v3
	v_cvt_pk_bf16_f32 v2, v18, v19
	v_cvt_pk_bf16_f32 v3, v6, v3
	flat_store_dwordx2 v[0:1], v[2:3] offset:16 sc1
	flat_load_dwordx2 v[6:7], v[16:17] offset:32
	s_nop 0
	global_load_dwordx4 v[2:5], v21, s[80:81] offset:64
	s_waitcnt vmcnt(0) lgkmcnt(0)
	v_and_b32_e32 v23, 0xffff0000, v6
	v_mov_b32_e32 v18, v2
	v_mul_f32_e32 v2, 0xbfb8aa3b, v23
	v_exp_f32_e32 v2, v2
	v_mov_b32_e32 v22, v3
	v_lshlrev_b32_e32 v25, 16, v7
	v_mov_b32_e32 v24, v4
	v_add_f32_e32 v2, 1.0, v2
	v_rcp_f32_e32 v9, v2
	v_and_b32_e32 v7, 0xffff0000, v7
	v_lshlrev_b32_e32 v19, 16, v6
	v_mul_f32_e32 v6, 0xbfb8aa3b, v19
	v_pk_mul_f32 v[2:3], v[8:9], v[22:23]
	v_exp_f32_e32 v6, v6
	v_mul_f32_e32 v8, v2, v3
	v_mul_f32_e32 v3, 0xbfb8aa3b, v25
	v_exp_f32_e32 v3, v3
	v_mul_f32_e32 v2, v10, v20
	v_add_f32_e32 v6, 1.0, v6
	v_rcp_f32_e32 v27, v6
	v_add_f32_e32 v3, 1.0, v3
	v_rcp_f32_e32 v3, v3
	v_mov_b32_e32 v6, v5
	v_pk_mul_f32 v[18:19], v[26:27], v[18:19]
	v_pk_mul_f32 v[2:3], v[2:3], v[24:25]
	s_nop 0
	v_mul_f32_e32 v4, v2, v3
	v_mul_f32_e32 v3, 0xbfb8aa3b, v7
	v_exp_f32_e32 v3, v3
	v_mul_f32_e32 v2, v11, v20
	v_mul_f32_e32 v18, v18, v19
	v_add_f32_e32 v3, 1.0, v3
	v_rcp_f32_e32 v3, v3
	s_nop 0
	v_pk_mul_f32 v[2:3], v[2:3], v[6:7]
	s_nop 0
	v_mul_f32_e32 v3, v2, v3
	v_cvt_pk_bf16_f32 v2, v18, v8
	v_cvt_pk_bf16_f32 v3, v4, v3
	flat_store_dwordx2 v[0:1], v[2:3] offset:32 sc1
	flat_load_dwordx2 v[2:3], v[16:17] offset:48
	s_nop 0
	global_load_dwordx4 v[4:7], v21, s[80:81] offset:96
	v_mul_f32_e32 v18, v12, v20
	s_waitcnt vmcnt(0) lgkmcnt(0)
	v_lshlrev_b32_e32 v9, 16, v2
	v_and_b32_e32 v11, 0xffff0000, v2
	v_mul_f32_e32 v2, 0xbfb8aa3b, v9
	v_exp_f32_e32 v2, v2
	v_mov_b32_e32 v8, v4
	v_lshlrev_b32_e32 v17, 16, v3
	v_mov_b32_e32 v10, v5
	v_add_f32_e32 v2, 1.0, v2
	v_rcp_f32_e32 v19, v2
	v_mul_f32_e32 v2, 0xbfb8aa3b, v11
	v_exp_f32_e32 v2, v2
	v_and_b32_e32 v3, 0xffff0000, v3
	v_pk_mul_f32 v[8:9], v[18:19], v[8:9]
	v_mov_b32_e32 v16, v6
	v_add_f32_e32 v2, 1.0, v2
	v_mul_f32_e32 v12, v8, v9
	v_rcp_f32_e32 v9, v2
	v_mul_f32_e32 v2, 0xbfb8aa3b, v17
	v_exp_f32_e32 v2, v2
	v_mul_f32_e32 v8, v13, v20
	v_pk_mul_f32 v[4:5], v[8:9], v[10:11]
	v_add_f32_e32 v2, 1.0, v2
	v_mul_f32_e32 v8, v4, v5
	v_rcp_f32_e32 v5, v2
	v_mul_f32_e32 v2, 0xbfb8aa3b, v3
	v_exp_f32_e32 v2, v2
	v_mul_f32_e32 v4, v14, v20
	v_pk_mul_f32 v[4:5], v[4:5], v[16:17]
	v_add_f32_e32 v2, 1.0, v2
	v_mul_f32_e32 v6, v4, v5
	v_rcp_f32_e32 v5, v2
	v_mul_f32_e32 v4, v15, v20
	v_mov_b32_e32 v2, v7
	v_pk_mul_f32 v[2:3], v[4:5], v[2:3]
	s_nop 0
	v_mul_f32_e32 v3, v2, v3
	v_cvt_pk_bf16_f32 v2, v12, v8
	v_cvt_pk_bf16_f32 v3, v6, v3
	flat_store_dwordx2 v[0:1], v[2:3] offset:48 sc1
	s_waitcnt lgkmcnt(0)
	s_barrier
	s_cbranch_scc1 .LBB0_619

; __device__ __forceinline__ unsigned cvt_pk_bf16(float lo, float hi) { unsigned r; asm("v_cvt_pk_bf16_f32 %0, %1, %2" : "=v"(r) : "v"(lo), "v"(hi)); return r; }
; __device__ __forceinline__ float bflo(unsigned w) { return __uint_as_float(w << 16); }
; __device__ __forceinline__ float bfhi(unsigned w) { return __uint_as_float(w & 0xffff0000u); }
; __device__ __forceinline__ float shx(float v, int off, int lane) { return __int_as_float(__builtin_amdgcn_ds_bpermute((lane ^ off) << 2, __float_as_int(v))); }
;     __device__ __forceinline__ void operator()(const f32x4 (&acc)[2][2][4][2], const RU& u, int wr, int wc, int fr, int fq) const {
;         const int col0 = u.pn * 256 + wc * 32 + 8 * fq, ln_ = fq * 16 + fr;
;         u32x4 bb[2][4][2];
; #pragma unroll
;         for (int ai = 0; ai < 2; ++ai)
; #pragma unroll
;             for (int m = 0; m < 4; ++m) { const bf16_t* rp = hb + (size_t)(u.pm * 256 + ai * 128 + wr * 64 + m * 16 + fr) * D_ + col0; bb[ai][m][0] = *(const u32x4*)rp; bb[ai][m][1] = *(const u32x4*)(rp + 128); }
; #pragma unroll
;         for (int ai = 0; ai < 2; ++ai)
; #pragma unroll
;             for (int m = 0; m < 4; ++m) {
;                 const int row = u.pm * 256 + ai * 128 + wr * 64 + m * 16 + fr; float sq = 0.f;
;                 bf16_t* rp = hb + (size_t)row * D_ + col0;
; #pragma unroll
;                 for (int bj = 0; bj < 2; ++bj) {
;                     const u32x4 b = bb[ai][m][bj];
;                     const f32x4 v0 = acc[ai][bj][m][0] + (f32x4){bflo(b.x), bfhi(b.x), bflo(b.y), bfhi(b.y)};
;                     const f32x4 v1 = acc[ai][bj][m][1] + (f32x4){bflo(b.z), bfhi(b.z), bflo(b.w), bfhi(b.w)};
;                     u32x4 w; w.x = cvt_pk_bf16(v0[0], v0[1]); w.y = cvt_pk_bf16(v0[2], v0[3]); w.z = cvt_pk_bf16(v1[0], v1[1]); w.w = cvt_pk_bf16(v1[2], v1[3]);
;                     *(u32x4*)(rp + bj * 128) = w;
;                     sq += ((v0[0] * v0[0] + v0[1] * v0[1]) + (v0[2] * v0[2] + v0[3] * v0[3])) + ((v1[0] * v1[0] + v1[1] * v1[1]) + (v1[2] * v1[2] + v1[3] * v1[3]));
;                 }
;                 sq += shx(sq, 16, ln_); sq += shx(sq, 32, ln_);
;                 if (fq == 0) red[wc * 256 + ai * 128 + wr * 64 + m * 16 + fr] = sq;
.LBB0_685:
	s_mul_i32 s16, s44, s23
	s_add_i32 s16, s16, s22
	s_lshl_b32 s17, s16, 3
	s_and_b32 s17, s17, 0xffffff00
	s_lshl_b32 s16, s16, 8
	v_or_b32_e32 v204, s17, v221
	s_and_b32 s18, s16, 0x1f00
	v_add_u32_e32 v112, s18, v202
	v_ashrrev_i32_e32 v205, 31, v204
	v_lshlrev_b64 v[232:233], 1, v[204:205]
	v_ashrrev_i32_e32 v113, 31, v112
	v_lshl_add_u64 v[114:115], s[6:7], 0, v[232:233]
	v_lshlrev_b64 v[236:237], 12, v[112:113]
	v_lshl_add_u64 v[116:117], v[114:115], 0, v[236:237]
	flat_load_dwordx4 v[228:231], v[116:117]
	flat_load_dwordx4 v[184:187], v[116:117] offset:256
	v_or_b32_e32 v116, 16, v112
	v_ashrrev_i32_e32 v117, 31, v116
	v_lshlrev_b64 v[218:219], 12, v[116:117]
	v_lshl_add_u64 v[116:117], v[114:115], 0, v[218:219]
	flat_load_dwordx4 v[180:183], v[116:117]
	flat_load_dwordx4 v[176:179], v[116:117] offset:256
	v_or_b32_e32 v116, 32, v112
	v_or_b32_e32 v112, 48, v112
	v_ashrrev_i32_e32 v117, 31, v116
	v_ashrrev_i32_e32 v113, 31, v112
	v_lshlrev_b64 v[216:217], 12, v[116:117]
	v_lshlrev_b64 v[214:215], 12, v[112:113]
	s_mov_b64 s[16:17], 0x80000
	v_lshl_add_u64 v[116:117], v[114:115], 0, v[216:217]
	v_lshl_add_u64 v[112:113], v[114:115], 0, v[214:215]
	v_lshl_add_u64 v[212:213], v[236:237], 0, s[16:17]
	s_mov_b64 s[16:17], 0x90000
	flat_load_dwordx4 v[172:175], v[116:117]
	flat_load_dwordx4 v[168:171], v[116:117] offset:256
	flat_load_dwordx4 v[164:167], v[112:113]
	flat_load_dwordx4 v[160:163], v[112:113] offset:256
	v_lshl_add_u64 v[112:113], v[114:115], 0, v[212:213]
	v_lshl_add_u64 v[210:211], v[236:237], 0, s[16:17]
	s_mov_b64 s[16:17], 0xa0000
	flat_load_dwordx4 v[156:159], v[112:113]
	flat_load_dwordx4 v[144:147], v[112:113] offset:256
	v_lshl_add_u64 v[112:113], v[114:115], 0, v[210:211]
	v_lshl_add_u64 v[208:209], v[236:237], 0, s[16:17]
	s_mov_b64 s[16:17], 0xb0000
	flat_load_dwordx4 v[140:143], v[112:113]
	flat_load_dwordx4 v[136:139], v[112:113] offset:256
	v_lshl_add_u64 v[112:113], v[114:115], 0, v[208:209]
	v_lshl_add_u64 v[206:207], v[236:237], 0, s[16:17]
	flat_load_dwordx4 v[128:131], v[112:113]
	flat_load_dwordx4 v[116:119], v[112:113] offset:256
	v_lshl_add_u64 v[112:113], v[114:115], 0, v[206:207]
	flat_load_dwordx4 v[120:123], v[112:113]
	s_nop 0
	flat_load_dwordx4 v[112:115], v[112:113] offset:256
	v_lshl_add_u64 v[236:237], s[6:7], 0, v[236:237]
	v_lshl_add_u64 v[232:233], v[236:237], 0, v[232:233]
	s_waitcnt vmcnt(0) lgkmcnt(0)
	v_lshlrev_b32_e32 v236, 16, v228
	v_and_b32_e32 v237, 0xffff0000, v228
	v_lshlrev_b32_e32 v228, 16, v229
	v_and_b32_e32 v229, 0xffff0000, v229
	v_pk_add_f32 v[154:155], v[154:155], v[228:229]
	v_lshlrev_b32_e32 v228, 16, v230
	v_and_b32_e32 v229, 0xffff0000, v230
	v_pk_add_f32 v[152:153], v[152:153], v[236:237]
	v_lshlrev_b32_e32 v230, 16, v231
	v_and_b32_e32 v231, 0xffff0000, v231
	v_pk_add_f32 v[228:229], v[148:149], v[228:229]
	v_cvt_pk_bf16_f32 v148, v152, v153
	v_cvt_pk_bf16_f32 v149, v154, v155
	v_pk_add_f32 v[230:231], v[150:151], v[230:231]
	v_cvt_pk_bf16_f32 v150, v228, v229
	s_nop 0
	v_cvt_pk_bf16_f32 v151, v230, v231
	flat_store_dwordx4 v[232:233], v[148:151] sc1
	s_nop 1
	v_mul_f32_e32 v148, v153, v153
	v_mul_f32_e32 v149, v155, v155
	v_fmac_f32_e32 v148, v152, v152
	v_fmac_f32_e32 v149, v154, v154
	v_add_f32_e32 v148, v148, v149
	v_mul_f32_e32 v149, v229, v229
	v_mul_f32_e32 v150, v231, v231
	v_fmac_f32_e32 v149, v228, v228
	v_fmac_f32_e32 v150, v230, v230
	v_add_f32_e32 v149, v149, v150
	v_add_f32_e32 v152, v148, v149
	v_lshlrev_b32_e32 v148, 16, v184
	v_and_b32_e32 v149, 0xffff0000, v184
	v_lshlrev_b32_e32 v150, 16, v185
	v_and_b32_e32 v151, 0xffff0000, v185
	v_pk_add_f32 v[132:133], v[132:133], v[148:149]
	v_lshlrev_b32_e32 v148, 16, v186
	v_and_b32_e32 v149, 0xffff0000, v186
	v_pk_add_f32 v[134:135], v[134:135], v[150:151]
	v_lshlrev_b32_e32 v150, 16, v187
	v_and_b32_e32 v151, 0xffff0000, v187
	v_pk_add_f32 v[148:149], v[124:125], v[148:149]
	v_cvt_pk_bf16_f32 v124, v132, v133
	v_cvt_pk_bf16_f32 v125, v134, v135
	v_pk_add_f32 v[150:151], v[126:127], v[150:151]
	v_cvt_pk_bf16_f32 v126, v148, v149
	s_nop 0
	v_cvt_pk_bf16_f32 v127, v150, v151
	flat_store_dwordx4 v[232:233], v[124:127] offset:256 sc1
	s_nop 1
	v_mul_f32_e32 v124, v133, v133
	v_mul_f32_e32 v125, v135, v135
	v_fmac_f32_e32 v124, v132, v132
	v_fmac_f32_e32 v125, v134, v134
	v_add_f32_e32 v124, v124, v125
	v_mul_f32_e32 v125, v149, v149
	v_mul_f32_e32 v126, v151, v151
	v_fmac_f32_e32 v125, v148, v148
	v_fmac_f32_e32 v126, v150, v150
	v_add_f32_e32 v125, v125, v126
	v_add_f32_e32 v124, v124, v125
	v_add_f32_e32 v124, v152, v124
	ds_bpermute_b32 v125, v222, v124
	s_waitcnt lgkmcnt(0)
	v_add_f32_e32 v124, v124, v125
	ds_bpermute_b32 v125, v223, v124
	s_and_saveexec_b64 s[16:17], s[0:1]
	s_cbranch_execz .LBB0_687
	s_waitcnt lgkmcnt(0)
	v_add_f32_e32 v124, v124, v125
	ds_write_b32 v224, v124
; __device__ __forceinline__ unsigned cvt_pk_bf16(float lo, float hi) { unsigned r; asm("v_cvt_pk_bf16_f32 %0, %1, %2" : "=v"(r) : "v"(lo), "v"(hi)); return r; }
; __device__ __forceinline__ float bflo(unsigned w) { return __uint_as_float(w << 16); }
; __device__ __forceinline__ float bfhi(unsigned w) { return __uint_as_float(w & 0xffff0000u); }
; __device__ __forceinline__ float shx(float v, int off, int lane) { return __int_as_float(__builtin_amdgcn_ds_bpermute((lane ^ off) << 2, __float_as_int(v))); }
;     __device__ __forceinline__ void operator()(const f32x4 (&acc)[2][2][4][2], const RU& u, int wr, int wc, int fr, int fq) const {
;     ...
;         for (int ai = 0; ai < 2; ++ai)
; #pragma unroll
;             for (int m = 0; m < 4; ++m) {
;                 const int row = u.pm * 256 + ai * 128 + wr * 64 + m * 16 + fr; float sq = 0.f;
;                 bf16_t* rp = hb + (size_t)row * D_ + col0;
; #pragma unroll
;                 for (int bj = 0; bj < 2; ++bj) {
;                     const u32x4 b = bb[ai][m][bj];
;                     const f32x4 v0 = acc[ai][bj][m][0] + (f32x4){bflo(b.x), bfhi(b.x), bflo(b.y), bfhi(b.y)};
;                     const f32x4 v1 = acc[ai][bj][m][1] + (f32x4){bflo(b.z), bfhi(b.z), bflo(b.w), bfhi(b.w)};
;                     u32x4 w; w.x = cvt_pk_bf16(v0[0], v0[1]); w.y = cvt_pk_bf16(v0[2], v0[3]); w.z = cvt_pk_bf16(v1[0], v1[1]); w.w = cvt_pk_bf16(v1[2], v1[3]);
;                     *(u32x4*)(rp + bj * 128) = w;
;                     sq += ((v0[0] * v0[0] + v0[1] * v0[1]) + (v0[2] * v0[2] + v0[3] * v0[3])) + ((v1[0] * v1[0] + v1[1] * v1[1]) + (v1[2] * v1[2] + v1[3] * v1[3]));
;                 }
;                 sq += shx(sq, 16, ln_); sq += shx(sq, 32, ln_);
;                 if (fq == 0) red[wc * 256 + ai * 128 + wr * 64 + m * 16 + fr] = sq;
.LBB0_687:
	s_or_b64 exec, exec, s[16:17]
	v_lshlrev_b32_e32 v126, 16, v180
	v_and_b32_e32 v127, 0xffff0000, v180
	v_lshlrev_b32_e32 v132, 16, v181
	v_and_b32_e32 v133, 0xffff0000, v181
	v_pk_add_f32 v[110:111], v[110:111], v[132:133]
	v_pk_add_f32 v[108:109], v[108:109], v[126:127]
	v_lshlrev_b32_e32 v126, 16, v182
	v_and_b32_e32 v127, 0xffff0000, v182
	v_lshlrev_b32_e32 v132, 16, v183
	v_and_b32_e32 v133, 0xffff0000, v183
	v_pk_add_f32 v[132:133], v[106:107], v[132:133]
	v_pk_add_f32 v[106:107], v[104:105], v[126:127]
	v_cvt_pk_bf16_f32 v104, v108, v109
	v_mul_f32_e32 v109, v109, v109
	v_fmac_f32_e32 v109, v108, v108
	v_mul_f32_e32 v108, v111, v111
	v_fmac_f32_e32 v108, v110, v110
	v_cvt_pk_bf16_f32 v105, v110, v111
	v_add_f32_e32 v108, v109, v108
	v_mul_f32_e32 v109, v107, v107
	v_mul_f32_e32 v110, v133, v133
	v_fmac_f32_e32 v109, v106, v106
	v_fmac_f32_e32 v110, v132, v132
	v_add_f32_e32 v109, v109, v110
	v_add_f32_e32 v126, v108, v109
	v_lshlrev_b32_e32 v108, 16, v176
	v_and_b32_e32 v109, 0xffff0000, v176
	v_lshlrev_b32_e32 v110, 16, v177
	v_and_b32_e32 v111, 0xffff0000, v177
	v_pk_add_f32 v[102:103], v[102:103], v[110:111]
	v_pk_add_f32 v[100:101], v[100:101], v[108:109]
	v_lshlrev_b32_e32 v108, 16, v178
	v_and_b32_e32 v109, 0xffff0000, v178
	v_lshlrev_b32_e32 v110, 16, v179
	v_and_b32_e32 v111, 0xffff0000, v179
	v_pk_add_f32 v[108:109], v[96:97], v[108:109]
	v_mul_f32_e32 v96, v101, v101
	v_mul_f32_e32 v97, v103, v103
	v_pk_add_f32 v[110:111], v[98:99], v[110:111]
	v_fmac_f32_e32 v96, v100, v100
	v_fmac_f32_e32 v97, v102, v102
	v_add_f32_e32 v96, v96, v97
	v_mul_f32_e32 v97, v109, v109
	v_mul_f32_e32 v98, v111, v111
	v_fmac_f32_e32 v97, v108, v108
	v_fmac_f32_e32 v98, v110, v110
	v_add_f32_e32 v97, v97, v98
	v_add_f32_e32 v96, v96, v97
	v_add_f32_e32 v96, v126, v96
	ds_bpermute_b32 v97, v222, v96
	s_waitcnt lgkmcnt(0)
	v_lshl_add_u64 v[124:125], s[6:7], 0, v[218:219]
	v_lshl_add_u64 v[124:125], v[204:205], 1, v[124:125]
	v_cvt_pk_bf16_f32 v106, v106, v107
	v_cvt_pk_bf16_f32 v107, v132, v133
	v_add_f32_e32 v96, v96, v97
	ds_bpermute_b32 v97, v223, v96
	flat_store_dwordx4 v[124:125], v[104:107] sc1
	v_cvt_pk_bf16_f32 v98, v100, v101
	v_cvt_pk_bf16_f32 v99, v102, v103
	v_cvt_pk_bf16_f32 v100, v108, v109
	v_cvt_pk_bf16_f32 v101, v110, v111
	flat_store_dwordx4 v[124:125], v[98:101] offset:256 sc1
	s_and_saveexec_b64 s[16:17], s[0:1]
	s_cbranch_execz .LBB0_689
	s_waitcnt lgkmcnt(0)
	v_add_f32_e32 v96, v96, v97
	ds_write_b32 v224, v96 offset:64
.LBB0_689:
	s_or_b64 exec, exec, s[16:17]
	v_lshlrev_b32_e32 v98, 16, v172
	v_and_b32_e32 v99, 0xffff0000, v172
	v_lshlrev_b32_e32 v100, 16, v173
	v_and_b32_e32 v101, 0xffff0000, v173
	v_pk_add_f32 v[94:95], v[94:95], v[100:101]
	v_pk_add_f32 v[92:93], v[92:93], v[98:99]
	v_lshlrev_b32_e32 v98, 16, v174
	v_and_b32_e32 v99, 0xffff0000, v174
	v_lshlrev_b32_e32 v100, 16, v175
	v_and_b32_e32 v101, 0xffff0000, v175
	v_pk_add_f32 v[100:101], v[90:91], v[100:101]
	v_pk_add_f32 v[90:91], v[88:89], v[98:99]
	v_cvt_pk_bf16_f32 v88, v92, v93
	v_mul_f32_e32 v93, v93, v93
	v_fmac_f32_e32 v93, v92, v92
	v_mul_f32_e32 v92, v95, v95
	v_fmac_f32_e32 v92, v94, v94
	v_cvt_pk_bf16_f32 v89, v94, v95
	v_add_f32_e32 v92, v93, v92
	v_mul_f32_e32 v93, v91, v91
	v_mul_f32_e32 v94, v101, v101
	v_fmac_f32_e32 v93, v90, v90
	v_fmac_f32_e32 v94, v100, v100
	v_add_f32_e32 v93, v93, v94
	v_add_f32_e32 v98, v92, v93
	v_lshlrev_b32_e32 v92, 16, v168
	v_and_b32_e32 v93, 0xffff0000, v168
	v_lshlrev_b32_e32 v94, 16, v169
	v_and_b32_e32 v95, 0xffff0000, v169
	v_pk_add_f32 v[86:87], v[86:87], v[94:95]
	v_pk_add_f32 v[84:85], v[84:85], v[92:93]
	v_lshlrev_b32_e32 v92, 16, v170
	v_and_b32_e32 v93, 0xffff0000, v170
	v_lshlrev_b32_e32 v94, 16, v171
	v_and_b32_e32 v95, 0xffff0000, v171
	v_pk_add_f32 v[92:93], v[80:81], v[92:93]
	v_mul_f32_e32 v80, v85, v85
	v_mul_f32_e32 v81, v87, v87
	v_pk_add_f32 v[94:95], v[82:83], v[94:95]
	v_fmac_f32_e32 v80, v84, v84
	v_fmac_f32_e32 v81, v86, v86
	v_add_f32_e32 v80, v80, v81
	v_mul_f32_e32 v81, v93, v93
	v_mul_f32_e32 v82, v95, v95
	v_fmac_f32_e32 v81, v92, v92
	v_fmac_f32_e32 v82, v94, v94
	v_add_f32_e32 v81, v81, v82
	v_add_f32_e32 v80, v80, v81
	v_add_f32_e32 v80, v98, v80
	ds_bpermute_b32 v81, v222, v80
	s_waitcnt lgkmcnt(0)
	v_lshl_add_u64 v[96:97], s[6:7], 0, v[216:217]
	v_lshl_add_u64 v[96:97], v[204:205], 1, v[96:97]
	v_cvt_pk_bf16_f32 v90, v90, v91
	v_cvt_pk_bf16_f32 v91, v100, v101
	v_add_f32_e32 v80, v80, v81
	ds_bpermute_b32 v81, v223, v80
	flat_store_dwordx4 v[96:97], v[88:91] sc1
	v_cvt_pk_bf16_f32 v82, v84, v85
	v_cvt_pk_bf16_f32 v83, v86, v87
	v_cvt_pk_bf16_f32 v84, v92, v93
	v_cvt_pk_bf16_f32 v85, v94, v95
	flat_store_dwordx4 v[96:97], v[82:85] offset:256 sc1
	s_and_saveexec_b64 s[16:17], s[0:1]
	s_cbranch_execz .LBB0_691
	s_waitcnt lgkmcnt(0)
	v_add_f32_e32 v80, v80, v81
	ds_write_b32 v224, v80 offset:128
; __device__ __forceinline__ unsigned cvt_pk_bf16(float lo, float hi) { unsigned r; asm("v_cvt_pk_bf16_f32 %0, %1, %2" : "=v"(r) : "v"(lo), "v"(hi)); return r; }
; __device__ __forceinline__ float bflo(unsigned w) { return __uint_as_float(w << 16); }
; __device__ __forceinline__ float bfhi(unsigned w) { return __uint_as_float(w & 0xffff0000u); }
; __device__ __forceinline__ float shx(float v, int off, int lane) { return __int_as_float(__builtin_amdgcn_ds_bpermute((lane ^ off) << 2, __float_as_int(v))); }
;     __device__ __forceinline__ void operator()(const f32x4 (&acc)[2][2][4][2], const RU& u, int wr, int wc, int fr, int fq) const {
;     ...
;         for (int ai = 0; ai < 2; ++ai)
; #pragma unroll
;             for (int m = 0; m < 4; ++m) {
;                 const int row = u.pm * 256 + ai * 128 + wr * 64 + m * 16 + fr; float sq = 0.f;
;                 bf16_t* rp = hb + (size_t)row * D_ + col0;
; #pragma unroll
;                 for (int bj = 0; bj < 2; ++bj) {
;                     const u32x4 b = bb[ai][m][bj];
;                     const f32x4 v0 = acc[ai][bj][m][0] + (f32x4){bflo(b.x), bfhi(b.x), bflo(b.y), bfhi(b.y)};
;                     const f32x4 v1 = acc[ai][bj][m][1] + (f32x4){bflo(b.z), bfhi(b.z), bflo(b.w), bfhi(b.w)};
;                     u32x4 w; w.x = cvt_pk_bf16(v0[0], v0[1]); w.y = cvt_pk_bf16(v0[2], v0[3]); w.z = cvt_pk_bf16(v1[0], v1[1]); w.w = cvt_pk_bf16(v1[2], v1[3]);
;                     *(u32x4*)(rp + bj * 128) = w;
;                     sq += ((v0[0] * v0[0] + v0[1] * v0[1]) + (v0[2] * v0[2] + v0[3] * v0[3])) + ((v1[0] * v1[0] + v1[1] * v1[1]) + (v1[2] * v1[2] + v1[3] * v1[3]));
;                 }
;                 sq += shx(sq, 16, ln_); sq += shx(sq, 32, ln_);
;                 if (fq == 0) red[wc * 256 + ai * 128 + wr * 64 + m * 16 + fr] = sq;
.LBB0_691:
	s_or_b64 exec, exec, s[16:17]
	v_lshlrev_b32_e32 v82, 16, v164
	v_and_b32_e32 v83, 0xffff0000, v164
	v_lshlrev_b32_e32 v84, 16, v165
	v_and_b32_e32 v85, 0xffff0000, v165
	v_pk_add_f32 v[78:79], v[78:79], v[84:85]
	v_pk_add_f32 v[76:77], v[76:77], v[82:83]
	v_lshlrev_b32_e32 v82, 16, v166
	v_and_b32_e32 v83, 0xffff0000, v166
	v_lshlrev_b32_e32 v84, 16, v167
	v_and_b32_e32 v85, 0xffff0000, v167
	v_pk_add_f32 v[84:85], v[74:75], v[84:85]
	v_pk_add_f32 v[74:75], v[72:73], v[82:83]
	v_cvt_pk_bf16_f32 v72, v76, v77
	v_mul_f32_e32 v77, v77, v77
	v_fmac_f32_e32 v77, v76, v76
	v_mul_f32_e32 v76, v79, v79
	v_fmac_f32_e32 v76, v78, v78
	v_cvt_pk_bf16_f32 v73, v78, v79
	v_add_f32_e32 v76, v77, v76
	v_mul_f32_e32 v77, v75, v75
	v_mul_f32_e32 v78, v85, v85
	v_fmac_f32_e32 v77, v74, v74
	v_fmac_f32_e32 v78, v84, v84
	v_add_f32_e32 v77, v77, v78
	v_add_f32_e32 v82, v76, v77
	v_lshlrev_b32_e32 v76, 16, v160
	v_and_b32_e32 v77, 0xffff0000, v160
	v_lshlrev_b32_e32 v78, 16, v161
	v_and_b32_e32 v79, 0xffff0000, v161
	v_pk_add_f32 v[70:71], v[70:71], v[78:79]
	v_pk_add_f32 v[68:69], v[68:69], v[76:77]
	v_lshlrev_b32_e32 v76, 16, v162
	v_and_b32_e32 v77, 0xffff0000, v162
	v_lshlrev_b32_e32 v78, 16, v163
	v_and_b32_e32 v79, 0xffff0000, v163
	v_pk_add_f32 v[76:77], v[64:65], v[76:77]
	v_mul_f32_e32 v64, v69, v69
	v_mul_f32_e32 v65, v71, v71
	v_pk_add_f32 v[78:79], v[66:67], v[78:79]
	v_fmac_f32_e32 v64, v68, v68
	v_fmac_f32_e32 v65, v70, v70
	v_add_f32_e32 v64, v64, v65
	v_mul_f32_e32 v65, v77, v77
	v_mul_f32_e32 v66, v79, v79
	v_fmac_f32_e32 v65, v76, v76
	v_fmac_f32_e32 v66, v78, v78
	v_add_f32_e32 v65, v65, v66
	v_add_f32_e32 v64, v64, v65
	v_add_f32_e32 v64, v82, v64
	ds_bpermute_b32 v65, v222, v64
	s_waitcnt lgkmcnt(0)
	v_lshl_add_u64 v[80:81], s[6:7], 0, v[214:215]
	v_lshl_add_u64 v[80:81], v[204:205], 1, v[80:81]
	v_cvt_pk_bf16_f32 v74, v74, v75
	v_cvt_pk_bf16_f32 v75, v84, v85
	v_add_f32_e32 v64, v64, v65
	ds_bpermute_b32 v65, v223, v64
	flat_store_dwordx4 v[80:81], v[72:75] sc1
	v_cvt_pk_bf16_f32 v66, v68, v69
	v_cvt_pk_bf16_f32 v67, v70, v71
	v_cvt_pk_bf16_f32 v68, v76, v77
	v_cvt_pk_bf16_f32 v69, v78, v79
	flat_store_dwordx4 v[80:81], v[66:69] offset:256 sc1
	s_and_saveexec_b64 s[16:17], s[0:1]
	s_cbranch_execz .LBB0_693
	s_waitcnt lgkmcnt(0)
	v_add_f32_e32 v64, v64, v65
	ds_write_b32 v224, v64 offset:192
.LBB0_693:
	s_or_b64 exec, exec, s[16:17]
	v_lshlrev_b32_e32 v66, 16, v156
	v_and_b32_e32 v67, 0xffff0000, v156
	v_lshlrev_b32_e32 v68, 16, v157
	v_and_b32_e32 v69, 0xffff0000, v157
	v_pk_add_f32 v[62:63], v[62:63], v[68:69]
	v_pk_add_f32 v[60:61], v[60:61], v[66:67]
	v_lshlrev_b32_e32 v66, 16, v158
	v_and_b32_e32 v67, 0xffff0000, v158
	v_lshlrev_b32_e32 v68, 16, v159
	v_and_b32_e32 v69, 0xffff0000, v159
	v_pk_add_f32 v[68:69], v[58:59], v[68:69]
	v_pk_add_f32 v[58:59], v[56:57], v[66:67]
	v_cvt_pk_bf16_f32 v56, v60, v61
	v_mul_f32_e32 v61, v61, v61
	v_fmac_f32_e32 v61, v60, v60
	v_mul_f32_e32 v60, v63, v63
	v_fmac_f32_e32 v60, v62, v62
	v_cvt_pk_bf16_f32 v57, v62, v63
	v_add_f32_e32 v60, v61, v60
	v_mul_f32_e32 v61, v59, v59
	v_mul_f32_e32 v62, v69, v69
	v_fmac_f32_e32 v61, v58, v58
	v_fmac_f32_e32 v62, v68, v68
	v_add_f32_e32 v61, v61, v62
	v_add_f32_e32 v66, v60, v61
	v_lshlrev_b32_e32 v60, 16, v144
	v_and_b32_e32 v61, 0xffff0000, v144
	v_lshlrev_b32_e32 v62, 16, v145
	v_and_b32_e32 v63, 0xffff0000, v145
	v_pk_add_f32 v[54:55], v[54:55], v[62:63]
	v_pk_add_f32 v[52:53], v[52:53], v[60:61]
	v_lshlrev_b32_e32 v60, 16, v146
	v_and_b32_e32 v61, 0xffff0000, v146
	v_lshlrev_b32_e32 v62, 16, v147
	v_and_b32_e32 v63, 0xffff0000, v147
	v_pk_add_f32 v[60:61], v[48:49], v[60:61]
	v_mul_f32_e32 v48, v53, v53
	v_mul_f32_e32 v49, v55, v55
	v_pk_add_f32 v[62:63], v[50:51], v[62:63]
	v_fmac_f32_e32 v48, v52, v52
	v_fmac_f32_e32 v49, v54, v54
	v_add_f32_e32 v48, v48, v49
	v_mul_f32_e32 v49, v61, v61
	v_mul_f32_e32 v50, v63, v63
	v_fmac_f32_e32 v49, v60, v60
	v_fmac_f32_e32 v50, v62, v62
	v_add_f32_e32 v49, v49, v50
	v_add_f32_e32 v48, v48, v49
	v_add_f32_e32 v48, v66, v48
	ds_bpermute_b32 v49, v222, v48
	s_waitcnt lgkmcnt(0)
	v_lshl_add_u64 v[64:65], s[6:7], 0, v[212:213]
	v_lshl_add_u64 v[64:65], v[204:205], 1, v[64:65]
	v_cvt_pk_bf16_f32 v58, v58, v59
	v_cvt_pk_bf16_f32 v59, v68, v69
	v_add_f32_e32 v48, v48, v49
	ds_bpermute_b32 v49, v223, v48
	flat_store_dwordx4 v[64:65], v[56:59] sc1
	v_cvt_pk_bf16_f32 v50, v52, v53
	v_cvt_pk_bf16_f32 v51, v54, v55
	v_cvt_pk_bf16_f32 v52, v60, v61
	v_cvt_pk_bf16_f32 v53, v62, v63
	flat_store_dwordx4 v[64:65], v[50:53] offset:256 sc1
	s_and_saveexec_b64 s[16:17], s[0:1]
	s_cbranch_execz .LBB0_695
	s_waitcnt lgkmcnt(0)
	v_add_f32_e32 v48, v48, v49
	ds_write_b32 v224, v48 offset:512
; __device__ __forceinline__ unsigned cvt_pk_bf16(float lo, float hi) { unsigned r; asm("v_cvt_pk_bf16_f32 %0, %1, %2" : "=v"(r) : "v"(lo), "v"(hi)); return r; }
; __device__ __forceinline__ float bflo(unsigned w) { return __uint_as_float(w << 16); }
; __device__ __forceinline__ float bfhi(unsigned w) { return __uint_as_float(w & 0xffff0000u); }
; __device__ __forceinline__ float shx(float v, int off, int lane) { return __int_as_float(__builtin_amdgcn_ds_bpermute((lane ^ off) << 2, __float_as_int(v))); }
;     __device__ __forceinline__ void operator()(const f32x4 (&acc)[2][2][4][2], const RU& u, int wr, int wc, int fr, int fq) const {
;     ...
;         for (int ai = 0; ai < 2; ++ai)
; #pragma unroll
;             for (int m = 0; m < 4; ++m) {
;                 const int row = u.pm * 256 + ai * 128 + wr * 64 + m * 16 + fr; float sq = 0.f;
;                 bf16_t* rp = hb + (size_t)row * D_ + col0;
; #pragma unroll
;                 for (int bj = 0; bj < 2; ++bj) {
;                     const u32x4 b = bb[ai][m][bj];
;                     const f32x4 v0 = acc[ai][bj][m][0] + (f32x4){bflo(b.x), bfhi(b.x), bflo(b.y), bfhi(b.y)};
;                     const f32x4 v1 = acc[ai][bj][m][1] + (f32x4){bflo(b.z), bfhi(b.z), bflo(b.w), bfhi(b.w)};
;                     u32x4 w; w.x = cvt_pk_bf16(v0[0], v0[1]); w.y = cvt_pk_bf16(v0[2], v0[3]); w.z = cvt_pk_bf16(v1[0], v1[1]); w.w = cvt_pk_bf16(v1[2], v1[3]);
;                     *(u32x4*)(rp + bj * 128) = w;
;                     sq += ((v0[0] * v0[0] + v0[1] * v0[1]) + (v0[2] * v0[2] + v0[3] * v0[3])) + ((v1[0] * v1[0] + v1[1] * v1[1]) + (v1[2] * v1[2] + v1[3] * v1[3]));
;                 }
;                 sq += shx(sq, 16, ln_); sq += shx(sq, 32, ln_);
;                 if (fq == 0) red[wc * 256 + ai * 128 + wr * 64 + m * 16 + fr] = sq;
.LBB0_695:
	s_or_b64 exec, exec, s[16:17]
	v_lshlrev_b32_e32 v50, 16, v140
	v_and_b32_e32 v51, 0xffff0000, v140
	v_lshlrev_b32_e32 v52, 16, v141
	v_and_b32_e32 v53, 0xffff0000, v141
	v_pk_add_f32 v[46:47], v[46:47], v[52:53]
	v_pk_add_f32 v[44:45], v[44:45], v[50:51]
	v_lshlrev_b32_e32 v50, 16, v142
	v_and_b32_e32 v51, 0xffff0000, v142
	v_lshlrev_b32_e32 v52, 16, v143
	v_and_b32_e32 v53, 0xffff0000, v143
	v_pk_add_f32 v[52:53], v[42:43], v[52:53]
	v_pk_add_f32 v[42:43], v[40:41], v[50:51]
	v_cvt_pk_bf16_f32 v40, v44, v45
	v_mul_f32_e32 v45, v45, v45
	v_fmac_f32_e32 v45, v44, v44
	v_mul_f32_e32 v44, v47, v47
	v_fmac_f32_e32 v44, v46, v46
	v_cvt_pk_bf16_f32 v41, v46, v47
	v_add_f32_e32 v44, v45, v44
	v_mul_f32_e32 v45, v43, v43
	v_mul_f32_e32 v46, v53, v53
	v_fmac_f32_e32 v45, v42, v42
	v_fmac_f32_e32 v46, v52, v52
	v_add_f32_e32 v45, v45, v46
	v_add_f32_e32 v50, v44, v45
	v_lshlrev_b32_e32 v44, 16, v136
	v_and_b32_e32 v45, 0xffff0000, v136
	v_lshlrev_b32_e32 v46, 16, v137
	v_and_b32_e32 v47, 0xffff0000, v137
	v_pk_add_f32 v[38:39], v[38:39], v[46:47]
	v_pk_add_f32 v[36:37], v[36:37], v[44:45]
	v_lshlrev_b32_e32 v44, 16, v138
	v_and_b32_e32 v45, 0xffff0000, v138
	v_lshlrev_b32_e32 v46, 16, v139
	v_and_b32_e32 v47, 0xffff0000, v139
	v_pk_add_f32 v[44:45], v[32:33], v[44:45]
	v_mul_f32_e32 v32, v37, v37
	v_mul_f32_e32 v33, v39, v39
	v_pk_add_f32 v[46:47], v[34:35], v[46:47]
	v_fmac_f32_e32 v32, v36, v36
	v_fmac_f32_e32 v33, v38, v38
	v_add_f32_e32 v32, v32, v33
	v_mul_f32_e32 v33, v45, v45
	v_mul_f32_e32 v34, v47, v47
	v_fmac_f32_e32 v33, v44, v44
	v_fmac_f32_e32 v34, v46, v46
	v_add_f32_e32 v33, v33, v34
	v_add_f32_e32 v32, v32, v33
	v_add_f32_e32 v32, v50, v32
	ds_bpermute_b32 v33, v222, v32
	s_waitcnt lgkmcnt(0)
	v_lshl_add_u64 v[48:49], s[6:7], 0, v[210:211]
	v_lshl_add_u64 v[48:49], v[204:205], 1, v[48:49]
	v_cvt_pk_bf16_f32 v42, v42, v43
	v_cvt_pk_bf16_f32 v43, v52, v53
	v_add_f32_e32 v32, v32, v33
	ds_bpermute_b32 v33, v223, v32
	flat_store_dwordx4 v[48:49], v[40:43] sc1
	v_cvt_pk_bf16_f32 v34, v36, v37
	v_cvt_pk_bf16_f32 v35, v38, v39
	v_cvt_pk_bf16_f32 v36, v44, v45
	v_cvt_pk_bf16_f32 v37, v46, v47
	flat_store_dwordx4 v[48:49], v[34:37] offset:256 sc1
	s_and_saveexec_b64 s[16:17], s[0:1]
	s_cbranch_execz .LBB0_697
	s_waitcnt lgkmcnt(0)
	v_add_f32_e32 v32, v32, v33
	ds_write_b32 v224, v32 offset:576
.LBB0_697:
	s_or_b64 exec, exec, s[16:17]
	v_lshlrev_b32_e32 v34, 16, v128
	v_and_b32_e32 v35, 0xffff0000, v128
	v_lshlrev_b32_e32 v36, 16, v129
	v_and_b32_e32 v37, 0xffff0000, v129
	v_pk_add_f32 v[30:31], v[30:31], v[36:37]
	v_pk_add_f32 v[28:29], v[28:29], v[34:35]
	v_lshlrev_b32_e32 v34, 16, v130
	v_and_b32_e32 v35, 0xffff0000, v130
	v_lshlrev_b32_e32 v36, 16, v131
	v_and_b32_e32 v37, 0xffff0000, v131
	v_pk_add_f32 v[36:37], v[26:27], v[36:37]
	v_pk_add_f32 v[26:27], v[24:25], v[34:35]
	v_cvt_pk_bf16_f32 v24, v28, v29
	v_mul_f32_e32 v29, v29, v29
	v_fmac_f32_e32 v29, v28, v28
	v_mul_f32_e32 v28, v31, v31
	v_fmac_f32_e32 v28, v30, v30
	v_cvt_pk_bf16_f32 v25, v30, v31
	v_add_f32_e32 v28, v29, v28
	v_mul_f32_e32 v29, v27, v27
	v_mul_f32_e32 v30, v37, v37
	v_fmac_f32_e32 v29, v26, v26
	v_fmac_f32_e32 v30, v36, v36
	v_add_f32_e32 v29, v29, v30
	v_add_f32_e32 v34, v28, v29
	v_lshlrev_b32_e32 v28, 16, v116
	v_and_b32_e32 v29, 0xffff0000, v116
	v_lshlrev_b32_e32 v30, 16, v117
	v_and_b32_e32 v31, 0xffff0000, v117
	v_pk_add_f32 v[22:23], v[22:23], v[30:31]
	v_pk_add_f32 v[20:21], v[20:21], v[28:29]
	v_lshlrev_b32_e32 v28, 16, v118
	v_and_b32_e32 v29, 0xffff0000, v118
	v_lshlrev_b32_e32 v30, 16, v119
	v_and_b32_e32 v31, 0xffff0000, v119
	v_pk_add_f32 v[28:29], v[16:17], v[28:29]
	v_mul_f32_e32 v16, v21, v21
	v_mul_f32_e32 v17, v23, v23
	v_pk_add_f32 v[30:31], v[18:19], v[30:31]
	v_fmac_f32_e32 v16, v20, v20
	v_fmac_f32_e32 v17, v22, v22
	v_add_f32_e32 v16, v16, v17
	v_mul_f32_e32 v17, v29, v29
	v_mul_f32_e32 v18, v31, v31
	v_fmac_f32_e32 v17, v28, v28
	v_fmac_f32_e32 v18, v30, v30
	v_add_f32_e32 v17, v17, v18
	v_add_f32_e32 v16, v16, v17
	v_add_f32_e32 v16, v34, v16
	ds_bpermute_b32 v17, v222, v16
	s_waitcnt lgkmcnt(0)
	v_lshl_add_u64 v[32:33], s[6:7], 0, v[208:209]
	v_lshl_add_u64 v[32:33], v[204:205], 1, v[32:33]
	v_cvt_pk_bf16_f32 v26, v26, v27
	v_cvt_pk_bf16_f32 v27, v36, v37
	v_add_f32_e32 v16, v16, v17
	ds_bpermute_b32 v17, v223, v16
	flat_store_dwordx4 v[32:33], v[24:27] sc1
	v_cvt_pk_bf16_f32 v18, v20, v21
	v_cvt_pk_bf16_f32 v19, v22, v23
	v_cvt_pk_bf16_f32 v20, v28, v29
	v_cvt_pk_bf16_f32 v21, v30, v31
	flat_store_dwordx4 v[32:33], v[18:21] offset:256 sc1
	s_and_saveexec_b64 s[16:17], s[0:1]
	s_cbranch_execz .LBB0_699
	s_waitcnt lgkmcnt(0)
	v_add_f32_e32 v16, v16, v17
	ds_write_b32 v224, v16 offset:640
.LBB0_699:
	s_or_b64 exec, exec, s[16:17]
	v_lshlrev_b32_e32 v18, 16, v120
	v_and_b32_e32 v19, 0xffff0000, v120
	v_lshlrev_b32_e32 v20, 16, v121
	v_and_b32_e32 v21, 0xffff0000, v121
	v_pk_add_f32 v[14:15], v[14:15], v[20:21]
	v_pk_add_f32 v[12:13], v[12:13], v[18:19]
	v_lshlrev_b32_e32 v18, 16, v122
	v_and_b32_e32 v19, 0xffff0000, v122
	v_lshlrev_b32_e32 v20, 16, v123
	v_and_b32_e32 v21, 0xffff0000, v123
	v_pk_add_f32 v[20:21], v[10:11], v[20:21]
	v_pk_add_f32 v[10:11], v[8:9], v[18:19]
	v_cvt_pk_bf16_f32 v8, v12, v13
	v_mul_f32_e32 v13, v13, v13
	v_fmac_f32_e32 v13, v12, v12
	v_mul_f32_e32 v12, v15, v15
	v_fmac_f32_e32 v12, v14, v14
	v_cvt_pk_bf16_f32 v9, v14, v15
	v_add_f32_e32 v12, v13, v12
	v_mul_f32_e32 v13, v11, v11
	v_mul_f32_e32 v14, v21, v21
	v_fmac_f32_e32 v13, v10, v10
	v_fmac_f32_e32 v14, v20, v20
	v_add_f32_e32 v13, v13, v14
	v_add_f32_e32 v18, v12, v13
	v_lshlrev_b32_e32 v12, 16, v112
	v_and_b32_e32 v13, 0xffff0000, v112
	v_lshlrev_b32_e32 v14, 16, v113
	v_and_b32_e32 v15, 0xffff0000, v113
	v_pk_add_f32 v[6:7], v[6:7], v[14:15]
	v_pk_add_f32 v[4:5], v[4:5], v[12:13]
	v_lshlrev_b32_e32 v12, 16, v114
	v_and_b32_e32 v13, 0xffff0000, v114
	v_lshlrev_b32_e32 v14, 16, v115
	v_and_b32_e32 v15, 0xffff0000, v115
	v_pk_add_f32 v[12:13], v[0:1], v[12:13]
	v_mul_f32_e32 v0, v5, v5
	v_mul_f32_e32 v1, v7, v7
	v_pk_add_f32 v[14:15], v[2:3], v[14:15]
	v_fmac_f32_e32 v0, v4, v4
	v_fmac_f32_e32 v1, v6, v6
	v_add_f32_e32 v0, v0, v1
	v_mul_f32_e32 v1, v13, v13
	v_mul_f32_e32 v2, v15, v15
	v_fmac_f32_e32 v1, v12, v12
	v_fmac_f32_e32 v2, v14, v14
	v_add_f32_e32 v1, v1, v2
	v_add_f32_e32 v0, v0, v1
	v_add_f32_e32 v0, v18, v0
	ds_bpermute_b32 v1, v222, v0
	s_waitcnt lgkmcnt(0)
	v_lshl_add_u64 v[16:17], s[6:7], 0, v[206:207]
	v_lshl_add_u64 v[16:17], v[204:205], 1, v[16:17]
	v_cvt_pk_bf16_f32 v10, v10, v11
	v_cvt_pk_bf16_f32 v11, v20, v21
	v_add_f32_e32 v0, v0, v1
	ds_bpermute_b32 v1, v223, v0
	flat_store_dwordx4 v[16:17], v[8:11] sc1
	v_cvt_pk_bf16_f32 v2, v4, v5
	v_cvt_pk_bf16_f32 v3, v6, v7
	v_cvt_pk_bf16_f32 v4, v12, v13
	v_cvt_pk_bf16_f32 v5, v14, v15
	flat_store_dwordx4 v[16:17], v[2:5] offset:256 sc1
	s_and_saveexec_b64 s[16:17], s[0:1]
	s_cbranch_execz .LBB0_701
	s_waitcnt lgkmcnt(0)
	v_add_f32_e32 v0, v0, v1
	ds_write_b32 v224, v0 offset:704

; __device__ __forceinline__ float u64f(u64 q) { return (float)(unsigned)(q >> 32) * 4294967296.f + (float)(unsigned)q; }
;     __device__ __forceinline__ void operator()(const f32x4 (&acc)[2][2][4][2], const GU& u, int wr, int wc, int fr, int fq) const {
;     ...
;         if ((u.mode & 3) == 1) { u64 q_[2][4];
; #pragma unroll
;             for (int ai = 0; ai < 2; ++ai)
; #pragma unroll
;                 for (int m = 0; m < 4; ++m) q_[ai][m] = u.sc[r0 + ai * 128 + m * 16];
; #pragma unroll
;             for (int ai = 0; ai < 2; ++ai)
; #pragma unroll
;                 for (int m = 0; m < 4; ++m) rsv[ai][m] = rsqrtf(u64f(q_[ai][m]) * SSQ_INV + EPS);
.Lp6_epi:
	s_mul_i32 s18, s72, s26
	s_add_i32 s18, s18, s24
	s_and_b32 s20, s18, 31
	s_lshl_b32 s19, s20, 18
	s_add_u32 s21, s14, s19
	s_addc_u32 s22, s15, 0
	s_lshl_b32 s18, s18, 2
	s_and_b32 s18, s18, 0xffffff80
	s_ashr_i32 s19, s18, 31
	s_lshl_b64 s[18:19], s[18:19], 1
	s_add_u32 s18, s21, s18
	s_addc_u32 s19, s22, s19
	s_lshl_b32 s72, s20, 11
	v_lshl_add_u64 v[96:97], v[88:89], 0, s[72:73]
	flat_load_dwordx2 v[104:105], v[96:97]
	flat_load_dwordx2 v[112:113], v[96:97] offset:128
	flat_load_dwordx2 v[114:115], v[96:97] offset:256
	flat_load_dwordx2 v[106:107], v[96:97] offset:384
	flat_load_dwordx2 v[108:109], v[96:97] offset:1024
	flat_load_dwordx2 v[110:111], v[96:97] offset:1152
	flat_load_dwordx2 v[102:103], v[96:97] offset:1280
	s_nop 0
	flat_load_dwordx2 v[96:97], v[96:97] offset:1408
	s_min_u32 s20, s91, 32
	s_sub_i32 s21, 32, s20
	s_waitcnt vmcnt(0) lgkmcnt(0)
	v_mov_b32_e32 v200, v105
	v_lshlrev_b64 v[116:117], s20, v[200:201]
	v_min_u32_e32 v95, 1, v116
	v_or_b32_e32 v95, v117, v95
	v_cvt_f32_u32_e32 v95, v95
	v_cvt_f32_u32_e32 v98, v104
	v_mov_b32_e32 v200, v113
	v_lshlrev_b64 v[104:105], s20, v[200:201]
	v_ldexp_f32 v95, v95, s21
	v_fmac_f32_e32 v98, 0x4f800000, v95
	v_fmamk_f32 v95, v98, 0x2e000000, v240
	v_cmp_gt_f32_e32 vcc, s85, v95
	v_mul_f32_e32 v98, 0x4b800000, v95
	v_cvt_f32_u32_e32 v100, v112
	v_cndmask_b32_e32 v95, v95, v98, vcc
	v_rsq_f32_e32 v95, v95
	v_mov_b32_e32 v200, v115
	v_cvt_f32_u32_e32 v102, v102
	v_cvt_f32_u32_e32 v96, v96
	v_mul_f32_e32 v98, 0x45800000, v95
	v_cndmask_b32_e32 v98, v95, v98, vcc
	v_min_u32_e32 v95, 1, v104
	v_or_b32_e32 v95, v105, v95
	v_cvt_f32_u32_e32 v95, v95
	v_lshlrev_b64 v[104:105], s20, v[200:201]
	v_mov_b32_e32 v200, v107
	v_lshlrev_b64 v[112:113], s20, v[200:201]
	v_ldexp_f32 v95, v95, s21
	v_fmac_f32_e32 v100, 0x4f800000, v95
	v_fmamk_f32 v95, v100, 0x2e000000, v240
	v_cmp_gt_f32_e32 vcc, s85, v95
	v_mul_f32_e32 v100, 0x4b800000, v95
	v_mov_b32_e32 v200, v109
	v_cndmask_b32_e32 v95, v95, v100, vcc
	v_rsq_f32_e32 v95, v95
	v_pk_mul_f32 v[62:63], v[62:63], v[98:99] op_sel_hi:[1,0]
	v_pk_mul_f32 v[60:61], v[60:61], v[98:99] op_sel_hi:[1,0]
	v_mul_f32_e32 v100, 0x45800000, v95
	v_cndmask_b32_e32 v100, v95, v100, vcc
	v_min_u32_e32 v95, 1, v104
	v_or_b32_e32 v95, v105, v95
	v_cvt_f32_u32_e32 v95, v95
	v_cvt_f32_u32_e32 v104, v114
	v_cvt_f32_u32_e32 v105, v106
	v_pk_mul_f32 v[114:115], v[58:59], v[98:99] op_sel_hi:[1,0]
	v_ldexp_f32 v95, v95, s21
	v_fmac_f32_e32 v104, 0x4f800000, v95
	v_fmamk_f32 v95, v104, 0x2e000000, v240
	v_cmp_gt_f32_e32 vcc, s85, v95
	v_mul_f32_e32 v104, 0x4b800000, v95
	v_pk_mul_f32 v[58:59], v[56:57], v[98:99] op_sel_hi:[1,0]
	v_cndmask_b32_e32 v95, v95, v104, vcc
	v_rsq_f32_e32 v95, v95
	v_cvt_pk_bf16_f32 v56, v60, v61
	v_cvt_pk_bf16_f32 v57, v62, v63
	v_cvt_pk_bf16_f32 v58, v58, v59
	v_cvt_pk_bf16_f32 v59, v114, v115
	v_pk_mul_f32 v[54:55], v[54:55], v[100:101] op_sel_hi:[1,0]
	v_mul_f32_e32 v104, 0x45800000, v95
	v_cndmask_b32_e32 v104, v95, v104, vcc
	v_min_u32_e32 v95, 1, v112
	v_or_b32_e32 v95, v113, v95
	v_cvt_f32_u32_e32 v95, v95
	v_lshlrev_b64 v[112:113], s20, v[200:201]
	v_mov_b32_e32 v200, v111
	v_pk_mul_f32 v[52:53], v[52:53], v[100:101] op_sel_hi:[1,0]
	v_ldexp_f32 v95, v95, s21
	v_fmac_f32_e32 v105, 0x4f800000, v95
	v_fmamk_f32 v95, v105, 0x2e000000, v240
	v_cmp_gt_f32_e32 vcc, s85, v95
	v_mul_f32_e32 v105, 0x4b800000, v95
	s_nop 0
	v_cndmask_b32_e32 v95, v95, v105, vcc
	v_rsq_f32_e32 v95, v95
	s_nop 0
	v_mul_f32_e32 v105, 0x45800000, v95
	v_cndmask_b32_e32 v106, v95, v105, vcc
	v_min_u32_e32 v95, 1, v112
	v_or_b32_e32 v95, v113, v95
	v_cvt_f32_u32_e32 v95, v95
	v_cvt_f32_u32_e32 v105, v108
	v_lshlrev_b64 v[112:113], s20, v[200:201]
	v_mov_b32_e32 v200, v103
	v_ldexp_f32 v95, v95, s21
	v_fmac_f32_e32 v105, 0x4f800000, v95
	v_fmamk_f32 v95, v105, 0x2e000000, v240
	v_cmp_gt_f32_e32 vcc, s85, v95
	v_mul_f32_e32 v105, 0x4b800000, v95
	v_pk_mul_f32 v[38:39], v[38:39], v[106:107] op_sel_hi:[1,0]
	v_cndmask_b32_e32 v95, v95, v105, vcc
	v_rsq_f32_e32 v95, v95
	v_pk_mul_f32 v[36:37], v[36:37], v[106:107] op_sel_hi:[1,0]
	v_mul_f32_e32 v105, 0x45800000, v95
	v_cndmask_b32_e32 v108, v95, v105, vcc
	v_min_u32_e32 v95, 1, v112
	v_or_b32_e32 v95, v113, v95
	v_cvt_f32_u32_e32 v95, v95
	v_cvt_f32_u32_e32 v105, v110
	v_lshlrev_b64 v[112:113], s20, v[200:201]
	v_mov_b32_e32 v200, v97
	v_ldexp_f32 v95, v95, s21
	v_fmac_f32_e32 v105, 0x4f800000, v95
	v_fmamk_f32 v95, v105, 0x2e000000, v240
	v_cmp_gt_f32_e32 vcc, s85, v95
	v_mul_f32_e32 v105, 0x4b800000, v95
	v_pk_mul_f32 v[30:31], v[30:31], v[108:109] op_sel_hi:[1,0]
	v_cndmask_b32_e32 v95, v95, v105, vcc
	v_rsq_f32_e32 v95, v95
; __device__ __forceinline__ unsigned cvt_pk_bf16(float lo, float hi) { unsigned r; asm("v_cvt_pk_bf16_f32 %0, %1, %2" : "=v"(r) : "v"(lo), "v"(hi)); return r; }
;     __device__ __forceinline__ void operator()(const f32x4 (&acc)[2][2][4][2], const GU& u, int wr, int wc, int fr, int fq) const {
;     ...
; #pragma unroll
;         for (int ai = 0; ai < 2; ++ai)
; #pragma unroll
;             for (int m = 0; m < 4; ++m) {
;                 const int row = r0 + ai * 128 + m * 16;
;                 const float rs = rsv[ai][m];
;                 bf16_t* rowp = u.out + (size_t)row * u.ldc + c0;
; #pragma unroll
;                 for (int bj = 0; bj < 2; ++bj) {
;                     if (bj == 1 && (u.mode & 8)) continue;
;                     f32x4 v0 = acc[ai][bj][m][0] * cs[bj][0] * rs, v1 = acc[ai][bj][m][1] * cs[bj][1] * rs;
;                     u32x4 w; w.x = cvt_pk_bf16(v0[0], v0[1]); w.y = cvt_pk_bf16(v0[2], v0[3]); w.z = cvt_pk_bf16(v1[0], v1[1]); w.w = cvt_pk_bf16(v1[2], v1[3]);
;                     *(u32x4*)(rowp + bj * 128) = w;
;                     if (bj == 0 && u.gates != nullptr && wc == 0) { float* gp = u.gates + (size_t)row * 32 + 8 * fq; *(f32x4*)gp = v0; *(f32x4*)(gp + 4) = v1; }
;                 }
	v_pk_mul_f32 v[28:29], v[28:29], v[108:109] op_sel_hi:[1,0]
	v_mul_f32_e32 v105, 0x45800000, v95
	v_cndmask_b32_e32 v110, v95, v105, vcc
	v_min_u32_e32 v95, 1, v112
	v_or_b32_e32 v95, v113, v95
	v_cvt_f32_u32_e32 v95, v95
	v_lshlrev_b64 v[112:113], s20, v[200:201]
	v_pk_mul_f32 v[46:47], v[46:47], v[104:105] op_sel_hi:[1,0]
	v_pk_mul_f32 v[44:45], v[44:45], v[104:105] op_sel_hi:[1,0]
	v_ldexp_f32 v95, v95, s21
	v_fmac_f32_e32 v102, 0x4f800000, v95
	v_fmamk_f32 v95, v102, 0x2e000000, v240
	v_cmp_gt_f32_e32 vcc, s85, v95
	v_mul_f32_e32 v102, 0x4b800000, v95
	v_pk_mul_f32 v[22:23], v[22:23], v[110:111] op_sel_hi:[1,0]
	v_cndmask_b32_e32 v95, v95, v102, vcc
	v_rsq_f32_e32 v95, v95
	v_pk_mul_f32 v[20:21], v[20:21], v[110:111] op_sel_hi:[1,0]
	v_mul_f32_e32 v102, 0x45800000, v95
	v_cndmask_b32_e32 v102, v95, v102, vcc
	v_min_u32_e32 v95, 1, v112
	v_or_b32_e32 v95, v113, v95
	v_cvt_f32_u32_e32 v95, v95
	v_lshl_add_u64 v[112:113], s[18:19], 0, v[72:73]
	v_pk_mul_f32 v[14:15], v[14:15], v[102:103] op_sel_hi:[1,0]
	v_pk_mul_f32 v[12:13], v[12:13], v[102:103] op_sel_hi:[1,0]
	v_ldexp_f32 v95, v95, s21
	v_fmac_f32_e32 v96, 0x4f800000, v95
	v_fmamk_f32 v95, v96, 0x2e000000, v240
	v_cmp_gt_f32_e32 vcc, s85, v95
	v_mul_f32_e32 v96, 0x4b800000, v95
	s_nop 0
	v_cndmask_b32_e32 v95, v95, v96, vcc
	v_rsq_f32_e32 v95, v95
	s_nop 0
	v_mul_f32_e32 v96, 0x45800000, v95
	v_cndmask_b32_e32 v96, v95, v96, vcc
	v_mov_b32_e32 v95, v201
	v_lshl_add_u64 v[112:113], v[112:113], 0, v[94:95]
	flat_store_dwordx4 v[112:113], v[56:59] sc1
	s_andn2_b64 vcc, exec, s[16:17]
	v_pk_mul_f32 v[6:7], v[6:7], v[96:97] op_sel_hi:[1,0]
	v_lshl_add_u64 v[56:57], s[18:19], 0, v[74:75]
	v_lshl_add_u64 v[56:57], v[56:57], 0, v[94:95]
	v_pk_mul_f32 v[58:59], v[50:51], v[100:101] op_sel_hi:[1,0]
	v_pk_mul_f32 v[50:51], v[48:49], v[100:101] op_sel_hi:[1,0]
	v_cvt_pk_bf16_f32 v48, v52, v53
	v_cvt_pk_bf16_f32 v49, v54, v55
	v_pk_mul_f32 v[4:5], v[4:5], v[96:97] op_sel_hi:[1,0]
	v_cvt_pk_bf16_f32 v50, v50, v51
	v_cvt_pk_bf16_f32 v51, v58, v59
	flat_store_dwordx4 v[56:57], v[48:51] sc1
	s_nop 1
	v_lshl_add_u64 v[48:49], s[18:19], 0, v[76:77]
	v_lshl_add_u64 v[48:49], v[48:49], 0, v[94:95]
	v_pk_mul_f32 v[50:51], v[42:43], v[104:105] op_sel_hi:[1,0]
	v_pk_mul_f32 v[42:43], v[40:41], v[104:105] op_sel_hi:[1,0]
	v_cvt_pk_bf16_f32 v40, v44, v45
	v_cvt_pk_bf16_f32 v41, v46, v47
	s_nop 0
	v_cvt_pk_bf16_f32 v42, v42, v43
	v_cvt_pk_bf16_f32 v43, v50, v51
	flat_store_dwordx4 v[48:49], v[40:43] sc1
	s_nop 1
	v_lshl_add_u64 v[40:41], s[18:19], 0, v[78:79]
	v_lshl_add_u64 v[40:41], v[40:41], 0, v[94:95]
	v_pk_mul_f32 v[42:43], v[34:35], v[106:107] op_sel_hi:[1,0]
	v_pk_mul_f32 v[34:35], v[32:33], v[106:107] op_sel_hi:[1,0]
	v_cvt_pk_bf16_f32 v32, v36, v37
	v_cvt_pk_bf16_f32 v33, v38, v39
	s_nop 0
	v_cvt_pk_bf16_f32 v34, v34, v35
	v_cvt_pk_bf16_f32 v35, v42, v43
	flat_store_dwordx4 v[40:41], v[32:35] sc1
	s_nop 1
	v_lshl_add_u64 v[32:33], s[18:19], 0, v[80:81]
	v_lshl_add_u64 v[32:33], v[32:33], 0, v[94:95]
	v_pk_mul_f32 v[34:35], v[26:27], v[108:109] op_sel_hi:[1,0]
	v_pk_mul_f32 v[26:27], v[24:25], v[108:109] op_sel_hi:[1,0]
	v_cvt_pk_bf16_f32 v24, v28, v29
	v_cvt_pk_bf16_f32 v25, v30, v31
	s_nop 0
	v_cvt_pk_bf16_f32 v26, v26, v27
	v_cvt_pk_bf16_f32 v27, v34, v35
	flat_store_dwordx4 v[32:33], v[24:27] sc1
	s_nop 1
	v_lshl_add_u64 v[24:25], s[18:19], 0, v[82:83]
	v_lshl_add_u64 v[24:25], v[24:25], 0, v[94:95]
	v_pk_mul_f32 v[26:27], v[18:19], v[110:111] op_sel_hi:[1,0]
	v_pk_mul_f32 v[18:19], v[16:17], v[110:111] op_sel_hi:[1,0]
	v_cvt_pk_bf16_f32 v16, v20, v21
	v_cvt_pk_bf16_f32 v17, v22, v23
	s_nop 0
	v_cvt_pk_bf16_f32 v18, v18, v19
	v_cvt_pk_bf16_f32 v19, v26, v27
	flat_store_dwordx4 v[24:25], v[16:19] sc1
	s_nop 1
	v_lshl_add_u64 v[16:17], s[18:19], 0, v[84:85]
	v_lshl_add_u64 v[16:17], v[16:17], 0, v[94:95]
	v_pk_mul_f32 v[18:19], v[10:11], v[102:103] op_sel_hi:[1,0]
	v_pk_mul_f32 v[10:11], v[8:9], v[102:103] op_sel_hi:[1,0]
	v_cvt_pk_bf16_f32 v8, v12, v13
	v_cvt_pk_bf16_f32 v9, v14, v15
	s_nop 0
	v_cvt_pk_bf16_f32 v10, v10, v11
	v_cvt_pk_bf16_f32 v11, v18, v19
	flat_store_dwordx4 v[16:17], v[8:11] sc1
	s_nop 1
	v_lshl_add_u64 v[8:9], s[18:19], 0, v[86:87]
	v_lshl_add_u64 v[8:9], v[8:9], 0, v[94:95]
	v_pk_mul_f32 v[10:11], v[2:3], v[96:97] op_sel_hi:[1,0]
	v_pk_mul_f32 v[2:3], v[0:1], v[96:97] op_sel_hi:[1,0]
	s_mov_b64 s[18:19], -1
	v_cvt_pk_bf16_f32 v0, v4, v5
	v_cvt_pk_bf16_f32 v1, v6, v7
	v_cvt_pk_bf16_f32 v2, v2, v3
	v_cvt_pk_bf16_f32 v3, v10, v11
	flat_store_dwordx4 v[8:9], v[0:3] sc1
	s_cbranch_vccnz .LBB0_764
	s_andn2_b64 vcc, exec, s[10:11]
	s_cbranch_vccnz .LBB0_763
	s_barrier
	s_branch .LBB0_763

; __device__ __forceinline__ unsigned cvt_pk_bf16(float lo, float hi) { unsigned r; asm("v_cvt_pk_bf16_f32 %0, %1, %2" : "=v"(r) : "v"(lo), "v"(hi)); return r; }
; __device__ __forceinline__ float bflo(unsigned w) { return __uint_as_float(w << 16); }
; __device__ __forceinline__ float bfhi(unsigned w) { return __uint_as_float(w & 0xffff0000u); }
; __device__ __forceinline__ float shx(float v, int off, int lane) { return __int_as_float(__builtin_amdgcn_ds_bpermute((lane ^ off) << 2, __float_as_int(v))); }
;     __device__ __forceinline__ void operator()(const f32x4 (&acc)[2][2][4][2], const RU& u, int wr, int wc, int fr, int fq) const {
;         const int col0 = u.pn * 256 + wc * 32 + 8 * fq, ln_ = fq * 16 + fr;
;         u32x4 bb[2][4][2];
; #pragma unroll
;         for (int ai = 0; ai < 2; ++ai)
; #pragma unroll
;             for (int m = 0; m < 4; ++m) { const bf16_t* rp = hb + (size_t)(u.pm * 256 + ai * 128 + wr * 64 + m * 16 + fr) * D_ + col0; bb[ai][m][0] = *(const u32x4*)rp; bb[ai][m][1] = *(const u32x4*)(rp + 128); }
; #pragma unroll
;         for (int ai = 0; ai < 2; ++ai)
; #pragma unroll
;             for (int m = 0; m < 4; ++m) {
;                 const int row = u.pm * 256 + ai * 128 + wr * 64 + m * 16 + fr; float sq = 0.f;
;                 bf16_t* rp = hb + (size_t)row * D_ + col0;
; #pragma unroll
;                 for (int bj = 0; bj < 2; ++bj) {
;                     const u32x4 b = bb[ai][m][bj];
;                     const f32x4 v0 = acc[ai][bj][m][0] + (f32x4){bflo(b.x), bfhi(b.x), bflo(b.y), bfhi(b.y)};
;                     const f32x4 v1 = acc[ai][bj][m][1] + (f32x4){bflo(b.z), bfhi(b.z), bflo(b.w), bfhi(b.w)};
;                     u32x4 w; w.x = cvt_pk_bf16(v0[0], v0[1]); w.y = cvt_pk_bf16(v0[2], v0[3]); w.z = cvt_pk_bf16(v1[0], v1[1]); w.w = cvt_pk_bf16(v1[2], v1[3]);
;                     *(u32x4*)(rp + bj * 128) = w;
;                     sq += ((v0[0] * v0[0] + v0[1] * v0[1]) + (v0[2] * v0[2] + v0[3] * v0[3])) + ((v1[0] * v1[0] + v1[1] * v1[1]) + (v1[2] * v1[2] + v1[3] * v1[3]));
;                 }
;                 sq += shx(sq, 16, ln_); sq += shx(sq, 32, ln_);
;                 if (fq == 0) red[wc * 256 + ai * 128 + wr * 64 + m * 16 + fr] = sq;
.LBB0_809:
	s_mul_i32 s16, s44, s22
	s_add_i32 s16, s16, s23
	s_lshl_b32 s17, s16, 3
	s_and_b32 s17, s17, 0xffffff00
	s_lshl_b32 s16, s16, 8
	v_or_b32_e32 v204, s17, v221
	s_and_b32 s18, s16, 0x1f00
	v_add_u32_e32 v112, s18, v202
	v_ashrrev_i32_e32 v205, 31, v204
	v_lshlrev_b64 v[232:233], 1, v[204:205]
	v_ashrrev_i32_e32 v113, 31, v112
	v_lshl_add_u64 v[114:115], s[6:7], 0, v[232:233]
	v_lshlrev_b64 v[236:237], 12, v[112:113]
	v_lshl_add_u64 v[116:117], v[114:115], 0, v[236:237]
	flat_load_dwordx4 v[228:231], v[116:117]
	flat_load_dwordx4 v[184:187], v[116:117] offset:256
	v_or_b32_e32 v116, 16, v112
	v_ashrrev_i32_e32 v117, 31, v116
	v_lshlrev_b64 v[218:219], 12, v[116:117]
	v_lshl_add_u64 v[116:117], v[114:115], 0, v[218:219]
	flat_load_dwordx4 v[180:183], v[116:117]
	flat_load_dwordx4 v[176:179], v[116:117] offset:256
	v_or_b32_e32 v116, 32, v112
	v_or_b32_e32 v112, 48, v112
	v_ashrrev_i32_e32 v117, 31, v116
	v_ashrrev_i32_e32 v113, 31, v112
	v_lshlrev_b64 v[216:217], 12, v[116:117]
	v_lshlrev_b64 v[214:215], 12, v[112:113]
	s_mov_b64 s[16:17], 0x80000
	v_lshl_add_u64 v[116:117], v[114:115], 0, v[216:217]
	v_lshl_add_u64 v[112:113], v[114:115], 0, v[214:215]
	v_lshl_add_u64 v[212:213], v[236:237], 0, s[16:17]
	s_mov_b64 s[16:17], 0x90000
	flat_load_dwordx4 v[172:175], v[116:117]
	flat_load_dwordx4 v[168:171], v[116:117] offset:256
	flat_load_dwordx4 v[164:167], v[112:113]
	flat_load_dwordx4 v[160:163], v[112:113] offset:256
	v_lshl_add_u64 v[112:113], v[114:115], 0, v[212:213]
	v_lshl_add_u64 v[210:211], v[236:237], 0, s[16:17]
	s_mov_b64 s[16:17], 0xa0000
	flat_load_dwordx4 v[156:159], v[112:113]
	flat_load_dwordx4 v[144:147], v[112:113] offset:256
	v_lshl_add_u64 v[112:113], v[114:115], 0, v[210:211]
	v_lshl_add_u64 v[208:209], v[236:237], 0, s[16:17]
	s_mov_b64 s[16:17], 0xb0000
	flat_load_dwordx4 v[140:143], v[112:113]
	flat_load_dwordx4 v[136:139], v[112:113] offset:256
	v_lshl_add_u64 v[112:113], v[114:115], 0, v[208:209]
	v_lshl_add_u64 v[206:207], v[236:237], 0, s[16:17]
	flat_load_dwordx4 v[128:131], v[112:113]
	flat_load_dwordx4 v[116:119], v[112:113] offset:256
	v_lshl_add_u64 v[112:113], v[114:115], 0, v[206:207]
	flat_load_dwordx4 v[120:123], v[112:113]
	s_nop 0
	flat_load_dwordx4 v[112:115], v[112:113] offset:256
	v_lshl_add_u64 v[236:237], s[6:7], 0, v[236:237]
	v_lshl_add_u64 v[232:233], v[236:237], 0, v[232:233]
	s_waitcnt vmcnt(0) lgkmcnt(0)
	v_lshlrev_b32_e32 v236, 16, v228
	v_and_b32_e32 v237, 0xffff0000, v228
	v_lshlrev_b32_e32 v228, 16, v229
	v_and_b32_e32 v229, 0xffff0000, v229
	v_pk_add_f32 v[154:155], v[154:155], v[228:229]
	v_lshlrev_b32_e32 v228, 16, v230
	v_and_b32_e32 v229, 0xffff0000, v230
	v_pk_add_f32 v[152:153], v[152:153], v[236:237]
	v_lshlrev_b32_e32 v230, 16, v231
	v_and_b32_e32 v231, 0xffff0000, v231
	v_pk_add_f32 v[228:229], v[148:149], v[228:229]
	v_cvt_pk_bf16_f32 v148, v152, v153
	v_cvt_pk_bf16_f32 v149, v154, v155
	v_pk_add_f32 v[230:231], v[150:151], v[230:231]
	v_cvt_pk_bf16_f32 v150, v228, v229
	s_nop 0
	v_cvt_pk_bf16_f32 v151, v230, v231
	flat_store_dwordx4 v[232:233], v[148:151] sc1
	s_nop 1
	v_mul_f32_e32 v148, v153, v153
	v_mul_f32_e32 v149, v155, v155
	v_fmac_f32_e32 v148, v152, v152
	v_fmac_f32_e32 v149, v154, v154
	v_add_f32_e32 v148, v148, v149
	v_mul_f32_e32 v149, v229, v229
	v_mul_f32_e32 v150, v231, v231
	v_fmac_f32_e32 v149, v228, v228
	v_fmac_f32_e32 v150, v230, v230
	v_add_f32_e32 v149, v149, v150
	v_add_f32_e32 v152, v148, v149
	v_lshlrev_b32_e32 v148, 16, v184
	v_and_b32_e32 v149, 0xffff0000, v184
	v_lshlrev_b32_e32 v150, 16, v185
	v_and_b32_e32 v151, 0xffff0000, v185
	v_pk_add_f32 v[132:133], v[132:133], v[148:149]
	v_lshlrev_b32_e32 v148, 16, v186
	v_and_b32_e32 v149, 0xffff0000, v186
	v_pk_add_f32 v[134:135], v[134:135], v[150:151]
	v_lshlrev_b32_e32 v150, 16, v187
	v_and_b32_e32 v151, 0xffff0000, v187
	v_pk_add_f32 v[148:149], v[124:125], v[148:149]
	v_cvt_pk_bf16_f32 v124, v132, v133
	v_cvt_pk_bf16_f32 v125, v134, v135
	v_pk_add_f32 v[150:151], v[126:127], v[150:151]
	v_cvt_pk_bf16_f32 v126, v148, v149
	s_nop 0
	v_cvt_pk_bf16_f32 v127, v150, v151
	flat_store_dwordx4 v[232:233], v[124:127] offset:256 sc1
	s_nop 1
	v_mul_f32_e32 v124, v133, v133
	v_mul_f32_e32 v125, v135, v135
	v_fmac_f32_e32 v124, v132, v132
	v_fmac_f32_e32 v125, v134, v134
	v_add_f32_e32 v124, v124, v125
	v_mul_f32_e32 v125, v149, v149
	v_mul_f32_e32 v126, v151, v151
	v_fmac_f32_e32 v125, v148, v148
	v_fmac_f32_e32 v126, v150, v150
	v_add_f32_e32 v125, v125, v126
	v_add_f32_e32 v124, v124, v125
	v_add_f32_e32 v124, v152, v124
	ds_bpermute_b32 v125, v222, v124
	s_waitcnt lgkmcnt(0)
	v_add_f32_e32 v124, v124, v125
	ds_bpermute_b32 v125, v223, v124
	s_and_saveexec_b64 s[16:17], s[0:1]
	s_cbranch_execz .LBB0_811
	s_waitcnt lgkmcnt(0)
	v_add_f32_e32 v124, v124, v125
	ds_write_b32 v224, v124

; #define LAS __attribute__((address_space(3)))
;     __device__ __forceinline__ void operator()(const f32x4 (&acc)[2][2][4][2], const CU2& u, int wr, int wc, int fr_, int fq_) const {
;     ...
;         for (int n = 0; n < 2; ++n) {
;             const float* wp = cw + 128 * u.pn + cl + 4 * n; const float* bp = cb + 128 * u.pn + cl + 4 * n;
;             const f32x4 g0 = *(const f32x4*)wp, g1 = *(const f32x4*)(wp + 2 * FF_), g2 = *(const f32x4*)(wp + 4 * FF_), gb = *(const f32x4*)bp;
;             const f32x4 v0 = *(const f32x4*)(wp + FF_), v1 = *(const f32x4*)(wp + 3 * FF_), v2 = *(const f32x4*)(wp + 5 * FF_), vb = *(const f32x4*)(bp + FF_);
;             f32x4 pg2 = acc[1][0][2][n] * rsv[6], pg1 = acc[1][0][3][n] * rsv[7], pv2 = acc[1][1][2][n] * rsv[6], pv1 = acc[1][1][3][n] * rsv[7];
; #pragma unroll
;             for (int e = 0; e < 4; ++e) {
;                 pg2[e] = __int_as_float(__builtin_amdgcn_mov_dpp(__float_as_int(pg2[e]), 0x111, 0xF, 0xF, true)); pg1[e] = __int_as_float(__builtin_amdgcn_mov_dpp(__float_as_int(pg1[e]), 0x111, 0xF, 0xF, true));
;                 pv2[e] = __int_as_float(__builtin_amdgcn_mov_dpp(__float_as_int(pv2[e]), 0x111, 0xF, 0xF, true)); pv1[e] = __int_as_float(__builtin_amdgcn_mov_dpp(__float_as_int(pv1[e]), 0x111, 0xF, 0xF, true));
;             }
;             if (fr == 0 && wr == 1) { pg2 = *(const LAS f32x4*)(hal + cl + 4 * n); pg1 = *(const LAS f32x4*)(hal + 256 + cl + 4 * n); pv2 = *(const LAS f32x4*)(hal + 128 + cl + 4 * n); pv1 = *(const LAS f32x4*)(hal + 384 + cl + 4 * n); }
; #pragma unroll
;             for (int j = 0; j < 8; ++j) {
;                 const f32x4 xg = acc[j >> 2][0][j & 3][n] * rsv[j], xv = acc[j >> 2][1][j & 3][n] * rsv[j];
;                 const f32x4 gc = gb + g2 * xg + g1 * pg1 + g0 * pg2, vc = vb + v2 * xv + v1 * pv1 + v0 * pv2;
;                 f32x4 sg;
; #pragma unroll
;                 for (int e = 0; e < 4; ++e) sg[e] = __builtin_amdgcn_rcpf(1.f + __expf(-gc[e]));
;                 const f32x4 o4 = gc * sg * vc;
;                 pg2 = pg1; pg1 = xg; pv2 = pv1; pv1 = xv;
;                 if (rb + j >= 2 && tb + j < T_) { u32x2 w; w.x = cvt_pk_bf16(o4[0], o4[1]); w.y = cvt_pk_bf16(o4[2], o4[3]); *(u32x2*)(act + (size_t)(tb + j) * FF_ + 128 * u.pn + cl + 4 * n) = w; }
;                 __builtin_amdgcn_sched_barrier(0);
.LBB0_931:
	s_or_b64 exec, exec, s[6:7]
	s_lshl_b64 s[0:1], s[0:1], 1
	s_add_u32 s0, s44, s0
	s_addc_u32 s1, s45, s1
	v_lshl_add_u64 v[50:51], v[226:227], 1, s[0:1]
	v_cmp_lt_i32_e32 vcc, 1, v225
	v_cmp_gt_i32_e64 s[0:1], s89, v200
	v_pk_mul_f32 v[80:81], v[150:151], v[228:229] op_sel_hi:[1,0]
	v_pk_mul_f32 v[68:69], v[148:149], v[228:229] op_sel_hi:[1,0]
	v_pk_mul_f32 v[130:131], v[146:147], v[228:229] op_sel_hi:[1,0]
	v_pk_mul_f32 v[134:135], v[144:145], v[228:229] op_sel_hi:[1,0]
	s_and_b64 s[10:11], vcc, s[0:1]
	s_and_saveexec_b64 s[0:1], s[10:11]
	s_cbranch_execz .LBB0_933
	s_waitcnt lgkmcnt(0)
	v_pk_fma_f32 v[84:85], v[80:81], v[166:167], v[170:171]
	v_pk_fma_f32 v[138:139], v[68:69], v[164:165], v[168:169]
	s_waitcnt lgkmcnt(2)
	v_pk_fma_f32 v[84:85], v[162:163], v[186:187], v[84:85]
	v_pk_fma_f32 v[138:139], v[160:161], v[184:185], v[138:139]
	v_pk_fma_f32 v[84:85], v[154:155], v[194:195], v[84:85]
	v_pk_fma_f32 v[138:139], v[152:153], v[192:193], v[138:139]
	v_mul_f32_e32 v146, 0xbfb8aa3b, v84
	v_mul_f32_e32 v144, 0xbfb8aa3b, v138
	v_mul_f32_e32 v145, 0xbfb8aa3b, v139
	v_mul_f32_e32 v147, 0xbfb8aa3b, v85
	v_exp_f32_e32 v144, v144
	v_exp_f32_e32 v145, v145
	v_exp_f32_e32 v146, v146
	v_exp_f32_e32 v147, v147
	v_add_f32_e32 v144, 1.0, v144
	v_add_f32_e32 v145, 1.0, v145
	v_add_f32_e32 v146, 1.0, v146
	v_add_f32_e32 v147, 1.0, v147
	v_rcp_f32_e32 v144, v144
	v_rcp_f32_e32 v145, v145
	v_rcp_f32_e32 v146, v146
	v_rcp_f32_e32 v147, v147
	s_waitcnt lgkmcnt(0)
	v_pk_fma_f32 v[72:73], v[130:131], v[178:179], v[182:183]
	v_pk_fma_f32 v[76:77], v[134:135], v[176:177], v[180:181]
	s_waitcnt lgkmcnt(0)
	v_pk_fma_f32 v[72:73], v[174:175], v[190:191], v[72:73]
	v_pk_fma_f32 v[76:77], v[172:173], v[188:189], v[76:77]
	v_pk_fma_f32 v[72:73], v[158:159], v[198:199], v[72:73]
	v_pk_fma_f32 v[76:77], v[156:157], v[196:197], v[76:77]
	v_pk_mul_f32 v[84:85], v[84:85], v[146:147]
	v_pk_mul_f32 v[138:139], v[138:139], v[144:145]
	v_pk_mul_f32 v[72:73], v[72:73], v[84:85]
	v_pk_mul_f32 v[76:77], v[76:77], v[138:139]
	s_nop 0
	v_cvt_pk_bf16_f32 v76, v76, v77
	v_cvt_pk_bf16_f32 v77, v72, v73
	v_mad_i64_i32 v[72:73], s[6:7], v200, s37, v[50:51]
	global_store_dwordx2 v[72:73], v[76:77], off sc1
.LBB0_933:
	s_or_b64 exec, exec, s[0:1]
	s_movk_i32 s0, 0x1fff
	v_cmp_lt_i32_e32 vcc, 0, v225
	v_cmp_gt_i32_e64 s[0:1], s0, v200
	v_pk_mul_f32 v[126:127], v[126:127], v[224:225] op_sel_hi:[1,0]
	v_pk_mul_f32 v[76:77], v[124:125], v[224:225] op_sel_hi:[1,0]
	v_pk_mul_f32 v[122:123], v[122:123], v[224:225] op_sel_hi:[1,0]
	v_pk_mul_f32 v[120:121], v[120:121], v[224:225] op_sel_hi:[1,0]
	s_and_b64 s[6:7], vcc, s[0:1]
	s_and_saveexec_b64 s[0:1], s[6:7]
	s_cbranch_execz .LBB0_935
	v_pk_fma_f32 v[124:125], v[126:127], v[166:167], v[170:171]
	v_pk_fma_f32 v[138:139], v[76:77], v[164:165], v[168:169]
	v_pk_fma_f32 v[124:125], v[80:81], v[162:163], v[124:125]
	v_pk_fma_f32 v[138:139], v[68:69], v[160:161], v[138:139]
	s_waitcnt lgkmcnt(0)
	v_pk_fma_f32 v[124:125], v[154:155], v[186:187], v[124:125]
	v_pk_fma_f32 v[138:139], v[152:153], v[184:185], v[138:139]
	v_mul_f32_e32 v146, 0xbfb8aa3b, v124
	v_mul_f32_e32 v144, 0xbfb8aa3b, v138
	v_mul_f32_e32 v145, 0xbfb8aa3b, v139
	v_mul_f32_e32 v147, 0xbfb8aa3b, v125
	v_exp_f32_e32 v144, v144
	v_exp_f32_e32 v145, v145
	v_exp_f32_e32 v146, v146
	v_exp_f32_e32 v147, v147
	v_add_f32_e32 v144, 1.0, v144
	v_add_f32_e32 v145, 1.0, v145
	v_add_f32_e32 v146, 1.0, v146
	v_add_f32_e32 v147, 1.0, v147
	v_rcp_f32_e32 v144, v144
	v_rcp_f32_e32 v145, v145
	v_rcp_f32_e32 v146, v146
	v_rcp_f32_e32 v147, v147
	v_pk_fma_f32 v[72:73], v[122:123], v[178:179], v[182:183]
	v_pk_fma_f32 v[84:85], v[120:121], v[176:177], v[180:181]
	v_pk_fma_f32 v[72:73], v[130:131], v[174:175], v[72:73]
	v_pk_fma_f32 v[84:85], v[134:135], v[172:173], v[84:85]
	v_pk_fma_f32 v[72:73], v[158:159], v[190:191], v[72:73]
	v_pk_fma_f32 v[84:85], v[156:157], v[188:189], v[84:85]
	v_pk_mul_f32 v[124:125], v[124:125], v[146:147]
	v_pk_mul_f32 v[138:139], v[138:139], v[144:145]
	v_pk_mul_f32 v[72:73], v[72:73], v[124:125]
	v_pk_mul_f32 v[84:85], v[84:85], v[138:139]
	s_nop 0
	v_cvt_pk_bf16_f32 v84, v84, v85
	v_cvt_pk_bf16_f32 v85, v72, v73
	v_mad_i64_i32 v[72:73], s[8:9], v223, s37, v[50:51]
	global_store_dwordx2 v[72:73], v[84:85], off sc1
.LBB0_935:
	s_or_b64 exec, exec, s[0:1]
	v_cmp_lt_i32_e32 vcc, -1, v225
	v_cmp_gt_i32_e64 s[0:1], s89, v221
	v_pk_mul_f32 v[84:85], v[118:119], v[222:223] op_sel_hi:[1,0]
	v_pk_mul_f32 v[72:73], v[116:117], v[222:223] op_sel_hi:[1,0]
	v_pk_mul_f32 v[114:115], v[114:115], v[222:223] op_sel_hi:[1,0]
	v_pk_mul_f32 v[112:113], v[112:113], v[222:223] op_sel_hi:[1,0]
	s_and_b64 s[8:9], vcc, s[0:1]
	s_and_saveexec_b64 s[0:1], s[8:9]
	s_cbranch_execz .LBB0_937
	v_pk_fma_f32 v[116:117], v[114:115], v[178:179], v[182:183]
	v_pk_fma_f32 v[124:125], v[84:85], v[166:167], v[170:171]
	v_pk_fma_f32 v[116:117], v[122:123], v[174:175], v[116:117]
	v_pk_fma_f32 v[124:125], v[126:127], v[162:163], v[124:125]
	v_pk_fma_f32 v[116:117], v[130:131], v[158:159], v[116:117]
	v_pk_fma_f32 v[130:131], v[72:73], v[164:165], v[168:169]
	v_pk_fma_f32 v[80:81], v[80:81], v[154:155], v[124:125]
	v_pk_fma_f32 v[130:131], v[76:77], v[160:161], v[130:131]
	v_pk_fma_f32 v[118:119], v[112:113], v[176:177], v[180:181]
	v_pk_fma_f32 v[68:69], v[68:69], v[152:153], v[130:131]
	v_mul_f32_e32 v130, 0xbfb8aa3b, v80
	v_mul_f32_e32 v124, 0xbfb8aa3b, v68
	v_mul_f32_e32 v125, 0xbfb8aa3b, v69
	v_mul_f32_e32 v131, 0xbfb8aa3b, v81
	v_exp_f32_e32 v124, v124
	v_exp_f32_e32 v125, v125
	v_exp_f32_e32 v130, v130
	v_exp_f32_e32 v131, v131
	v_add_f32_e32 v124, 1.0, v124
	v_add_f32_e32 v125, 1.0, v125
	v_add_f32_e32 v130, 1.0, v130
	v_add_f32_e32 v131, 1.0, v131
	v_rcp_f32_e32 v124, v124
	v_rcp_f32_e32 v125, v125
	v_rcp_f32_e32 v130, v130
	v_rcp_f32_e32 v131, v131
	v_pk_fma_f32 v[118:119], v[120:121], v[172:173], v[118:119]
	v_pk_mul_f32 v[68:69], v[68:69], v[124:125]
	v_pk_fma_f32 v[118:119], v[134:135], v[156:157], v[118:119]
	v_pk_mul_f32 v[80:81], v[80:81], v[130:131]
	v_pk_mul_f32 v[68:69], v[118:119], v[68:69]
	v_pk_mul_f32 v[80:81], v[116:117], v[80:81]
	v_cvt_pk_bf16_f32 v68, v68, v69
	s_nop 0
	v_cvt_pk_bf16_f32 v69, v80, v81
	v_mad_i64_i32 v[80:81], s[12:13], v221, s37, v[50:51]
	global_store_dwordx2 v[80:81], v[68:69], off sc1
; __device__ __forceinline__ unsigned cvt_pk_bf16(float lo, float hi) { unsigned r; asm("v_cvt_pk_bf16_f32 %0, %1, %2" : "=v"(r) : "v"(lo), "v"(hi)); return r; }
;     __device__ __forceinline__ void operator()(const f32x4 (&acc)[2][2][4][2], const CU2& u, int wr, int wc, int fr_, int fq_) const {
;     ...
;             for (int j = 0; j < 8; ++j) {
;                 const f32x4 xg = acc[j >> 2][0][j & 3][n] * rsv[j], xv = acc[j >> 2][1][j & 3][n] * rsv[j];
;                 const f32x4 gc = gb + g2 * xg + g1 * pg1 + g0 * pg2, vc = vb + v2 * xv + v1 * pv1 + v0 * pv2;
;                 f32x4 sg;
; #pragma unroll
;                 for (int e = 0; e < 4; ++e) sg[e] = __builtin_amdgcn_rcpf(1.f + __expf(-gc[e]));
;                 const f32x4 o4 = gc * sg * vc;
;                 pg2 = pg1; pg1 = xg; pv2 = pv1; pv1 = xv;
;                 if (rb + j >= 2 && tb + j < T_) { u32x2 w; w.x = cvt_pk_bf16(o4[0], o4[1]); w.y = cvt_pk_bf16(o4[2], o4[3]); *(u32x2*)(act + (size_t)(tb + j) * FF_ + 128 * u.pn + cl + 4 * n) = w; }
.LBB0_937:
	s_or_b64 exec, exec, s[0:1]
	s_movk_i32 s0, 0x1ffd
	v_cmp_lt_i32_e32 vcc, -2, v225
	v_cmp_gt_i32_e64 s[0:1], s0, v200
	v_pk_mul_f32 v[80:81], v[110:111], v[220:221] op_sel_hi:[1,0]
	v_pk_mul_f32 v[68:69], v[108:109], v[220:221] op_sel_hi:[1,0]
	v_pk_mul_f32 v[106:107], v[106:107], v[220:221] op_sel_hi:[1,0]
	v_pk_mul_f32 v[104:105], v[104:105], v[220:221] op_sel_hi:[1,0]
	s_and_b64 s[12:13], vcc, s[0:1]
	s_and_saveexec_b64 s[0:1], s[12:13]
	s_cbranch_execz .LBB0_939
	v_pk_fma_f32 v[116:117], v[80:81], v[166:167], v[170:171]
	v_pk_fma_f32 v[118:119], v[68:69], v[164:165], v[168:169]
	v_pk_fma_f32 v[110:111], v[104:105], v[176:177], v[180:181]
	v_pk_fma_f32 v[116:117], v[84:85], v[162:163], v[116:117]
	v_pk_fma_f32 v[118:119], v[72:73], v[160:161], v[118:119]
	v_pk_fma_f32 v[110:111], v[112:113], v[172:173], v[110:111]
	v_pk_fma_f32 v[116:117], v[126:127], v[154:155], v[116:117]
	v_pk_fma_f32 v[76:77], v[76:77], v[152:153], v[118:119]
	v_pk_fma_f32 v[110:111], v[120:121], v[156:157], v[110:111]
	v_mul_f32_e32 v118, 0xbfb8aa3b, v76
	v_mul_f32_e32 v119, 0xbfb8aa3b, v77
	v_mul_f32_e32 v120, 0xbfb8aa3b, v116
	v_mul_f32_e32 v121, 0xbfb8aa3b, v117
	v_exp_f32_e32 v118, v118
	v_exp_f32_e32 v119, v119
	v_exp_f32_e32 v120, v120
	v_exp_f32_e32 v121, v121
	v_add_f32_e32 v118, 1.0, v118
	v_add_f32_e32 v119, 1.0, v119
	v_add_f32_e32 v120, 1.0, v120
	v_add_f32_e32 v121, 1.0, v121
	v_rcp_f32_e32 v118, v118
	v_rcp_f32_e32 v119, v119
	v_rcp_f32_e32 v120, v120
	v_rcp_f32_e32 v121, v121
	v_pk_fma_f32 v[108:109], v[106:107], v[178:179], v[182:183]
	v_pk_mul_f32 v[76:77], v[76:77], v[118:119]
	v_pk_fma_f32 v[108:109], v[114:115], v[174:175], v[108:109]
	v_pk_mul_f32 v[116:117], v[116:117], v[120:121]
	v_pk_fma_f32 v[108:109], v[122:123], v[158:159], v[108:109]
	v_pk_mul_f32 v[76:77], v[110:111], v[76:77]
	v_pk_mul_f32 v[108:109], v[108:109], v[116:117]
	v_cvt_pk_bf16_f32 v76, v76, v77
	s_nop 0
	v_cvt_pk_bf16_f32 v77, v108, v109
	v_mad_i64_i32 v[108:109], s[14:15], v219, s37, v[50:51]
	global_store_dwordx2 v[108:109], v[76:77], off sc1
.LBB0_939:
	s_or_b64 exec, exec, s[0:1]
	s_movk_i32 s0, 0x1ffc
	v_cmp_lt_i32_e32 vcc, -3, v225
	v_cmp_gt_i32_e64 s[0:1], s0, v200
	v_pk_mul_f32 v[102:103], v[102:103], v[218:219] op_sel_hi:[1,0]
	v_pk_mul_f32 v[76:77], v[100:101], v[218:219] op_sel_hi:[1,0]
	v_pk_mul_f32 v[98:99], v[98:99], v[218:219] op_sel_hi:[1,0]
	v_pk_mul_f32 v[96:97], v[96:97], v[218:219] op_sel_hi:[1,0]
	s_and_b64 s[14:15], vcc, s[0:1]
	s_and_saveexec_b64 s[0:1], s[14:15]
	s_cbranch_execz .LBB0_941
	v_pk_fma_f32 v[108:109], v[96:97], v[176:177], v[180:181]
	v_pk_fma_f32 v[110:111], v[102:103], v[166:167], v[170:171]
	v_pk_fma_f32 v[108:109], v[104:105], v[172:173], v[108:109]
	v_pk_fma_f32 v[110:111], v[80:81], v[162:163], v[110:111]
	v_pk_fma_f32 v[108:109], v[112:113], v[156:157], v[108:109]
	v_pk_fma_f32 v[112:113], v[76:77], v[164:165], v[168:169]
	v_pk_fma_f32 v[84:85], v[84:85], v[154:155], v[110:111]
	v_pk_fma_f32 v[112:113], v[68:69], v[160:161], v[112:113]
	v_pk_fma_f32 v[100:101], v[98:99], v[178:179], v[182:183]
	v_pk_fma_f32 v[72:73], v[72:73], v[152:153], v[112:113]
	v_mul_f32_e32 v112, 0xbfb8aa3b, v84
	v_mul_f32_e32 v110, 0xbfb8aa3b, v72
	v_mul_f32_e32 v111, 0xbfb8aa3b, v73
	v_mul_f32_e32 v113, 0xbfb8aa3b, v85
	v_exp_f32_e32 v110, v110
	v_exp_f32_e32 v111, v111
	v_exp_f32_e32 v112, v112
	v_exp_f32_e32 v113, v113
	v_add_f32_e32 v110, 1.0, v110
	v_add_f32_e32 v111, 1.0, v111
	v_add_f32_e32 v112, 1.0, v112
	v_add_f32_e32 v113, 1.0, v113
	v_rcp_f32_e32 v110, v110
	v_rcp_f32_e32 v111, v111
	v_rcp_f32_e32 v112, v112
	v_rcp_f32_e32 v113, v113
	v_pk_fma_f32 v[100:101], v[106:107], v[174:175], v[100:101]
	v_pk_mul_f32 v[72:73], v[72:73], v[110:111]
	v_pk_fma_f32 v[100:101], v[114:115], v[158:159], v[100:101]
	v_pk_mul_f32 v[84:85], v[84:85], v[112:113]
	v_pk_mul_f32 v[72:73], v[108:109], v[72:73]
	v_pk_mul_f32 v[84:85], v[100:101], v[84:85]
	v_cvt_pk_bf16_f32 v72, v72, v73
	s_nop 0
	v_cvt_pk_bf16_f32 v73, v84, v85
	v_mad_i64_i32 v[84:85], s[26:27], v217, s37, v[50:51]
	global_store_dwordx2 v[84:85], v[72:73], off sc1
; __device__ __forceinline__ unsigned cvt_pk_bf16(float lo, float hi) { unsigned r; asm("v_cvt_pk_bf16_f32 %0, %1, %2" : "=v"(r) : "v"(lo), "v"(hi)); return r; }
;     __device__ __forceinline__ void operator()(const f32x4 (&acc)[2][2][4][2], const CU2& u, int wr, int wc, int fr_, int fq_) const {
;     ...
;             for (int j = 0; j < 8; ++j) {
;                 const f32x4 xg = acc[j >> 2][0][j & 3][n] * rsv[j], xv = acc[j >> 2][1][j & 3][n] * rsv[j];
;                 const f32x4 gc = gb + g2 * xg + g1 * pg1 + g0 * pg2, vc = vb + v2 * xv + v1 * pv1 + v0 * pv2;
;                 f32x4 sg;
; #pragma unroll
;                 for (int e = 0; e < 4; ++e) sg[e] = __builtin_amdgcn_rcpf(1.f + __expf(-gc[e]));
;                 const f32x4 o4 = gc * sg * vc;
;                 pg2 = pg1; pg1 = xg; pv2 = pv1; pv1 = xv;
;                 if (rb + j >= 2 && tb + j < T_) { u32x2 w; w.x = cvt_pk_bf16(o4[0], o4[1]); w.y = cvt_pk_bf16(o4[2], o4[3]); *(u32x2*)(act + (size_t)(tb + j) * FF_ + 128 * u.pn + cl + 4 * n) = w; }
.LBB0_941:
	s_or_b64 exec, exec, s[0:1]
	s_movk_i32 s0, 0x1ffb
	v_cmp_lt_i32_e32 vcc, -4, v225
	v_cmp_gt_i32_e64 s[0:1], s0, v200
	v_pk_mul_f32 v[94:95], v[94:95], v[216:217] op_sel_hi:[1,0]
	v_pk_mul_f32 v[92:93], v[92:93], v[216:217] op_sel_hi:[1,0]
	v_pk_mul_f32 v[72:73], v[90:91], v[216:217] op_sel_hi:[1,0]
	v_pk_mul_f32 v[84:85], v[88:89], v[216:217] op_sel_hi:[1,0]
	s_and_b64 s[26:27], vcc, s[0:1]
	s_and_saveexec_b64 s[0:1], s[26:27]
	s_cbranch_execz .LBB0_943
	v_pk_fma_f32 v[90:91], v[84:85], v[176:177], v[180:181]
	v_pk_fma_f32 v[100:101], v[94:95], v[166:167], v[170:171]
	v_pk_fma_f32 v[90:91], v[96:97], v[172:173], v[90:91]
	v_pk_fma_f32 v[100:101], v[102:103], v[162:163], v[100:101]
	v_pk_fma_f32 v[90:91], v[104:105], v[156:157], v[90:91]
	v_pk_fma_f32 v[104:105], v[92:93], v[164:165], v[168:169]
	v_pk_fma_f32 v[80:81], v[80:81], v[154:155], v[100:101]
	v_pk_fma_f32 v[104:105], v[76:77], v[160:161], v[104:105]
	v_pk_fma_f32 v[88:89], v[72:73], v[178:179], v[182:183]
	v_pk_fma_f32 v[68:69], v[68:69], v[152:153], v[104:105]
	v_mul_f32_e32 v104, 0xbfb8aa3b, v80
	v_mul_f32_e32 v100, 0xbfb8aa3b, v68
	v_mul_f32_e32 v101, 0xbfb8aa3b, v69
	v_mul_f32_e32 v105, 0xbfb8aa3b, v81
	v_exp_f32_e32 v100, v100
	v_exp_f32_e32 v101, v101
	v_exp_f32_e32 v104, v104
	v_exp_f32_e32 v105, v105
	v_add_f32_e32 v100, 1.0, v100
	v_add_f32_e32 v101, 1.0, v101
	v_add_f32_e32 v104, 1.0, v104
	v_add_f32_e32 v105, 1.0, v105
	v_rcp_f32_e32 v100, v100
	v_rcp_f32_e32 v101, v101
	v_rcp_f32_e32 v104, v104
	v_rcp_f32_e32 v105, v105
	v_pk_fma_f32 v[88:89], v[98:99], v[174:175], v[88:89]
	v_pk_mul_f32 v[68:69], v[68:69], v[100:101]
	v_pk_fma_f32 v[88:89], v[106:107], v[158:159], v[88:89]
	v_pk_mul_f32 v[80:81], v[80:81], v[104:105]
	v_pk_mul_f32 v[68:69], v[90:91], v[68:69]
	v_pk_mul_f32 v[80:81], v[88:89], v[80:81]
	v_cvt_pk_bf16_f32 v68, v68, v69
	s_nop 0
	v_cvt_pk_bf16_f32 v69, v80, v81
	v_mad_i64_i32 v[80:81], s[28:29], v246, s37, v[50:51]
	global_store_dwordx2 v[80:81], v[68:69], off sc1
.LBB0_943:
	s_or_b64 exec, exec, s[0:1]
	s_movk_i32 s0, 0x1ffa
	v_mov_b32_e32 v233, v232
	v_cmp_lt_i32_e32 vcc, -5, v225
	v_cmp_gt_i32_e64 s[0:1], s0, v200
	v_pk_mul_f32 v[68:69], v[86:87], v[232:233]
	s_and_b64 s[28:29], vcc, s[0:1]
	s_and_saveexec_b64 s[0:1], s[28:29]
	s_cbranch_execz .LBB0_945
	v_pk_fma_f32 v[88:89], v[142:143], v[166:167], v[170:171]
	v_pk_fma_f32 v[90:91], v[140:141], v[164:165], v[168:169]
	v_pk_fma_f32 v[86:87], v[132:133], v[176:177], v[180:181]
	v_pk_fma_f32 v[88:89], v[94:95], v[162:163], v[88:89]
	v_pk_fma_f32 v[90:91], v[92:93], v[160:161], v[90:91]
	v_pk_fma_f32 v[86:87], v[84:85], v[172:173], v[86:87]
	v_pk_fma_f32 v[88:89], v[102:103], v[154:155], v[88:89]
	v_pk_fma_f32 v[76:77], v[76:77], v[152:153], v[90:91]
	v_pk_fma_f32 v[86:87], v[96:97], v[156:157], v[86:87]
	v_mul_f32_e32 v90, 0xbfb8aa3b, v76
	v_mul_f32_e32 v91, 0xbfb8aa3b, v77
	v_mul_f32_e32 v96, 0xbfb8aa3b, v88
	v_mul_f32_e32 v97, 0xbfb8aa3b, v89
	v_exp_f32_e32 v90, v90
	v_exp_f32_e32 v91, v91
	v_exp_f32_e32 v96, v96
	v_exp_f32_e32 v97, v97
	v_add_f32_e32 v90, 1.0, v90
	v_add_f32_e32 v91, 1.0, v91
	v_add_f32_e32 v96, 1.0, v96
	v_add_f32_e32 v97, 1.0, v97
	v_rcp_f32_e32 v90, v90
	v_rcp_f32_e32 v91, v91
	v_rcp_f32_e32 v96, v96
	v_rcp_f32_e32 v97, v97
	v_pk_fma_f32 v[80:81], v[68:69], v[178:179], v[182:183]
	v_pk_mul_f32 v[76:77], v[76:77], v[90:91]
	v_pk_fma_f32 v[80:81], v[72:73], v[174:175], v[80:81]
	v_pk_mul_f32 v[88:89], v[88:89], v[96:97]
	v_pk_fma_f32 v[80:81], v[98:99], v[158:159], v[80:81]
	v_pk_mul_f32 v[76:77], v[86:87], v[76:77]
	v_pk_mul_f32 v[80:81], v[80:81], v[88:89]
	v_cvt_pk_bf16_f32 v76, v76, v77
	s_nop 0
	v_cvt_pk_bf16_f32 v77, v80, v81
	v_mad_i64_i32 v[80:81], s[30:31], v245, s37, v[50:51]
	global_store_dwordx2 v[80:81], v[76:77], off sc1
.LBB0_945:
	s_or_b64 exec, exec, s[0:1]
	s_movk_i32 s0, 0x1ff9
	v_cmp_lt_i32_e32 vcc, -6, v225
	v_cmp_gt_i32_e64 s[0:1], s0, v200
	s_and_b64 s[0:1], vcc, s[0:1]
	s_and_saveexec_b64 s[30:31], s[0:1]
	s_cbranch_execz .LBB0_947
	v_mov_b32_e32 v231, v230
	v_pk_mul_f32 v[76:77], v[78:79], v[230:231]
	v_pk_fma_f32 v[78:79], v[136:137], v[176:177], v[180:181]
	v_pk_fma_f32 v[76:77], v[76:77], v[178:179], v[182:183]
	v_pk_fma_f32 v[80:81], v[128:129], v[164:165], v[168:169]
	v_pk_fma_f32 v[68:69], v[68:69], v[174:175], v[76:77]
	v_pk_fma_f32 v[76:77], v[132:133], v[172:173], v[78:79]
	v_pk_mul_f32 v[78:79], v[82:83], v[230:231]
	v_pk_fma_f32 v[80:81], v[140:141], v[160:161], v[80:81]
	v_pk_fma_f32 v[78:79], v[78:79], v[166:167], v[170:171]
	v_pk_fma_f32 v[80:81], v[92:93], v[152:153], v[80:81]
	v_pk_fma_f32 v[78:79], v[142:143], v[162:163], v[78:79]
	v_mul_f32_e32 v82, 0xbfb8aa3b, v80
	v_pk_fma_f32 v[78:79], v[94:95], v[154:155], v[78:79]
	v_mul_f32_e32 v83, 0xbfb8aa3b, v81
	v_mul_f32_e32 v86, 0xbfb8aa3b, v78
	v_mul_f32_e32 v87, 0xbfb8aa3b, v79
	v_exp_f32_e32 v82, v82
	v_exp_f32_e32 v83, v83
	v_exp_f32_e32 v86, v86
	v_exp_f32_e32 v87, v87
	v_add_f32_e32 v82, 1.0, v82
	v_add_f32_e32 v83, 1.0, v83
	v_add_f32_e32 v86, 1.0, v86
	v_add_f32_e32 v87, 1.0, v87
	v_rcp_f32_e32 v82, v82
	v_rcp_f32_e32 v86, v86
	v_rcp_f32_e32 v87, v87
	v_rcp_f32_e32 v83, v83
	v_pk_fma_f32 v[68:69], v[72:73], v[158:159], v[68:69]
	v_pk_fma_f32 v[72:73], v[84:85], v[156:157], v[76:77]
	v_pk_mul_f32 v[76:77], v[78:79], v[86:87]
	v_pk_mul_f32 v[78:79], v[80:81], v[82:83]
	v_pk_mul_f32 v[68:69], v[68:69], v[76:77]
	v_pk_mul_f32 v[72:73], v[72:73], v[78:79]
	s_nop 0
	v_cvt_pk_bf16_f32 v72, v72, v73
	v_cvt_pk_bf16_f32 v73, v68, v69
	v_mad_i64_i32 v[68:69], vcc, v244, s37, v[50:51]
	global_store_dwordx2 v[68:69], v[72:73], off sc1

; #define LAS __attribute__((address_space(3)))
;     __device__ __forceinline__ void operator()(const f32x4 (&acc)[2][2][4][2], const CU2& u, int wr, int wc, int fr_, int fq_) const {
;     ...
;         for (int n = 0; n < 2; ++n) {
;             const float* wp = cw + 128 * u.pn + cl + 4 * n; const float* bp = cb + 128 * u.pn + cl + 4 * n;
;             const f32x4 g0 = *(const f32x4*)wp, g1 = *(const f32x4*)(wp + 2 * FF_), g2 = *(const f32x4*)(wp + 4 * FF_), gb = *(const f32x4*)bp;
;             const f32x4 v0 = *(const f32x4*)(wp + FF_), v1 = *(const f32x4*)(wp + 3 * FF_), v2 = *(const f32x4*)(wp + 5 * FF_), vb = *(const f32x4*)(bp + FF_);
;             f32x4 pg2 = acc[1][0][2][n] * rsv[6], pg1 = acc[1][0][3][n] * rsv[7], pv2 = acc[1][1][2][n] * rsv[6], pv1 = acc[1][1][3][n] * rsv[7];
; #pragma unroll
;             for (int e = 0; e < 4; ++e) {
;                 pg2[e] = __int_as_float(__builtin_amdgcn_mov_dpp(__float_as_int(pg2[e]), 0x111, 0xF, 0xF, true)); pg1[e] = __int_as_float(__builtin_amdgcn_mov_dpp(__float_as_int(pg1[e]), 0x111, 0xF, 0xF, true));
;                 pv2[e] = __int_as_float(__builtin_amdgcn_mov_dpp(__float_as_int(pv2[e]), 0x111, 0xF, 0xF, true)); pv1[e] = __int_as_float(__builtin_amdgcn_mov_dpp(__float_as_int(pv1[e]), 0x111, 0xF, 0xF, true));
;             }
;             if (fr == 0 && wr == 1) { pg2 = *(const LAS f32x4*)(hal + cl + 4 * n); pg1 = *(const LAS f32x4*)(hal + 256 + cl + 4 * n); pv2 = *(const LAS f32x4*)(hal + 128 + cl + 4 * n); pv1 = *(const LAS f32x4*)(hal + 384 + cl + 4 * n); }
; #pragma unroll
;             for (int j = 0; j < 8; ++j) {
;                 const f32x4 xg = acc[j >> 2][0][j & 3][n] * rsv[j], xv = acc[j >> 2][1][j & 3][n] * rsv[j];
;                 const f32x4 gc = gb + g2 * xg + g1 * pg1 + g0 * pg2, vc = vb + v2 * xv + v1 * pv1 + v0 * pv2;
;                 f32x4 sg;
; #pragma unroll
;                 for (int e = 0; e < 4; ++e) sg[e] = __builtin_amdgcn_rcpf(1.f + __expf(-gc[e]));
;                 const f32x4 o4 = gc * sg * vc;
;                 pg2 = pg1; pg1 = xg; pv2 = pv1; pv1 = xv;
;                 if (rb + j >= 2 && tb + j < T_) { u32x2 w; w.x = cvt_pk_bf16(o4[0], o4[1]); w.y = cvt_pk_bf16(o4[2], o4[3]); *(u32x2*)(act + (size_t)(tb + j) * FF_ + 128 * u.pn + cl + 4 * n) = w; }
.LBB0_949:
	s_or_b64 exec, exec, s[30:31]
	v_mov_b32_e32 v229, v228
	v_mov_b32_e32 v114, v228
	v_mov_b32_e32 v115, v228
	v_pk_mul_f32 v[60:61], v[60:61], v[114:115]
	v_pk_mul_f32 v[58:59], v[58:59], v[228:229]
	v_pk_mul_f32 v[42:43], v[42:43], v[114:115]
	v_pk_mul_f32 v[40:41], v[40:41], v[228:229]
	s_and_saveexec_b64 s[4:5], s[10:11]
	s_cbranch_execz .LBB0_951
	s_waitcnt lgkmcnt(0)
	v_pk_fma_f32 v[114:115], v[42:43], v[102:103], v[106:107]
	v_pk_fma_f32 v[116:117], v[40:41], v[100:101], v[104:105]
	s_waitcnt lgkmcnt(0)
	v_pk_fma_f32 v[114:115], v[98:99], v[56:57], v[114:115]
	v_pk_fma_f32 v[116:117], v[96:97], v[54:55], v[116:117]
	v_pk_fma_f32 v[74:75], v[82:83], v[74:75], v[114:115]
	v_pk_fma_f32 v[72:73], v[80:81], v[72:73], v[116:117]
	v_pk_fma_f32 v[114:115], v[60:61], v[90:91], v[94:95]
	v_pk_fma_f32 v[116:117], v[58:59], v[88:89], v[92:93]
	v_pk_fma_f32 v[114:115], v[86:87], v[46:47], v[114:115]
	v_pk_fma_f32 v[116:117], v[84:85], v[44:45], v[116:117]
	v_pk_fma_f32 v[70:71], v[78:79], v[70:71], v[114:115]
	v_pk_fma_f32 v[68:69], v[76:77], v[68:69], v[116:117]
	v_mul_f32_e32 v116, 0xbfb8aa3b, v70
	v_mul_f32_e32 v114, 0xbfb8aa3b, v68
	v_mul_f32_e32 v115, 0xbfb8aa3b, v69
	v_mul_f32_e32 v117, 0xbfb8aa3b, v71
	v_exp_f32_e32 v114, v114
	v_exp_f32_e32 v115, v115
	v_exp_f32_e32 v116, v116
	v_exp_f32_e32 v117, v117
	v_add_f32_e32 v114, 1.0, v114
	v_add_f32_e32 v115, 1.0, v115
	v_add_f32_e32 v116, 1.0, v116
	v_add_f32_e32 v117, 1.0, v117
	v_rcp_f32_e32 v114, v114
	v_rcp_f32_e32 v115, v115
	v_rcp_f32_e32 v116, v116
	v_rcp_f32_e32 v117, v117
	v_pk_mul_f32 v[68:69], v[68:69], v[114:115]
	s_nop 0
	v_pk_mul_f32 v[68:69], v[72:73], v[68:69]
	v_pk_mul_f32 v[70:71], v[70:71], v[116:117]
	v_cvt_pk_bf16_f32 v68, v68, v69
	s_nop 0
	v_pk_mul_f32 v[70:71], v[74:75], v[70:71]
	s_nop 0
	v_cvt_pk_bf16_f32 v69, v70, v71
	v_mad_i64_i32 v[70:71], s[10:11], v200, s37, v[50:51]
	global_store_dwordx2 v[70:71], v[68:69], off offset:8 sc1
.LBB0_951:
	s_or_b64 exec, exec, s[4:5]
	v_mov_b32_e32 v225, v224
	s_waitcnt lgkmcnt(0)
	v_mov_b32_e32 v68, v224
	v_mov_b32_e32 v69, v224
	v_pk_mul_f32 v[38:39], v[38:39], v[68:69]
	v_pk_mul_f32 v[36:37], v[36:37], v[224:225]
	v_pk_mul_f32 v[34:35], v[34:35], v[68:69]
	v_pk_mul_f32 v[32:33], v[32:33], v[224:225]
	s_and_saveexec_b64 s[4:5], s[6:7]
	s_cbranch_execz .LBB0_953
	v_pk_fma_f32 v[68:69], v[34:35], v[102:103], v[106:107]
	v_pk_fma_f32 v[70:71], v[32:33], v[100:101], v[104:105]
	v_pk_fma_f32 v[68:69], v[42:43], v[98:99], v[68:69]
	v_pk_fma_f32 v[70:71], v[40:41], v[96:97], v[70:71]
	v_pk_fma_f32 v[56:57], v[82:83], v[56:57], v[68:69]
	v_pk_fma_f32 v[54:55], v[80:81], v[54:55], v[70:71]
	v_pk_fma_f32 v[68:69], v[38:39], v[90:91], v[94:95]
	v_pk_fma_f32 v[70:71], v[36:37], v[88:89], v[92:93]
	v_pk_fma_f32 v[68:69], v[60:61], v[86:87], v[68:69]
	v_pk_fma_f32 v[70:71], v[58:59], v[84:85], v[70:71]
	v_pk_fma_f32 v[46:47], v[78:79], v[46:47], v[68:69]
	v_pk_fma_f32 v[44:45], v[76:77], v[44:45], v[70:71]
	v_mul_f32_e32 v70, 0xbfb8aa3b, v46
	v_mul_f32_e32 v68, 0xbfb8aa3b, v44
	v_mul_f32_e32 v69, 0xbfb8aa3b, v45
	v_mul_f32_e32 v71, 0xbfb8aa3b, v47
	v_exp_f32_e32 v68, v68
	v_exp_f32_e32 v69, v69
	v_exp_f32_e32 v70, v70
	v_exp_f32_e32 v71, v71
	v_add_f32_e32 v68, 1.0, v68
	v_add_f32_e32 v69, 1.0, v69
	v_add_f32_e32 v70, 1.0, v70
	v_add_f32_e32 v71, 1.0, v71
	v_rcp_f32_e32 v68, v68
	v_rcp_f32_e32 v69, v69
	v_rcp_f32_e32 v70, v70
	v_rcp_f32_e32 v71, v71
	v_pk_mul_f32 v[44:45], v[44:45], v[68:69]
	s_nop 0
	v_pk_mul_f32 v[44:45], v[54:55], v[44:45]
	v_pk_mul_f32 v[46:47], v[46:47], v[70:71]
	v_cvt_pk_bf16_f32 v44, v44, v45
	s_nop 0
	v_pk_mul_f32 v[46:47], v[56:57], v[46:47]
	s_nop 0
	v_cvt_pk_bf16_f32 v45, v46, v47
	v_mad_i64_i32 v[46:47], s[6:7], v223, s37, v[50:51]
	global_store_dwordx2 v[46:47], v[44:45], off offset:8 sc1
.LBB0_953:
	s_or_b64 exec, exec, s[4:5]
	v_mov_b32_e32 v223, v222
	v_mov_b32_e32 v44, v222
	v_mov_b32_e32 v45, v222
	v_pk_mul_f32 v[30:31], v[30:31], v[44:45]
	v_pk_mul_f32 v[28:29], v[28:29], v[222:223]
	v_pk_mul_f32 v[26:27], v[26:27], v[44:45]
	v_pk_mul_f32 v[24:25], v[24:25], v[222:223]
	s_and_saveexec_b64 s[4:5], s[8:9]
	s_cbranch_execz .LBB0_955
	v_pk_fma_f32 v[44:45], v[26:27], v[102:103], v[106:107]
	v_pk_fma_f32 v[46:47], v[24:25], v[100:101], v[104:105]
	v_pk_fma_f32 v[44:45], v[34:35], v[98:99], v[44:45]
	v_pk_fma_f32 v[46:47], v[32:33], v[96:97], v[46:47]
	v_pk_fma_f32 v[42:43], v[42:43], v[82:83], v[44:45]
	v_pk_fma_f32 v[40:41], v[40:41], v[80:81], v[46:47]
	v_pk_fma_f32 v[44:45], v[30:31], v[90:91], v[94:95]
	v_pk_fma_f32 v[46:47], v[28:29], v[88:89], v[92:93]
	v_pk_fma_f32 v[44:45], v[38:39], v[86:87], v[44:45]
	v_pk_fma_f32 v[46:47], v[36:37], v[84:85], v[46:47]
	v_pk_fma_f32 v[44:45], v[60:61], v[78:79], v[44:45]
	v_pk_fma_f32 v[46:47], v[58:59], v[76:77], v[46:47]
	v_mul_f32_e32 v56, 0xbfb8aa3b, v44
	v_mul_f32_e32 v54, 0xbfb8aa3b, v46
	v_mul_f32_e32 v55, 0xbfb8aa3b, v47
	v_mul_f32_e32 v57, 0xbfb8aa3b, v45
	v_exp_f32_e32 v54, v54
	v_exp_f32_e32 v55, v55
	v_exp_f32_e32 v56, v56
	v_exp_f32_e32 v57, v57
	v_add_f32_e32 v54, 1.0, v54
	v_add_f32_e32 v55, 1.0, v55
	v_add_f32_e32 v56, 1.0, v56
	v_add_f32_e32 v57, 1.0, v57
	v_rcp_f32_e32 v54, v54
	v_rcp_f32_e32 v55, v55
	v_rcp_f32_e32 v56, v56
	v_rcp_f32_e32 v57, v57
	v_pk_mul_f32 v[46:47], v[46:47], v[54:55]
	s_nop 0
	v_pk_mul_f32 v[40:41], v[40:41], v[46:47]
	v_pk_mul_f32 v[44:45], v[44:45], v[56:57]
	v_cvt_pk_bf16_f32 v40, v40, v41
	s_nop 0
	v_pk_mul_f32 v[42:43], v[42:43], v[44:45]
	s_nop 0
	v_cvt_pk_bf16_f32 v41, v42, v43
	v_mad_i64_i32 v[42:43], s[6:7], v221, s37, v[50:51]
	global_store_dwordx2 v[42:43], v[40:41], off offset:8 sc1
; __device__ __forceinline__ unsigned cvt_pk_bf16(float lo, float hi) { unsigned r; asm("v_cvt_pk_bf16_f32 %0, %1, %2" : "=v"(r) : "v"(lo), "v"(hi)); return r; }
;     __device__ __forceinline__ void operator()(const f32x4 (&acc)[2][2][4][2], const CU2& u, int wr, int wc, int fr_, int fq_) const {
;     ...
;             for (int j = 0; j < 8; ++j) {
;                 const f32x4 xg = acc[j >> 2][0][j & 3][n] * rsv[j], xv = acc[j >> 2][1][j & 3][n] * rsv[j];
;                 const f32x4 gc = gb + g2 * xg + g1 * pg1 + g0 * pg2, vc = vb + v2 * xv + v1 * pv1 + v0 * pv2;
;                 f32x4 sg;
; #pragma unroll
;                 for (int e = 0; e < 4; ++e) sg[e] = __builtin_amdgcn_rcpf(1.f + __expf(-gc[e]));
;                 const f32x4 o4 = gc * sg * vc;
;                 pg2 = pg1; pg1 = xg; pv2 = pv1; pv1 = xv;
;                 if (rb + j >= 2 && tb + j < T_) { u32x2 w; w.x = cvt_pk_bf16(o4[0], o4[1]); w.y = cvt_pk_bf16(o4[2], o4[3]); *(u32x2*)(act + (size_t)(tb + j) * FF_ + 128 * u.pn + cl + 4 * n) = w; }
.LBB0_955:
	s_or_b64 exec, exec, s[4:5]
	v_mov_b32_e32 v221, v220
	v_mov_b32_e32 v40, v220
	v_mov_b32_e32 v41, v220
	v_pk_mul_f32 v[22:23], v[22:23], v[40:41]
	v_pk_mul_f32 v[20:21], v[20:21], v[220:221]
	v_pk_mul_f32 v[18:19], v[18:19], v[40:41]
	v_pk_mul_f32 v[16:17], v[16:17], v[220:221]
	s_and_saveexec_b64 s[4:5], s[12:13]
	s_cbranch_execz .LBB0_957
	v_pk_fma_f32 v[40:41], v[18:19], v[102:103], v[106:107]
	v_pk_fma_f32 v[42:43], v[16:17], v[100:101], v[104:105]
	v_pk_fma_f32 v[40:41], v[26:27], v[98:99], v[40:41]
	v_pk_fma_f32 v[42:43], v[24:25], v[96:97], v[42:43]
	v_pk_fma_f32 v[34:35], v[34:35], v[82:83], v[40:41]
	v_pk_fma_f32 v[32:33], v[32:33], v[80:81], v[42:43]
	v_pk_fma_f32 v[40:41], v[22:23], v[90:91], v[94:95]
	v_pk_fma_f32 v[42:43], v[20:21], v[88:89], v[92:93]
	v_pk_fma_f32 v[40:41], v[30:31], v[86:87], v[40:41]
	v_pk_fma_f32 v[42:43], v[28:29], v[84:85], v[42:43]
	v_pk_fma_f32 v[38:39], v[38:39], v[78:79], v[40:41]
	v_pk_fma_f32 v[36:37], v[36:37], v[76:77], v[42:43]
	v_mul_f32_e32 v42, 0xbfb8aa3b, v38
	v_mul_f32_e32 v40, 0xbfb8aa3b, v36
	v_mul_f32_e32 v41, 0xbfb8aa3b, v37
	v_mul_f32_e32 v43, 0xbfb8aa3b, v39
	v_exp_f32_e32 v40, v40
	v_exp_f32_e32 v41, v41
	v_exp_f32_e32 v42, v42
	v_exp_f32_e32 v43, v43
	v_add_f32_e32 v40, 1.0, v40
	v_add_f32_e32 v41, 1.0, v41
	v_add_f32_e32 v42, 1.0, v42
	v_add_f32_e32 v43, 1.0, v43
	v_rcp_f32_e32 v40, v40
	v_rcp_f32_e32 v41, v41
	v_rcp_f32_e32 v42, v42
	v_rcp_f32_e32 v43, v43
	v_pk_mul_f32 v[36:37], v[36:37], v[40:41]
	s_nop 0
	v_pk_mul_f32 v[32:33], v[32:33], v[36:37]
	v_pk_mul_f32 v[38:39], v[38:39], v[42:43]
	v_cvt_pk_bf16_f32 v32, v32, v33
	s_nop 0
	v_pk_mul_f32 v[34:35], v[34:35], v[38:39]
	s_nop 0
	v_cvt_pk_bf16_f32 v33, v34, v35
	v_mad_i64_i32 v[34:35], s[6:7], v219, s37, v[50:51]
	global_store_dwordx2 v[34:35], v[32:33], off offset:8 sc1
.LBB0_957:
	s_or_b64 exec, exec, s[4:5]
	v_mov_b32_e32 v219, v218
	v_mov_b32_e32 v32, v218
	v_mov_b32_e32 v33, v218
	v_pk_mul_f32 v[14:15], v[14:15], v[32:33]
	v_pk_mul_f32 v[12:13], v[12:13], v[218:219]
	v_pk_mul_f32 v[10:11], v[10:11], v[32:33]
	v_pk_mul_f32 v[8:9], v[8:9], v[218:219]
	s_and_saveexec_b64 s[4:5], s[14:15]
	s_cbranch_execz .LBB0_959
	v_pk_fma_f32 v[32:33], v[10:11], v[102:103], v[106:107]
	v_pk_fma_f32 v[34:35], v[8:9], v[100:101], v[104:105]
	v_pk_fma_f32 v[32:33], v[18:19], v[98:99], v[32:33]
	v_pk_fma_f32 v[34:35], v[16:17], v[96:97], v[34:35]
	v_pk_fma_f32 v[26:27], v[26:27], v[82:83], v[32:33]
	v_pk_fma_f32 v[24:25], v[24:25], v[80:81], v[34:35]
	v_pk_fma_f32 v[32:33], v[14:15], v[90:91], v[94:95]
	v_pk_fma_f32 v[34:35], v[12:13], v[88:89], v[92:93]
	v_pk_fma_f32 v[32:33], v[22:23], v[86:87], v[32:33]
	v_pk_fma_f32 v[34:35], v[20:21], v[84:85], v[34:35]
	v_pk_fma_f32 v[30:31], v[30:31], v[78:79], v[32:33]
	v_pk_fma_f32 v[28:29], v[28:29], v[76:77], v[34:35]
	v_mul_f32_e32 v34, 0xbfb8aa3b, v30
	v_mul_f32_e32 v32, 0xbfb8aa3b, v28
	v_mul_f32_e32 v33, 0xbfb8aa3b, v29
	v_mul_f32_e32 v35, 0xbfb8aa3b, v31
	v_exp_f32_e32 v32, v32
	v_exp_f32_e32 v33, v33
	v_exp_f32_e32 v34, v34
	v_exp_f32_e32 v35, v35
	v_add_f32_e32 v32, 1.0, v32
	v_add_f32_e32 v33, 1.0, v33
	v_add_f32_e32 v34, 1.0, v34
	v_add_f32_e32 v35, 1.0, v35
	v_rcp_f32_e32 v32, v32
	v_rcp_f32_e32 v33, v33
	v_rcp_f32_e32 v34, v34
	v_rcp_f32_e32 v35, v35
	v_pk_mul_f32 v[28:29], v[28:29], v[32:33]
	s_nop 0
	v_pk_mul_f32 v[24:25], v[24:25], v[28:29]
	v_pk_mul_f32 v[30:31], v[30:31], v[34:35]
	v_cvt_pk_bf16_f32 v24, v24, v25
	s_nop 0
	v_pk_mul_f32 v[26:27], v[26:27], v[30:31]
	s_nop 0
	v_cvt_pk_bf16_f32 v25, v26, v27
	v_mad_i64_i32 v[26:27], s[6:7], v217, s37, v[50:51]
	global_store_dwordx2 v[26:27], v[24:25], off offset:8 sc1
; __device__ __forceinline__ unsigned cvt_pk_bf16(float lo, float hi) { unsigned r; asm("v_cvt_pk_bf16_f32 %0, %1, %2" : "=v"(r) : "v"(lo), "v"(hi)); return r; }
;     __device__ __forceinline__ void operator()(const f32x4 (&acc)[2][2][4][2], const CU2& u, int wr, int wc, int fr_, int fq_) const {
;     ...
;             for (int j = 0; j < 8; ++j) {
;                 const f32x4 xg = acc[j >> 2][0][j & 3][n] * rsv[j], xv = acc[j >> 2][1][j & 3][n] * rsv[j];
;                 const f32x4 gc = gb + g2 * xg + g1 * pg1 + g0 * pg2, vc = vb + v2 * xv + v1 * pv1 + v0 * pv2;
;                 f32x4 sg;
; #pragma unroll
;                 for (int e = 0; e < 4; ++e) sg[e] = __builtin_amdgcn_rcpf(1.f + __expf(-gc[e]));
;                 const f32x4 o4 = gc * sg * vc;
;                 pg2 = pg1; pg1 = xg; pv2 = pv1; pv1 = xv;
;                 if (rb + j >= 2 && tb + j < T_) { u32x2 w; w.x = cvt_pk_bf16(o4[0], o4[1]); w.y = cvt_pk_bf16(o4[2], o4[3]); *(u32x2*)(act + (size_t)(tb + j) * FF_ + 128 * u.pn + cl + 4 * n) = w; }
.LBB0_959:
	s_or_b64 exec, exec, s[4:5]
	v_mov_b32_e32 v217, v216
	v_mov_b32_e32 v24, v216
	v_mov_b32_e32 v25, v216
	v_pk_mul_f32 v[6:7], v[6:7], v[24:25]
	v_pk_mul_f32 v[4:5], v[4:5], v[216:217]
	v_pk_mul_f32 v[2:3], v[2:3], v[24:25]
	v_pk_mul_f32 v[0:1], v[0:1], v[216:217]
	s_and_saveexec_b64 s[4:5], s[26:27]
	s_cbranch_execz .LBB0_961
	v_pk_fma_f32 v[24:25], v[2:3], v[102:103], v[106:107]
	v_pk_fma_f32 v[26:27], v[0:1], v[100:101], v[104:105]
	v_pk_fma_f32 v[24:25], v[10:11], v[98:99], v[24:25]
	v_pk_fma_f32 v[26:27], v[8:9], v[96:97], v[26:27]
	v_pk_fma_f32 v[18:19], v[18:19], v[82:83], v[24:25]
	v_pk_fma_f32 v[16:17], v[16:17], v[80:81], v[26:27]
	v_pk_fma_f32 v[24:25], v[6:7], v[90:91], v[94:95]
	v_pk_fma_f32 v[26:27], v[4:5], v[88:89], v[92:93]
	v_pk_fma_f32 v[24:25], v[14:15], v[86:87], v[24:25]
	v_pk_fma_f32 v[26:27], v[12:13], v[84:85], v[26:27]
	v_pk_fma_f32 v[22:23], v[22:23], v[78:79], v[24:25]
	v_pk_fma_f32 v[20:21], v[20:21], v[76:77], v[26:27]
	v_mul_f32_e32 v26, 0xbfb8aa3b, v22
	v_mul_f32_e32 v24, 0xbfb8aa3b, v20
	v_mul_f32_e32 v25, 0xbfb8aa3b, v21
	v_mul_f32_e32 v27, 0xbfb8aa3b, v23
	v_exp_f32_e32 v24, v24
	v_exp_f32_e32 v25, v25
	v_exp_f32_e32 v26, v26
	v_exp_f32_e32 v27, v27
	v_add_f32_e32 v24, 1.0, v24
	v_add_f32_e32 v25, 1.0, v25
	v_add_f32_e32 v26, 1.0, v26
	v_add_f32_e32 v27, 1.0, v27
	v_rcp_f32_e32 v24, v24
	v_rcp_f32_e32 v25, v25
	v_rcp_f32_e32 v26, v26
	v_rcp_f32_e32 v27, v27
	v_pk_mul_f32 v[20:21], v[20:21], v[24:25]
	s_nop 0
	v_pk_mul_f32 v[16:17], v[16:17], v[20:21]
	v_pk_mul_f32 v[22:23], v[22:23], v[26:27]
	v_cvt_pk_bf16_f32 v16, v16, v17
	s_nop 0
	v_pk_mul_f32 v[18:19], v[18:19], v[22:23]
	s_nop 0
	v_cvt_pk_bf16_f32 v17, v18, v19
	v_mad_i64_i32 v[18:19], s[6:7], v246, s37, v[50:51]
	global_store_dwordx2 v[18:19], v[16:17], off offset:8 sc1
.LBB0_961:
	s_or_b64 exec, exec, s[4:5]
	s_and_saveexec_b64 s[4:5], s[28:29]
	s_cbranch_execz .LBB0_963
	v_pk_fma_f32 v[16:17], v[110:111], v[102:103], v[106:107]
	v_pk_fma_f32 v[18:19], v[62:63], v[100:101], v[104:105]
	v_pk_fma_f32 v[16:17], v[2:3], v[98:99], v[16:17]
	v_pk_fma_f32 v[18:19], v[0:1], v[96:97], v[18:19]
	v_pk_fma_f32 v[10:11], v[10:11], v[82:83], v[16:17]
	v_pk_fma_f32 v[8:9], v[8:9], v[80:81], v[18:19]
	v_pk_fma_f32 v[16:17], v[64:65], v[90:91], v[94:95]
	v_pk_fma_f32 v[18:19], v[48:49], v[88:89], v[92:93]
	v_pk_fma_f32 v[16:17], v[6:7], v[86:87], v[16:17]
	v_pk_fma_f32 v[18:19], v[4:5], v[84:85], v[18:19]
	v_pk_fma_f32 v[14:15], v[14:15], v[78:79], v[16:17]
	v_pk_fma_f32 v[12:13], v[12:13], v[76:77], v[18:19]
	v_mul_f32_e32 v18, 0xbfb8aa3b, v14
	v_mul_f32_e32 v16, 0xbfb8aa3b, v12
	v_mul_f32_e32 v17, 0xbfb8aa3b, v13
	v_mul_f32_e32 v19, 0xbfb8aa3b, v15
	v_exp_f32_e32 v16, v16
	v_exp_f32_e32 v17, v17
	v_exp_f32_e32 v18, v18
	v_exp_f32_e32 v19, v19
	v_add_f32_e32 v16, 1.0, v16
	v_add_f32_e32 v17, 1.0, v17
	v_add_f32_e32 v18, 1.0, v18
	v_add_f32_e32 v19, 1.0, v19
	v_rcp_f32_e32 v16, v16
	v_rcp_f32_e32 v17, v17
	v_rcp_f32_e32 v18, v18
	v_rcp_f32_e32 v19, v19
	v_pk_mul_f32 v[12:13], v[12:13], v[16:17]
	s_nop 0
	v_pk_mul_f32 v[8:9], v[8:9], v[12:13]
	v_pk_mul_f32 v[14:15], v[14:15], v[18:19]
	v_cvt_pk_bf16_f32 v8, v8, v9
	s_nop 0
	v_pk_mul_f32 v[10:11], v[10:11], v[14:15]
	s_nop 0
	v_cvt_pk_bf16_f32 v9, v10, v11
	v_mad_i64_i32 v[10:11], s[6:7], v245, s37, v[50:51]
	global_store_dwordx2 v[10:11], v[8:9], off offset:8 sc1
.LBB0_963:
	s_or_b64 exec, exec, s[4:5]
	s_and_saveexec_b64 s[4:5], s[0:1]
	s_cbranch_execz .LBB0_965
	v_pk_fma_f32 v[12:13], v[52:53], v[88:89], v[92:93]
	v_pk_fma_f32 v[8:9], v[112:113], v[102:103], v[106:107]
	v_pk_fma_f32 v[12:13], v[48:49], v[84:85], v[12:13]
	v_pk_fma_f32 v[10:11], v[66:67], v[100:101], v[104:105]
	v_pk_fma_f32 v[4:5], v[4:5], v[76:77], v[12:13]
	v_pk_fma_f32 v[8:9], v[110:111], v[98:99], v[8:9]
	v_mul_f32_e32 v12, 0xbfb8aa3b, v4
	v_exp_f32_e32 v14, v12
	v_pk_fma_f32 v[12:13], v[108:109], v[90:91], v[94:95]
	v_pk_fma_f32 v[10:11], v[62:63], v[96:97], v[10:11]
	v_pk_fma_f32 v[12:13], v[64:65], v[86:87], v[12:13]
	v_pk_fma_f32 v[2:3], v[2:3], v[82:83], v[8:9]
	v_pk_fma_f32 v[6:7], v[6:7], v[78:79], v[12:13]
	v_add_f32_e32 v12, 1.0, v14
	v_mul_f32_e32 v13, 0xbfb8aa3b, v5
	v_mul_f32_e32 v14, 0xbfb8aa3b, v6
	v_mul_f32_e32 v15, 0xbfb8aa3b, v7
	v_exp_f32_e32 v13, v13
	v_exp_f32_e32 v14, v14
	v_exp_f32_e32 v15, v15
	v_rcp_f32_e32 v12, v12
	v_add_f32_e32 v13, 1.0, v13
	v_add_f32_e32 v14, 1.0, v14
	v_add_f32_e32 v15, 1.0, v15
	v_rcp_f32_e32 v14, v14
	v_rcp_f32_e32 v15, v15
	v_rcp_f32_e32 v13, v13
	v_pk_fma_f32 v[0:1], v[0:1], v[80:81], v[10:11]
	v_pk_mul_f32 v[6:7], v[6:7], v[14:15]
	v_pk_mul_f32 v[4:5], v[4:5], v[12:13]
	v_pk_mul_f32 v[2:3], v[2:3], v[6:7]
	v_pk_mul_f32 v[0:1], v[0:1], v[4:5]
	s_nop 0
	v_cvt_pk_bf16_f32 v0, v0, v1
	v_cvt_pk_bf16_f32 v1, v2, v3
	v_mad_i64_i32 v[2:3], s[0:1], v244, s37, v[50:51]
	global_store_dwordx2 v[2:3], v[0:1], off offset:8 sc1

; __device__ __forceinline__ unsigned cvt_pk_bf16(float lo, float hi) { unsigned r; asm("v_cvt_pk_bf16_f32 %0, %1, %2" : "=v"(r) : "v"(lo), "v"(hi)); return r; }
; __device__ __forceinline__ float bflo(unsigned w) { return __uint_as_float(w << 16); }
; __device__ __forceinline__ float bfhi(unsigned w) { return __uint_as_float(w & 0xffff0000u); }
; __device__ __forceinline__ float shx(float v, int off, int lane) { return __int_as_float(__builtin_amdgcn_ds_bpermute((lane ^ off) << 2, __float_as_int(v))); }
;     __device__ __forceinline__ void operator()(const f32x4 (&acc)[2][2][4][2], const RU& u, int wr, int wc, int fr, int fq) const {
;     ...
;             for (int m = 0; m < 4; ++m) { const bf16_t* rp = hb + (size_t)(u.pm * 256 + ai * 128 + wr * 64 + m * 16 + fr) * D_ + col0; bb[ai][m][0] = *(const u32x4*)rp; bb[ai][m][1] = *(const u32x4*)(rp + 128); }
; #pragma unroll
;         for (int ai = 0; ai < 2; ++ai)
; #pragma unroll
;             for (int m = 0; m < 4; ++m) {
;                 const int row = u.pm * 256 + ai * 128 + wr * 64 + m * 16 + fr; float sq = 0.f;
;                 bf16_t* rp = hb + (size_t)row * D_ + col0;
; #pragma unroll
;                 for (int bj = 0; bj < 2; ++bj) {
;                     const u32x4 b = bb[ai][m][bj];
;                     const f32x4 v0 = acc[ai][bj][m][0] + (f32x4){bflo(b.x), bfhi(b.x), bflo(b.y), bfhi(b.y)};
;                     const f32x4 v1 = acc[ai][bj][m][1] + (f32x4){bflo(b.z), bfhi(b.z), bflo(b.w), bfhi(b.w)};
;                     u32x4 w; w.x = cvt_pk_bf16(v0[0], v0[1]); w.y = cvt_pk_bf16(v0[2], v0[3]); w.z = cvt_pk_bf16(v1[0], v1[1]); w.w = cvt_pk_bf16(v1[2], v1[3]);
;                     *(u32x4*)(rp + bj * 128) = w;
;                     sq += ((v0[0] * v0[0] + v0[1] * v0[1]) + (v0[2] * v0[2] + v0[3] * v0[3])) + ((v1[0] * v1[0] + v1[1] * v1[1]) + (v1[2] * v1[2] + v1[3] * v1[3]));
;                 }
;                 sq += shx(sq, 16, ln_); sq += shx(sq, 32, ln_);
;                 if (fq == 0) red[wc * 256 + ai * 128 + wr * 64 + m * 16 + fr] = sq;
.LBB0_1036:
	s_mul_i32 s16, s52, s25
	s_add_i32 s16, s16, s24
	s_lshl_b32 s17, s16, 3
	s_and_b32 s17, s17, 0xffffff00
	s_lshl_b32 s16, s16, 8
	v_or_b32_e32 v204, s17, v221
	s_and_b32 s18, s16, 0x1f00
	v_add_u32_e32 v112, s18, v202
	v_ashrrev_i32_e32 v205, 31, v204
	v_lshlrev_b64 v[232:233], 1, v[204:205]
	v_ashrrev_i32_e32 v113, 31, v112
	v_lshl_add_u64 v[114:115], s[6:7], 0, v[232:233]
	v_lshlrev_b64 v[236:237], 12, v[112:113]
	v_lshl_add_u64 v[116:117], v[114:115], 0, v[236:237]
	flat_load_dwordx4 v[228:231], v[116:117]
	flat_load_dwordx4 v[184:187], v[116:117] offset:256
	v_or_b32_e32 v116, 16, v112
	v_ashrrev_i32_e32 v117, 31, v116
	v_lshlrev_b64 v[218:219], 12, v[116:117]
	v_lshl_add_u64 v[116:117], v[114:115], 0, v[218:219]
	flat_load_dwordx4 v[180:183], v[116:117]
	flat_load_dwordx4 v[176:179], v[116:117] offset:256
	v_or_b32_e32 v116, 32, v112
	v_or_b32_e32 v112, 48, v112
	v_ashrrev_i32_e32 v117, 31, v116
	v_ashrrev_i32_e32 v113, 31, v112
	v_lshlrev_b64 v[216:217], 12, v[116:117]
	v_lshlrev_b64 v[214:215], 12, v[112:113]
	s_mov_b64 s[16:17], 0x80000
	v_lshl_add_u64 v[116:117], v[114:115], 0, v[216:217]
	v_lshl_add_u64 v[112:113], v[114:115], 0, v[214:215]
	v_lshl_add_u64 v[212:213], v[236:237], 0, s[16:17]
	s_mov_b64 s[16:17], 0x90000
	flat_load_dwordx4 v[172:175], v[116:117]
	flat_load_dwordx4 v[168:171], v[116:117] offset:256
	flat_load_dwordx4 v[164:167], v[112:113]
	flat_load_dwordx4 v[160:163], v[112:113] offset:256
	v_lshl_add_u64 v[112:113], v[114:115], 0, v[212:213]
	v_lshl_add_u64 v[210:211], v[236:237], 0, s[16:17]
	s_mov_b64 s[16:17], 0xa0000
	flat_load_dwordx4 v[156:159], v[112:113]
	flat_load_dwordx4 v[144:147], v[112:113] offset:256
	v_lshl_add_u64 v[112:113], v[114:115], 0, v[210:211]
	v_lshl_add_u64 v[208:209], v[236:237], 0, s[16:17]
	s_mov_b64 s[16:17], 0xb0000
	flat_load_dwordx4 v[140:143], v[112:113]
	flat_load_dwordx4 v[136:139], v[112:113] offset:256
	v_lshl_add_u64 v[112:113], v[114:115], 0, v[208:209]
	v_lshl_add_u64 v[206:207], v[236:237], 0, s[16:17]
	flat_load_dwordx4 v[128:131], v[112:113]
	flat_load_dwordx4 v[116:119], v[112:113] offset:256
	v_lshl_add_u64 v[112:113], v[114:115], 0, v[206:207]
	flat_load_dwordx4 v[120:123], v[112:113]
	s_nop 0
	flat_load_dwordx4 v[112:115], v[112:113] offset:256
	v_lshl_add_u64 v[236:237], s[6:7], 0, v[236:237]
	v_lshl_add_u64 v[232:233], v[236:237], 0, v[232:233]
	s_waitcnt vmcnt(0) lgkmcnt(0)
	v_lshlrev_b32_e32 v236, 16, v228
	v_and_b32_e32 v237, 0xffff0000, v228
	v_lshlrev_b32_e32 v228, 16, v229
	v_and_b32_e32 v229, 0xffff0000, v229
	v_pk_add_f32 v[154:155], v[154:155], v[228:229]
	v_lshlrev_b32_e32 v228, 16, v230
	v_and_b32_e32 v229, 0xffff0000, v230
	v_pk_add_f32 v[152:153], v[152:153], v[236:237]
	v_lshlrev_b32_e32 v230, 16, v231
	v_and_b32_e32 v231, 0xffff0000, v231
	v_pk_add_f32 v[228:229], v[148:149], v[228:229]
	v_cvt_pk_bf16_f32 v148, v152, v153
	v_cvt_pk_bf16_f32 v149, v154, v155
	v_pk_add_f32 v[230:231], v[150:151], v[230:231]
	v_cvt_pk_bf16_f32 v150, v228, v229
	s_nop 0
	v_cvt_pk_bf16_f32 v151, v230, v231
	flat_store_dwordx4 v[232:233], v[148:151] sc1
	s_nop 1
	v_mul_f32_e32 v148, v153, v153
	v_mul_f32_e32 v149, v155, v155
	v_fmac_f32_e32 v148, v152, v152
	v_fmac_f32_e32 v149, v154, v154
	v_add_f32_e32 v148, v148, v149
	v_mul_f32_e32 v149, v229, v229
	v_mul_f32_e32 v150, v231, v231
	v_fmac_f32_e32 v149, v228, v228
	v_fmac_f32_e32 v150, v230, v230
	v_add_f32_e32 v149, v149, v150
	v_add_f32_e32 v152, v148, v149
	v_lshlrev_b32_e32 v148, 16, v184
	v_and_b32_e32 v149, 0xffff0000, v184
	v_lshlrev_b32_e32 v150, 16, v185
	v_and_b32_e32 v151, 0xffff0000, v185
	v_pk_add_f32 v[132:133], v[132:133], v[148:149]
	v_lshlrev_b32_e32 v148, 16, v186
	v_and_b32_e32 v149, 0xffff0000, v186
	v_pk_add_f32 v[134:135], v[134:135], v[150:151]
	v_lshlrev_b32_e32 v150, 16, v187
	v_and_b32_e32 v151, 0xffff0000, v187
	v_pk_add_f32 v[148:149], v[124:125], v[148:149]
	v_cvt_pk_bf16_f32 v124, v132, v133
	v_cvt_pk_bf16_f32 v125, v134, v135
	v_pk_add_f32 v[150:151], v[126:127], v[150:151]
	v_cvt_pk_bf16_f32 v126, v148, v149
	s_nop 0
	v_cvt_pk_bf16_f32 v127, v150, v151
	flat_store_dwordx4 v[232:233], v[124:127] offset:256 sc1
	s_nop 1
	v_mul_f32_e32 v124, v133, v133
	v_mul_f32_e32 v125, v135, v135
	v_fmac_f32_e32 v124, v132, v132
	v_fmac_f32_e32 v125, v134, v134
	v_add_f32_e32 v124, v124, v125
	v_mul_f32_e32 v125, v149, v149
	v_mul_f32_e32 v126, v151, v151
	v_fmac_f32_e32 v125, v148, v148
	v_fmac_f32_e32 v126, v150, v150
	v_add_f32_e32 v125, v125, v126
	v_add_f32_e32 v124, v124, v125
	v_add_f32_e32 v124, v152, v124
	ds_bpermute_b32 v125, v222, v124
	s_waitcnt lgkmcnt(0)
	v_add_f32_e32 v124, v124, v125
	ds_bpermute_b32 v125, v223, v124
	s_and_saveexec_b64 s[16:17], s[0:1]
	s_cbranch_execz .LBB0_1038
	s_waitcnt lgkmcnt(0)
	v_add_f32_e32 v124, v124, v125
	ds_write_b32 v224, v124

; __device__ __forceinline__ float bflo(unsigned w) { return __uint_as_float(w << 16); }
; __device__ __forceinline__ float bfhi(unsigned w) { return __uint_as_float(w & 0xffff0000u); }
; __device__ __forceinline__ float u64f(u64 q) { return (float)(unsigned)(q >> 32) * 4294967296.f + (float)(unsigned)q; }
; __global__ void __launch_bounds__(512, 2) hybrid_fwd(Params p) {
;     ...
;         for (int row = c * 8 + wave; row < T_; row += G * 8) {
;             const float rs = rsqrtf(u64f(sq[row]) * SSQ_INV + EPS);
; #pragma unroll
;             for (int j = 0; j < 8; ++j) { const u32x2 hv = *(const u32x2*)(HB + (size_t)row * D_ + 256 * j + 4 * lane); const f32x4 g = *(const f32x4*)(p.final_norm + 256 * j + 4 * lane);
;                 *(f32x4*)(p.out + (size_t)row * D_ + 256 * j + 4 * lane) = (f32x4){bflo(hv.x), bfhi(hv.x), bflo(hv.y), bfhi(hv.y)} * rs * g; }
.LBB0_1111:
	s_add_u32 s14, s50, s10
	v_lshl_add_u64 v[18:19], s[50:51], 0, v[14:15]
	s_addc_u32 s15, s51, s11
	v_add_co_u32_e32 v22, vcc, s13, v18
	v_mov_b64_e32 v[24:25], s[14:15]
	s_nop 0
	v_addc_co_u32_e32 v23, vcc, 0, v19, vcc
	flat_load_dwordx2 v[26:27], v[24:25]
	flat_load_dwordx2 v[28:29], v[22:23]
	global_load_dwordx4 v[18:21], v[2:3], off
	s_add_i32 s0, s0, s2
	s_add_u32 s10, s10, s6
	s_addc_u32 s11, s11, s7
	v_lshl_add_u64 v[14:15], v[14:15], 0, s[8:9]
	s_cmpk_gt_i32 s0, 0x1fff
	s_waitcnt vmcnt(0) lgkmcnt(0)
	v_mov_b32_e32 v0, v27
	v_cvt_f32_u32_e32 v17, v26
	v_lshlrev_b32_e32 v24, 16, v28
	v_and_b32_e32 v25, 0xffff0000, v28
	v_lshlrev_b32_e32 v26, 16, v29
	v_and_b32_e32 v27, 0xffff0000, v29
	v_lshlrev_b64 v[28:29], s1, v[0:1]
	v_min_u32_e32 v0, 1, v28
	v_or_b32_e32 v0, v29, v0
	v_cvt_f32_u32_e32 v0, v0
	v_ldexp_f32 v0, v0, s3
	v_fmac_f32_e32 v17, 0x4f800000, v0
	v_fmamk_f32 v0, v17, 0x2e000000, v16
	v_mul_f32_e32 v17, 0x4b800000, v0
	v_cmp_gt_f32_e32 vcc, s12, v0
	s_nop 1
	v_cndmask_b32_e32 v0, v0, v17, vcc
	v_rsq_f32_e32 v0, v0
	s_nop 0
	v_mul_f32_e32 v17, 0x45800000, v0
	v_cndmask_b32_e32 v0, v0, v17, vcc
	v_pk_mul_f32 v[24:25], v[0:1], v[24:25] op_sel_hi:[0,1]
	v_pk_mul_f32 v[26:27], v[0:1], v[26:27] op_sel_hi:[0,1]
	v_pk_mul_f32 v[20:21], v[20:21], v[26:27]
	v_pk_mul_f32 v[18:19], v[18:19], v[24:25]
	global_store_dwordx4 v[12:13], v[18:21], off offset:-4096 sc1
	flat_load_dwordx2 v[24:25], v[22:23] offset:512
	s_nop 0
	global_load_dwordx4 v[18:21], v[2:3], off offset:1024
	s_waitcnt vmcnt(0) lgkmcnt(0)
	v_lshlrev_b32_e32 v26, 16, v24
	v_and_b32_e32 v27, 0xffff0000, v24
	v_lshlrev_b32_e32 v24, 16, v25
	v_and_b32_e32 v25, 0xffff0000, v25
	v_pk_mul_f32 v[26:27], v[0:1], v[26:27] op_sel_hi:[0,1]
	v_pk_mul_f32 v[24:25], v[0:1], v[24:25] op_sel_hi:[0,1]
	v_pk_mul_f32 v[20:21], v[20:21], v[24:25]
	v_pk_mul_f32 v[18:19], v[18:19], v[26:27]
	global_store_dwordx4 v[12:13], v[18:21], off offset:-3072 sc1
	flat_load_dwordx2 v[24:25], v[22:23] offset:1024
	s_nop 0
	global_load_dwordx4 v[18:21], v[2:3], off offset:2048
	s_waitcnt vmcnt(0) lgkmcnt(0)
	v_lshlrev_b32_e32 v26, 16, v24
	v_and_b32_e32 v27, 0xffff0000, v24
	v_lshlrev_b32_e32 v24, 16, v25
	v_and_b32_e32 v25, 0xffff0000, v25
	v_pk_mul_f32 v[26:27], v[0:1], v[26:27] op_sel_hi:[0,1]
	v_pk_mul_f32 v[24:25], v[0:1], v[24:25] op_sel_hi:[0,1]
	v_pk_mul_f32 v[20:21], v[20:21], v[24:25]
	v_pk_mul_f32 v[18:19], v[18:19], v[26:27]
	global_store_dwordx4 v[12:13], v[18:21], off offset:-2048 sc1
	flat_load_dwordx2 v[24:25], v[22:23] offset:1536
	s_nop 0
	global_load_dwordx4 v[18:21], v[2:3], off offset:3072
	s_waitcnt vmcnt(0) lgkmcnt(0)
	v_lshlrev_b32_e32 v26, 16, v24
	v_and_b32_e32 v27, 0xffff0000, v24
	v_lshlrev_b32_e32 v24, 16, v25
	v_and_b32_e32 v25, 0xffff0000, v25
	v_pk_mul_f32 v[26:27], v[0:1], v[26:27] op_sel_hi:[0,1]
	v_pk_mul_f32 v[24:25], v[0:1], v[24:25] op_sel_hi:[0,1]
	v_pk_mul_f32 v[20:21], v[20:21], v[24:25]
	v_pk_mul_f32 v[18:19], v[18:19], v[26:27]
	global_store_dwordx4 v[12:13], v[18:21], off offset:-1024 sc1
	flat_load_dwordx2 v[24:25], v[22:23] offset:2048
	s_nop 0
	global_load_dwordx4 v[18:21], v[4:5], off
	s_waitcnt vmcnt(0) lgkmcnt(0)
	v_lshlrev_b32_e32 v26, 16, v24
	v_and_b32_e32 v27, 0xffff0000, v24
	v_lshlrev_b32_e32 v24, 16, v25
	v_and_b32_e32 v25, 0xffff0000, v25
	v_pk_mul_f32 v[26:27], v[0:1], v[26:27] op_sel_hi:[0,1]
	v_pk_mul_f32 v[24:25], v[0:1], v[24:25] op_sel_hi:[0,1]
	v_pk_mul_f32 v[20:21], v[20:21], v[24:25]
	v_pk_mul_f32 v[18:19], v[18:19], v[26:27]
	global_store_dwordx4 v[12:13], v[18:21], off sc1
	flat_load_dwordx2 v[24:25], v[22:23] offset:2560
	s_nop 0
	global_load_dwordx4 v[18:21], v[6:7], off
	s_waitcnt vmcnt(0) lgkmcnt(0)
	v_lshlrev_b32_e32 v26, 16, v24
	v_and_b32_e32 v27, 0xffff0000, v24
	v_lshlrev_b32_e32 v24, 16, v25
	v_and_b32_e32 v25, 0xffff0000, v25
	v_pk_mul_f32 v[26:27], v[0:1], v[26:27] op_sel_hi:[0,1]
	v_pk_mul_f32 v[24:25], v[0:1], v[24:25] op_sel_hi:[0,1]
	v_pk_mul_f32 v[20:21], v[20:21], v[24:25]
	v_pk_mul_f32 v[18:19], v[18:19], v[26:27]
	global_store_dwordx4 v[12:13], v[18:21], off offset:1024 sc1
	flat_load_dwordx2 v[24:25], v[22:23] offset:3072
	s_nop 0
	global_load_dwordx4 v[18:21], v[8:9], off
	s_waitcnt vmcnt(0) lgkmcnt(0)
	v_lshlrev_b32_e32 v26, 16, v24
	v_and_b32_e32 v27, 0xffff0000, v24
	v_lshlrev_b32_e32 v24, 16, v25
	v_and_b32_e32 v25, 0xffff0000, v25
	v_pk_mul_f32 v[26:27], v[0:1], v[26:27] op_sel_hi:[0,1]
	v_pk_mul_f32 v[24:25], v[0:1], v[24:25] op_sel_hi:[0,1]
	v_pk_mul_f32 v[20:21], v[20:21], v[24:25]
	v_pk_mul_f32 v[18:19], v[18:19], v[26:27]
	global_store_dwordx4 v[12:13], v[18:21], off offset:2048 sc1
	flat_load_dwordx2 v[24:25], v[22:23] offset:3584
	s_nop 0
	global_load_dwordx4 v[18:21], v[10:11], off
	s_waitcnt vmcnt(0) lgkmcnt(0)
	v_lshlrev_b32_e32 v22, 16, v24
	v_and_b32_e32 v23, 0xffff0000, v24
	v_lshlrev_b32_e32 v24, 16, v25
	v_and_b32_e32 v25, 0xffff0000, v25
	v_pk_mul_f32 v[22:23], v[0:1], v[22:23] op_sel_hi:[0,1]
	v_pk_mul_f32 v[24:25], v[0:1], v[24:25] op_sel_hi:[0,1]
	v_pk_mul_f32 v[20:21], v[20:21], v[24:25]
	v_pk_mul_f32 v[18:19], v[18:19], v[22:23]
	global_store_dwordx4 v[12:13], v[18:21], off offset:3072 sc1
	v_lshl_add_u64 v[12:13], v[12:13], 0, s[4:5]
	s_cbranch_scc0 .LBB0_1111
